# rotated GEMM loops: DMA pieces moved one or two MFMAs earlier inside the first half-step (6,8,10,12 / 4,5,6)
# baseline (speedup 1.0000x reference)
.Lgf_G5x_top:
	s_waitcnt vmcnt(3)
	s_waitcnt lgkmcnt(0)
	s_barrier
	v_mfma_f32_16x16x32_bf16 v[102:105], v[2:5], v[26:29], v[102:105]
	v_mfma_f32_16x16x32_bf16 v[98:101], v[6:9], v[26:29], v[98:101]
	s_add_i32 s17, s8, -3
	s_and_b32 s19, s17, 2
	s_mulk_i32 s19, 0x6000
	v_add_u32_e32 v110, s19, v142
	ds_read_b128 v[106:109], v110
	v_mfma_f32_16x16x32_bf16 v[86:89], v[10:13], v[26:29], v[86:89]
	ds_read_b128 v[144:147], v110 offset:1024
	s_and_b32 s89, s8, 3
	s_mulk_i32 s89, 0x6000
	s_add_i32 s89, s89, s88
	s_mov_b32 m0, s89
	v_mfma_f32_16x16x32_bf16 v[70:73], v[14:17], v[26:29], v[70:73]
	global_load_lds_dwordx4 v126, s[90:91]
	s_add_i32 m0, s89, 0x2000
	v_mfma_f32_16x16x32_bf16 v[90:93], v[2:5], v[22:25], v[90:93]
	global_load_lds_dwordx4 v128, s[90:91]
	s_add_i32 m0, s89, 0x4000
	v_mfma_f32_16x16x32_bf16 v[78:81], v[6:9], v[22:25], v[78:81]
	global_load_lds_dwordx4 v130, s[92:93]
	s_add_u32 s90, s90, 64
	s_addc_u32 s91, s91, 0
	s_add_u32 s92, s92, 64
	s_addc_u32 s93, s93, 0
	v_mfma_f32_16x16x32_bf16 v[62:65], v[10:13], v[22:25], v[62:65]
	v_mfma_f32_16x16x32_bf16 v[50:53], v[14:17], v[22:25], v[50:53]
	s_waitcnt lgkmcnt(0)
	v_mfma_f32_16x16x32_bf16 v[74:77], v[2:5], v[106:109], v[74:77]
	s_add_i32 s26, s8, -2
	s_and_b32 s28, s26, 3
	s_mulk_i32 s28, 0x6000
	v_add_u32_e32 v127, s28, v140
	v_add_u32_e32 v143, s28, v141
	ds_read_b128 v[26:29], v143
	v_mfma_f32_16x16x32_bf16 v[58:61], v[6:9], v[106:109], v[58:61]
	ds_read_b128 v[22:25], v143 offset:1024
	v_mfma_f32_16x16x32_bf16 v[38:41], v[10:13], v[106:109], v[38:41]
	ds_read_b128 v[118:121], v127
	v_mfma_f32_16x16x32_bf16 v[30:33], v[14:17], v[106:109], v[30:33]
	ds_read_b128 v[114:117], v127 offset:1024
	ds_read_b128 v[110:113], v127 offset:2048
	ds_read_b128 v[106:109], v127 offset:3072
	v_mfma_f32_16x16x32_bf16 v[94:97], v[2:5], v[144:147], v[94:97]
	v_mfma_f32_16x16x32_bf16 v[82:85], v[6:9], v[144:147], v[82:85]
	v_mfma_f32_16x16x32_bf16 v[66:69], v[10:13], v[144:147], v[66:69]
	v_mfma_f32_16x16x32_bf16 v[34:37], v[14:17], v[144:147], v[34:37]
	s_waitcnt vmcnt(3)
	s_waitcnt lgkmcnt(0)
	s_barrier
	v_mfma_f32_16x16x32_bf16 v[102:105], v[118:121], v[26:29], v[102:105]
	v_mfma_f32_16x16x32_bf16 v[98:101], v[114:117], v[26:29], v[98:101]
	v_add_u32_e32 v132, s28, v142
	ds_read_b128 v[144:147], v132
	v_mfma_f32_16x16x32_bf16 v[86:89], v[110:113], v[26:29], v[86:89]
	ds_read_b128 v[122:125], v132 offset:1024
	s_add_i32 s89, s19, s88
	s_mov_b32 m0, s89
	v_mfma_f32_16x16x32_bf16 v[70:73], v[106:109], v[26:29], v[70:73]
	global_load_lds_dwordx4 v126, s[90:91]
	s_add_i32 m0, s89, 0x2000
	v_mfma_f32_16x16x32_bf16 v[90:93], v[118:121], v[22:25], v[90:93]
	global_load_lds_dwordx4 v128, s[90:91]
	s_add_i32 m0, s89, 0x4000
	v_mfma_f32_16x16x32_bf16 v[78:81], v[114:117], v[22:25], v[78:81]
	global_load_lds_dwordx4 v130, s[92:93]
	s_add_u32 s90, s90, 64
	s_addc_u32 s91, s91, 0
	s_add_u32 s92, s92, 64
	s_addc_u32 s93, s93, 0
	v_mfma_f32_16x16x32_bf16 v[62:65], v[110:113], v[22:25], v[62:65]
	v_mfma_f32_16x16x32_bf16 v[50:53], v[106:109], v[22:25], v[50:53]
	s_waitcnt lgkmcnt(0)
	v_mfma_f32_16x16x32_bf16 v[74:77], v[118:121], v[144:147], v[74:77]
	s_add_i32 s19, s8, -1
	s_and_b32 s19, s19, 2
	s_mulk_i32 s19, 0x6000
	v_add_u32_e32 v127, s19, v140
	v_add_u32_e32 v132, s19, v141
	ds_read_b128 v[26:29], v132
	v_mfma_f32_16x16x32_bf16 v[58:61], v[114:117], v[144:147], v[58:61]
	ds_read_b128 v[22:25], v132 offset:1024
	v_mfma_f32_16x16x32_bf16 v[38:41], v[110:113], v[144:147], v[38:41]
	ds_read_b128 v[2:5], v127
	v_mfma_f32_16x16x32_bf16 v[30:33], v[106:109], v[144:147], v[30:33]
	ds_read_b128 v[6:9], v127 offset:1024
	ds_read_b128 v[10:13], v127 offset:2048
	ds_read_b128 v[14:17], v127 offset:3072
	s_add_u32 s20, s20, 0x80
	s_addc_u32 s21, s21, 0
	s_add_i32 s8, s8, 2
	s_cmpk_gt_u32 s17, 0x55
	v_mfma_f32_16x16x32_bf16 v[94:97], v[118:121], v[122:125], v[94:97]
	v_mfma_f32_16x16x32_bf16 v[82:85], v[114:117], v[122:125], v[82:85]
	v_mfma_f32_16x16x32_bf16 v[66:69], v[110:113], v[122:125], v[66:69]
	v_mfma_f32_16x16x32_bf16 v[34:37], v[106:109], v[122:125], v[34:37]
	s_cmp_lt_u32 s8, 86
	s_cbranch_scc1 .Lgf_G5x_top
	s_waitcnt vmcnt(3)
	s_waitcnt lgkmcnt(0)
	s_barrier
	v_mfma_f32_16x16x32_bf16 v[102:105], v[2:5], v[26:29], v[102:105]
	v_mfma_f32_16x16x32_bf16 v[98:101], v[6:9], v[26:29], v[98:101]
	s_add_i32 s17, s8, -3
	s_and_b32 s19, s17, 2
	s_mulk_i32 s19, 0x6000
	v_add_u32_e32 v110, s19, v142
	ds_read_b128 v[106:109], v110
	v_mfma_f32_16x16x32_bf16 v[86:89], v[10:13], v[26:29], v[86:89]
	ds_read_b128 v[144:147], v110 offset:1024
	s_and_b32 s89, s8, 3
	s_mulk_i32 s89, 0x6000
	s_add_i32 s89, s89, s88
	s_mov_b32 m0, s89
	v_mfma_f32_16x16x32_bf16 v[70:73], v[14:17], v[26:29], v[70:73]
	global_load_lds_dwordx4 v126, s[90:91]
	s_add_i32 m0, s89, 0x2000
	v_mfma_f32_16x16x32_bf16 v[90:93], v[2:5], v[22:25], v[90:93]
	global_load_lds_dwordx4 v128, s[90:91]
	s_add_i32 m0, s89, 0x4000
	v_mfma_f32_16x16x32_bf16 v[78:81], v[6:9], v[22:25], v[78:81]
	global_load_lds_dwordx4 v130, s[92:93]
	s_add_u32 s90, s90, 64
	s_addc_u32 s91, s91, 0
	s_add_u32 s92, s92, 64
	s_addc_u32 s93, s93, 0
	v_mfma_f32_16x16x32_bf16 v[62:65], v[10:13], v[22:25], v[62:65]
	v_mfma_f32_16x16x32_bf16 v[50:53], v[14:17], v[22:25], v[50:53]
	s_waitcnt lgkmcnt(0)
	v_mfma_f32_16x16x32_bf16 v[74:77], v[2:5], v[106:109], v[74:77]
	s_add_i32 s26, s8, -2
	s_and_b32 s28, s26, 3
	s_mulk_i32 s28, 0x6000
	v_add_u32_e32 v127, s28, v140
	v_add_u32_e32 v143, s28, v141
	ds_read_b128 v[26:29], v143
	v_mfma_f32_16x16x32_bf16 v[58:61], v[6:9], v[106:109], v[58:61]
	ds_read_b128 v[22:25], v143 offset:1024
	v_mfma_f32_16x16x32_bf16 v[38:41], v[10:13], v[106:109], v[38:41]
	ds_read_b128 v[118:121], v127
	v_mfma_f32_16x16x32_bf16 v[30:33], v[14:17], v[106:109], v[30:33]
	ds_read_b128 v[114:117], v127 offset:1024
	ds_read_b128 v[110:113], v127 offset:2048
	ds_read_b128 v[106:109], v127 offset:3072
	v_mfma_f32_16x16x32_bf16 v[94:97], v[2:5], v[144:147], v[94:97]
	v_mfma_f32_16x16x32_bf16 v[82:85], v[6:9], v[144:147], v[82:85]
	v_mfma_f32_16x16x32_bf16 v[66:69], v[10:13], v[144:147], v[66:69]
	v_mfma_f32_16x16x32_bf16 v[34:37], v[14:17], v[144:147], v[34:37]
	s_waitcnt vmcnt(3)
	s_waitcnt lgkmcnt(0)
	s_barrier
	v_mfma_f32_16x16x32_bf16 v[102:105], v[118:121], v[26:29], v[102:105]
	v_mfma_f32_16x16x32_bf16 v[98:101], v[114:117], v[26:29], v[98:101]
	v_add_u32_e32 v132, s28, v142
	ds_read_b128 v[144:147], v132
	v_mfma_f32_16x16x32_bf16 v[86:89], v[110:113], v[26:29], v[86:89]
	ds_read_b128 v[122:125], v132 offset:1024
	v_mfma_f32_16x16x32_bf16 v[70:73], v[106:109], v[26:29], v[70:73]
	v_mfma_f32_16x16x32_bf16 v[90:93], v[118:121], v[22:25], v[90:93]
	v_mfma_f32_16x16x32_bf16 v[78:81], v[114:117], v[22:25], v[78:81]
	v_mfma_f32_16x16x32_bf16 v[62:65], v[110:113], v[22:25], v[62:65]
	v_mfma_f32_16x16x32_bf16 v[50:53], v[106:109], v[22:25], v[50:53]
	s_waitcnt lgkmcnt(0)
	v_mfma_f32_16x16x32_bf16 v[74:77], v[118:121], v[144:147], v[74:77]
	s_add_i32 s19, s8, -1
	s_and_b32 s19, s19, 2
	s_mulk_i32 s19, 0x6000
	v_add_u32_e32 v127, s19, v140
	v_add_u32_e32 v132, s19, v141
	ds_read_b128 v[26:29], v132
	v_mfma_f32_16x16x32_bf16 v[58:61], v[114:117], v[144:147], v[58:61]
	ds_read_b128 v[22:25], v132 offset:1024
	v_mfma_f32_16x16x32_bf16 v[38:41], v[110:113], v[144:147], v[38:41]
	ds_read_b128 v[2:5], v127
	v_mfma_f32_16x16x32_bf16 v[30:33], v[106:109], v[144:147], v[30:33]
	ds_read_b128 v[6:9], v127 offset:1024
	ds_read_b128 v[10:13], v127 offset:2048
	ds_read_b128 v[14:17], v127 offset:3072
	s_add_u32 s20, s20, 0x80
	s_addc_u32 s21, s21, 0
	s_add_i32 s8, s8, 2
	s_cmpk_gt_u32 s17, 0x55
	v_mfma_f32_16x16x32_bf16 v[94:97], v[118:121], v[122:125], v[94:97]
	v_mfma_f32_16x16x32_bf16 v[82:85], v[114:117], v[122:125], v[82:85]
	v_mfma_f32_16x16x32_bf16 v[66:69], v[110:113], v[122:125], v[66:69]
	v_mfma_f32_16x16x32_bf16 v[34:37], v[106:109], v[122:125], v[34:37]
	s_waitcnt vmcnt(0)
	s_waitcnt lgkmcnt(0)
	s_barrier
	v_mfma_f32_16x16x32_bf16 v[102:105], v[2:5], v[26:29], v[102:105]
	v_mfma_f32_16x16x32_bf16 v[98:101], v[6:9], v[26:29], v[98:101]
	s_add_i32 s17, s8, -3
	s_and_b32 s19, s17, 2
	s_mulk_i32 s19, 0x6000
	v_add_u32_e32 v110, s19, v142
	ds_read_b128 v[106:109], v110
	v_mfma_f32_16x16x32_bf16 v[86:89], v[10:13], v[26:29], v[86:89]
	ds_read_b128 v[144:147], v110 offset:1024
	v_mfma_f32_16x16x32_bf16 v[70:73], v[14:17], v[26:29], v[70:73]
	v_mfma_f32_16x16x32_bf16 v[90:93], v[2:5], v[22:25], v[90:93]
	v_mfma_f32_16x16x32_bf16 v[78:81], v[6:9], v[22:25], v[78:81]
	v_mfma_f32_16x16x32_bf16 v[62:65], v[10:13], v[22:25], v[62:65]
	v_mfma_f32_16x16x32_bf16 v[50:53], v[14:17], v[22:25], v[50:53]
	s_waitcnt lgkmcnt(0)
	v_mfma_f32_16x16x32_bf16 v[74:77], v[2:5], v[106:109], v[74:77]
	s_add_i32 s26, s8, -2
	s_and_b32 s28, s26, 3
	s_mulk_i32 s28, 0x6000
	v_add_u32_e32 v127, s28, v140
	v_add_u32_e32 v143, s28, v141
	ds_read_b128 v[26:29], v143
	v_mfma_f32_16x16x32_bf16 v[58:61], v[6:9], v[106:109], v[58:61]
	ds_read_b128 v[22:25], v143 offset:1024
	v_mfma_f32_16x16x32_bf16 v[38:41], v[10:13], v[106:109], v[38:41]
	ds_read_b128 v[118:121], v127
	v_mfma_f32_16x16x32_bf16 v[30:33], v[14:17], v[106:109], v[30:33]
	ds_read_b128 v[114:117], v127 offset:1024
	ds_read_b128 v[110:113], v127 offset:2048
	ds_read_b128 v[106:109], v127 offset:3072
	v_mfma_f32_16x16x32_bf16 v[94:97], v[2:5], v[144:147], v[94:97]
	v_mfma_f32_16x16x32_bf16 v[82:85], v[6:9], v[144:147], v[82:85]
	v_mfma_f32_16x16x32_bf16 v[66:69], v[10:13], v[144:147], v[66:69]
	v_mfma_f32_16x16x32_bf16 v[34:37], v[14:17], v[144:147], v[34:37]
	s_waitcnt vmcnt(0)
	s_waitcnt lgkmcnt(0)
	s_barrier
	v_mfma_f32_16x16x32_bf16 v[102:105], v[118:121], v[26:29], v[102:105]
	v_mfma_f32_16x16x32_bf16 v[98:101], v[114:117], v[26:29], v[98:101]
	v_add_u32_e32 v132, s28, v142
	ds_read_b128 v[144:147], v132
	v_mfma_f32_16x16x32_bf16 v[86:89], v[110:113], v[26:29], v[86:89]
	ds_read_b128 v[122:125], v132 offset:1024
	v_mfma_f32_16x16x32_bf16 v[70:73], v[106:109], v[26:29], v[70:73]
	v_mfma_f32_16x16x32_bf16 v[90:93], v[118:121], v[22:25], v[90:93]
	v_mfma_f32_16x16x32_bf16 v[78:81], v[114:117], v[22:25], v[78:81]
	v_mfma_f32_16x16x32_bf16 v[62:65], v[110:113], v[22:25], v[62:65]
	v_mfma_f32_16x16x32_bf16 v[50:53], v[106:109], v[22:25], v[50:53]
	s_waitcnt lgkmcnt(0)
	v_mfma_f32_16x16x32_bf16 v[74:77], v[118:121], v[144:147], v[74:77]
	v_mfma_f32_16x16x32_bf16 v[58:61], v[114:117], v[144:147], v[58:61]
	v_mfma_f32_16x16x32_bf16 v[38:41], v[110:113], v[144:147], v[38:41]
	v_mfma_f32_16x16x32_bf16 v[30:33], v[106:109], v[144:147], v[30:33]
	s_add_u32 s20, s20, 0x80
	s_addc_u32 s21, s21, 0
	s_add_i32 s8, s8, 2
	s_cmpk_gt_u32 s17, 0x55
	v_mfma_f32_16x16x32_bf16 v[94:97], v[118:121], v[122:125], v[94:97]
	v_mfma_f32_16x16x32_bf16 v[82:85], v[114:117], v[122:125], v[82:85]
	v_mfma_f32_16x16x32_bf16 v[66:69], v[110:113], v[122:125], v[66:69]
	v_mfma_f32_16x16x32_bf16 v[34:37], v[106:109], v[122:125], v[34:37]
	s_branch .LBB0_135
.Lgr_G5x_entry:
	s_waitcnt vmcnt(3)
	s_waitcnt lgkmcnt(0)
	s_barrier
	v_mfma_f32_16x16x32_bf16 v[102:105], v[2:5], v[26:29], v[102:105]
	v_mfma_f32_16x16x32_bf16 v[98:101], v[6:9], v[26:29], v[98:101]
	s_add_i32 s17, s8, -3
	s_and_b32 s19, s17, 2
	s_mulk_i32 s19, 0x6000
	v_add_u32_e32 v110, s19, v142
	ds_read_b128 v[106:109], v110
	v_mfma_f32_16x16x32_bf16 v[86:89], v[10:13], v[26:29], v[86:89]
	ds_read_b128 v[144:147], v110 offset:1024
	s_and_b32 s89, s8, 3
	s_mulk_i32 s89, 0x6000
	s_add_i32 s89, s89, s88
	s_mov_b32 m0, s89
	v_mfma_f32_16x16x32_bf16 v[70:73], v[14:17], v[26:29], v[70:73]
	global_load_lds_dwordx4 v126, s[90:91]
	s_add_i32 m0, s89, 0x2000
	v_mfma_f32_16x16x32_bf16 v[90:93], v[2:5], v[22:25], v[90:93]
	global_load_lds_dwordx4 v128, s[90:91]
	s_add_i32 m0, s89, 0x4000
	v_mfma_f32_16x16x32_bf16 v[78:81], v[6:9], v[22:25], v[78:81]
	global_load_lds_dwordx4 v130, s[92:93]
	s_add_u32 s90, s90, 64
	s_addc_u32 s91, s91, 0
	s_add_u32 s92, s92, 64
	s_addc_u32 s93, s93, 0
	v_mfma_f32_16x16x32_bf16 v[62:65], v[10:13], v[22:25], v[62:65]
	v_mfma_f32_16x16x32_bf16 v[50:53], v[14:17], v[22:25], v[50:53]
	s_waitcnt vmcnt(3)
	s_waitcnt lgkmcnt(0)
	s_barrier
	v_mfma_f32_16x16x32_bf16 v[74:77], v[2:5], v[106:109], v[74:77]
	s_add_i32 s26, s8, -2
	s_and_b32 s28, s26, 3
	s_mulk_i32 s28, 0x6000
	v_add_u32_e32 v127, s28, v140
	v_add_u32_e32 v143, s28, v141
	ds_read_b128 v[26:29], v143
	v_mfma_f32_16x16x32_bf16 v[58:61], v[6:9], v[106:109], v[58:61]
	ds_read_b128 v[22:25], v143 offset:1024
	v_mfma_f32_16x16x32_bf16 v[38:41], v[10:13], v[106:109], v[38:41]
	ds_read_b128 v[118:121], v127
	v_mfma_f32_16x16x32_bf16 v[30:33], v[14:17], v[106:109], v[30:33]
	ds_read_b128 v[114:117], v127 offset:1024
	ds_read_b128 v[110:113], v127 offset:2048
	ds_read_b128 v[106:109], v127 offset:3072
	v_mfma_f32_16x16x32_bf16 v[94:97], v[2:5], v[144:147], v[94:97]
	v_mfma_f32_16x16x32_bf16 v[82:85], v[6:9], v[144:147], v[82:85]
	v_mfma_f32_16x16x32_bf16 v[66:69], v[10:13], v[144:147], v[66:69]
	v_mfma_f32_16x16x32_bf16 v[34:37], v[14:17], v[144:147], v[34:37]
	s_waitcnt lgkmcnt(0)
	v_mfma_f32_16x16x32_bf16 v[102:105], v[118:121], v[26:29], v[102:105]
	v_mfma_f32_16x16x32_bf16 v[98:101], v[114:117], v[26:29], v[98:101]
	v_add_u32_e32 v132, s28, v142
	ds_read_b128 v[144:147], v132
	v_mfma_f32_16x16x32_bf16 v[86:89], v[110:113], v[26:29], v[86:89]
	ds_read_b128 v[122:125], v132 offset:1024
	s_add_i32 s89, s19, s88
	s_mov_b32 m0, s89
	v_mfma_f32_16x16x32_bf16 v[70:73], v[106:109], v[26:29], v[70:73]
	global_load_lds_dwordx4 v126, s[90:91]
	s_add_i32 m0, s89, 0x2000
	v_mfma_f32_16x16x32_bf16 v[90:93], v[118:121], v[22:25], v[90:93]
	global_load_lds_dwordx4 v128, s[90:91]
	s_add_i32 m0, s89, 0x4000
	v_mfma_f32_16x16x32_bf16 v[78:81], v[114:117], v[22:25], v[78:81]
	global_load_lds_dwordx4 v130, s[92:93]
	s_add_u32 s90, s90, 64
	s_addc_u32 s91, s91, 0
	s_add_u32 s92, s92, 64
	s_addc_u32 s93, s93, 0
	v_mfma_f32_16x16x32_bf16 v[62:65], v[110:113], v[22:25], v[62:65]
	v_mfma_f32_16x16x32_bf16 v[50:53], v[106:109], v[22:25], v[50:53]
.Lgr_G5x_top:
	s_waitcnt vmcnt(3)
	s_waitcnt lgkmcnt(0)
	s_barrier
	v_mfma_f32_16x16x32_bf16 v[74:77], v[118:121], v[144:147], v[74:77]
	s_add_i32 s19, s8, -1
	s_and_b32 s19, s19, 2
	s_mulk_i32 s19, 0x6000
	v_add_u32_e32 v127, s19, v140
	v_add_u32_e32 v132, s19, v141
	ds_read_b128 v[26:29], v132
	v_mfma_f32_16x16x32_bf16 v[58:61], v[114:117], v[144:147], v[58:61]
	ds_read_b128 v[22:25], v132 offset:1024
	v_mfma_f32_16x16x32_bf16 v[38:41], v[110:113], v[144:147], v[38:41]
	ds_read_b128 v[2:5], v127
	v_mfma_f32_16x16x32_bf16 v[30:33], v[106:109], v[144:147], v[30:33]
	ds_read_b128 v[6:9], v127 offset:1024
	ds_read_b128 v[10:13], v127 offset:2048
	ds_read_b128 v[14:17], v127 offset:3072
	s_add_u32 s20, s20, 0x80
	s_addc_u32 s21, s21, 0
	s_add_i32 s8, s8, 2
	s_cmpk_gt_u32 s17, 0x55
	v_mfma_f32_16x16x32_bf16 v[94:97], v[118:121], v[122:125], v[94:97]
	v_mfma_f32_16x16x32_bf16 v[82:85], v[114:117], v[122:125], v[82:85]
	v_mfma_f32_16x16x32_bf16 v[66:69], v[110:113], v[122:125], v[66:69]
	v_mfma_f32_16x16x32_bf16 v[34:37], v[106:109], v[122:125], v[34:37]
	s_cmp_lt_u32 s8, 86
	s_cbranch_scc0 .Lgr_G5x_tail
	s_waitcnt lgkmcnt(0)
	v_mfma_f32_16x16x32_bf16 v[102:105], v[2:5], v[26:29], v[102:105]
	v_mfma_f32_16x16x32_bf16 v[98:101], v[6:9], v[26:29], v[98:101]
	s_add_i32 s17, s8, -3
	s_and_b32 s19, s17, 2
	s_mulk_i32 s19, 0x6000
	v_add_u32_e32 v110, s19, v142
	ds_read_b128 v[106:109], v110
	v_mfma_f32_16x16x32_bf16 v[86:89], v[10:13], v[26:29], v[86:89]
	ds_read_b128 v[144:147], v110 offset:1024
	s_and_b32 s89, s8, 3
	s_mulk_i32 s89, 0x6000
	s_add_i32 s89, s89, s88
	s_mov_b32 m0, s89
	v_mfma_f32_16x16x32_bf16 v[70:73], v[14:17], v[26:29], v[70:73]
	global_load_lds_dwordx4 v126, s[90:91]
	s_add_i32 m0, s89, 0x2000
	v_mfma_f32_16x16x32_bf16 v[90:93], v[2:5], v[22:25], v[90:93]
	global_load_lds_dwordx4 v128, s[90:91]
	s_add_i32 m0, s89, 0x4000
	v_mfma_f32_16x16x32_bf16 v[78:81], v[6:9], v[22:25], v[78:81]
	global_load_lds_dwordx4 v130, s[92:93]
	s_add_u32 s90, s90, 64
	s_addc_u32 s91, s91, 0
	s_add_u32 s92, s92, 64
	s_addc_u32 s93, s93, 0
	v_mfma_f32_16x16x32_bf16 v[62:65], v[10:13], v[22:25], v[62:65]
	v_mfma_f32_16x16x32_bf16 v[50:53], v[14:17], v[22:25], v[50:53]
	s_waitcnt vmcnt(3)
	s_waitcnt lgkmcnt(0)
	s_barrier
	v_mfma_f32_16x16x32_bf16 v[74:77], v[2:5], v[106:109], v[74:77]
	s_add_i32 s26, s8, -2
	s_and_b32 s28, s26, 3
	s_mulk_i32 s28, 0x6000
	v_add_u32_e32 v127, s28, v140
	v_add_u32_e32 v143, s28, v141
	ds_read_b128 v[26:29], v143
	v_mfma_f32_16x16x32_bf16 v[58:61], v[6:9], v[106:109], v[58:61]
	ds_read_b128 v[22:25], v143 offset:1024
	v_mfma_f32_16x16x32_bf16 v[38:41], v[10:13], v[106:109], v[38:41]
	ds_read_b128 v[118:121], v127
	v_mfma_f32_16x16x32_bf16 v[30:33], v[14:17], v[106:109], v[30:33]
	ds_read_b128 v[114:117], v127 offset:1024
	ds_read_b128 v[110:113], v127 offset:2048
	ds_read_b128 v[106:109], v127 offset:3072
	v_mfma_f32_16x16x32_bf16 v[94:97], v[2:5], v[144:147], v[94:97]
	v_mfma_f32_16x16x32_bf16 v[82:85], v[6:9], v[144:147], v[82:85]
	v_mfma_f32_16x16x32_bf16 v[66:69], v[10:13], v[144:147], v[66:69]
	v_mfma_f32_16x16x32_bf16 v[34:37], v[14:17], v[144:147], v[34:37]
	s_waitcnt lgkmcnt(0)
	v_mfma_f32_16x16x32_bf16 v[102:105], v[118:121], v[26:29], v[102:105]
	v_mfma_f32_16x16x32_bf16 v[98:101], v[114:117], v[26:29], v[98:101]
	v_add_u32_e32 v132, s28, v142
	ds_read_b128 v[144:147], v132
	v_mfma_f32_16x16x32_bf16 v[86:89], v[110:113], v[26:29], v[86:89]
	ds_read_b128 v[122:125], v132 offset:1024
	s_add_i32 s89, s19, s88
	s_mov_b32 m0, s89
	v_mfma_f32_16x16x32_bf16 v[70:73], v[106:109], v[26:29], v[70:73]
	global_load_lds_dwordx4 v126, s[90:91]
	s_add_i32 m0, s89, 0x2000
	v_mfma_f32_16x16x32_bf16 v[90:93], v[118:121], v[22:25], v[90:93]
	global_load_lds_dwordx4 v128, s[90:91]
	s_add_i32 m0, s89, 0x4000
	v_mfma_f32_16x16x32_bf16 v[78:81], v[114:117], v[22:25], v[78:81]
	global_load_lds_dwordx4 v130, s[92:93]
	s_add_u32 s90, s90, 64
	s_addc_u32 s91, s91, 0
	s_add_u32 s92, s92, 64
	s_addc_u32 s93, s93, 0
	v_mfma_f32_16x16x32_bf16 v[62:65], v[110:113], v[22:25], v[62:65]
	v_mfma_f32_16x16x32_bf16 v[50:53], v[106:109], v[22:25], v[50:53]
	s_branch .Lgr_G5x_top
.Lgr_G5x_tail:
	s_waitcnt lgkmcnt(0)
	v_mfma_f32_16x16x32_bf16 v[102:105], v[2:5], v[26:29], v[102:105]
	v_mfma_f32_16x16x32_bf16 v[98:101], v[6:9], v[26:29], v[98:101]
	s_add_i32 s17, s8, -3
	s_and_b32 s19, s17, 2
	s_mulk_i32 s19, 0x6000
	v_add_u32_e32 v110, s19, v142
	ds_read_b128 v[106:109], v110
	v_mfma_f32_16x16x32_bf16 v[86:89], v[10:13], v[26:29], v[86:89]
	ds_read_b128 v[144:147], v110 offset:1024
	s_and_b32 s89, s8, 3
	s_mulk_i32 s89, 0x6000
	s_add_i32 s89, s89, s88
	s_mov_b32 m0, s89
	v_mfma_f32_16x16x32_bf16 v[70:73], v[14:17], v[26:29], v[70:73]
	global_load_lds_dwordx4 v126, s[90:91]
	s_add_i32 m0, s89, 0x2000
	v_mfma_f32_16x16x32_bf16 v[90:93], v[2:5], v[22:25], v[90:93]
	global_load_lds_dwordx4 v128, s[90:91]
	s_add_i32 m0, s89, 0x4000
	v_mfma_f32_16x16x32_bf16 v[78:81], v[6:9], v[22:25], v[78:81]
	global_load_lds_dwordx4 v130, s[92:93]
	s_add_u32 s90, s90, 64
	s_addc_u32 s91, s91, 0
	s_add_u32 s92, s92, 64
	s_addc_u32 s93, s93, 0
	v_mfma_f32_16x16x32_bf16 v[62:65], v[10:13], v[22:25], v[62:65]
	v_mfma_f32_16x16x32_bf16 v[50:53], v[14:17], v[22:25], v[50:53]
	s_waitcnt vmcnt(3)
	s_waitcnt lgkmcnt(0)
	s_barrier
	v_mfma_f32_16x16x32_bf16 v[74:77], v[2:5], v[106:109], v[74:77]
	s_add_i32 s26, s8, -2
	s_and_b32 s28, s26, 3
	s_mulk_i32 s28, 0x6000
	v_add_u32_e32 v127, s28, v140
	v_add_u32_e32 v143, s28, v141
	ds_read_b128 v[26:29], v143
	v_mfma_f32_16x16x32_bf16 v[58:61], v[6:9], v[106:109], v[58:61]
	ds_read_b128 v[22:25], v143 offset:1024
	v_mfma_f32_16x16x32_bf16 v[38:41], v[10:13], v[106:109], v[38:41]
	ds_read_b128 v[118:121], v127
	v_mfma_f32_16x16x32_bf16 v[30:33], v[14:17], v[106:109], v[30:33]
	ds_read_b128 v[114:117], v127 offset:1024
	ds_read_b128 v[110:113], v127 offset:2048
	ds_read_b128 v[106:109], v127 offset:3072
	v_mfma_f32_16x16x32_bf16 v[94:97], v[2:5], v[144:147], v[94:97]
	v_mfma_f32_16x16x32_bf16 v[82:85], v[6:9], v[144:147], v[82:85]
	v_mfma_f32_16x16x32_bf16 v[66:69], v[10:13], v[144:147], v[66:69]
	v_mfma_f32_16x16x32_bf16 v[34:37], v[14:17], v[144:147], v[34:37]
	s_waitcnt lgkmcnt(0)
	v_mfma_f32_16x16x32_bf16 v[102:105], v[118:121], v[26:29], v[102:105]
	v_mfma_f32_16x16x32_bf16 v[98:101], v[114:117], v[26:29], v[98:101]
	v_add_u32_e32 v132, s28, v142
	ds_read_b128 v[144:147], v132
	v_mfma_f32_16x16x32_bf16 v[86:89], v[110:113], v[26:29], v[86:89]
	ds_read_b128 v[122:125], v132 offset:1024
	v_mfma_f32_16x16x32_bf16 v[70:73], v[106:109], v[26:29], v[70:73]
	v_mfma_f32_16x16x32_bf16 v[90:93], v[118:121], v[22:25], v[90:93]
	v_mfma_f32_16x16x32_bf16 v[78:81], v[114:117], v[22:25], v[78:81]
	v_mfma_f32_16x16x32_bf16 v[62:65], v[110:113], v[22:25], v[62:65]
	v_mfma_f32_16x16x32_bf16 v[50:53], v[106:109], v[22:25], v[50:53]
	s_waitcnt vmcnt(0)
	s_waitcnt lgkmcnt(0)
	s_barrier
	v_mfma_f32_16x16x32_bf16 v[74:77], v[118:121], v[144:147], v[74:77]
	s_add_i32 s19, s8, -1
	s_and_b32 s19, s19, 2
	s_mulk_i32 s19, 0x6000
	v_add_u32_e32 v127, s19, v140
	v_add_u32_e32 v132, s19, v141
	ds_read_b128 v[26:29], v132
	v_mfma_f32_16x16x32_bf16 v[58:61], v[114:117], v[144:147], v[58:61]
	ds_read_b128 v[22:25], v132 offset:1024
	v_mfma_f32_16x16x32_bf16 v[38:41], v[110:113], v[144:147], v[38:41]
	ds_read_b128 v[2:5], v127
	v_mfma_f32_16x16x32_bf16 v[30:33], v[106:109], v[144:147], v[30:33]
	ds_read_b128 v[6:9], v127 offset:1024
	ds_read_b128 v[10:13], v127 offset:2048
	ds_read_b128 v[14:17], v127 offset:3072
	s_add_u32 s20, s20, 0x80
	s_addc_u32 s21, s21, 0
	s_add_i32 s8, s8, 2
	s_cmpk_gt_u32 s17, 0x55
	v_mfma_f32_16x16x32_bf16 v[94:97], v[118:121], v[122:125], v[94:97]
	v_mfma_f32_16x16x32_bf16 v[82:85], v[114:117], v[122:125], v[82:85]
	v_mfma_f32_16x16x32_bf16 v[66:69], v[110:113], v[122:125], v[66:69]
	v_mfma_f32_16x16x32_bf16 v[34:37], v[106:109], v[122:125], v[34:37]
	s_waitcnt lgkmcnt(0)
	v_mfma_f32_16x16x32_bf16 v[102:105], v[2:5], v[26:29], v[102:105]
	v_mfma_f32_16x16x32_bf16 v[98:101], v[6:9], v[26:29], v[98:101]
	s_add_i32 s17, s8, -3
	s_and_b32 s19, s17, 2
	s_mulk_i32 s19, 0x6000
	v_add_u32_e32 v110, s19, v142
	ds_read_b128 v[106:109], v110
	v_mfma_f32_16x16x32_bf16 v[86:89], v[10:13], v[26:29], v[86:89]
	ds_read_b128 v[144:147], v110 offset:1024
	v_mfma_f32_16x16x32_bf16 v[70:73], v[14:17], v[26:29], v[70:73]
	v_mfma_f32_16x16x32_bf16 v[90:93], v[2:5], v[22:25], v[90:93]
	v_mfma_f32_16x16x32_bf16 v[78:81], v[6:9], v[22:25], v[78:81]
	v_mfma_f32_16x16x32_bf16 v[62:65], v[10:13], v[22:25], v[62:65]
	v_mfma_f32_16x16x32_bf16 v[50:53], v[14:17], v[22:25], v[50:53]
	s_waitcnt vmcnt(0)
	s_waitcnt lgkmcnt(0)
	s_barrier
	v_mfma_f32_16x16x32_bf16 v[74:77], v[2:5], v[106:109], v[74:77]
	s_add_i32 s26, s8, -2
	s_and_b32 s28, s26, 3
	s_mulk_i32 s28, 0x6000
	v_add_u32_e32 v127, s28, v140
	v_add_u32_e32 v143, s28, v141
	ds_read_b128 v[26:29], v143
	v_mfma_f32_16x16x32_bf16 v[58:61], v[6:9], v[106:109], v[58:61]
	ds_read_b128 v[22:25], v143 offset:1024
	v_mfma_f32_16x16x32_bf16 v[38:41], v[10:13], v[106:109], v[38:41]
	ds_read_b128 v[118:121], v127
	v_mfma_f32_16x16x32_bf16 v[30:33], v[14:17], v[106:109], v[30:33]
	ds_read_b128 v[114:117], v127 offset:1024
	ds_read_b128 v[110:113], v127 offset:2048
	ds_read_b128 v[106:109], v127 offset:3072
	v_mfma_f32_16x16x32_bf16 v[94:97], v[2:5], v[144:147], v[94:97]
	v_mfma_f32_16x16x32_bf16 v[82:85], v[6:9], v[144:147], v[82:85]
	v_mfma_f32_16x16x32_bf16 v[66:69], v[10:13], v[144:147], v[66:69]
	v_mfma_f32_16x16x32_bf16 v[34:37], v[14:17], v[144:147], v[34:37]
	s_waitcnt lgkmcnt(0)
	v_mfma_f32_16x16x32_bf16 v[102:105], v[118:121], v[26:29], v[102:105]
	v_mfma_f32_16x16x32_bf16 v[98:101], v[114:117], v[26:29], v[98:101]
	v_add_u32_e32 v132, s28, v142
	ds_read_b128 v[144:147], v132
	v_mfma_f32_16x16x32_bf16 v[86:89], v[110:113], v[26:29], v[86:89]
	ds_read_b128 v[122:125], v132 offset:1024
	v_mfma_f32_16x16x32_bf16 v[70:73], v[106:109], v[26:29], v[70:73]
	v_mfma_f32_16x16x32_bf16 v[90:93], v[118:121], v[22:25], v[90:93]
	v_mfma_f32_16x16x32_bf16 v[78:81], v[114:117], v[22:25], v[78:81]
	v_mfma_f32_16x16x32_bf16 v[62:65], v[110:113], v[22:25], v[62:65]
	v_mfma_f32_16x16x32_bf16 v[50:53], v[106:109], v[22:25], v[50:53]
	s_waitcnt vmcnt(0)
	s_waitcnt lgkmcnt(0)
	s_barrier
	v_mfma_f32_16x16x32_bf16 v[74:77], v[118:121], v[144:147], v[74:77]
	v_mfma_f32_16x16x32_bf16 v[58:61], v[114:117], v[144:147], v[58:61]
	v_mfma_f32_16x16x32_bf16 v[38:41], v[110:113], v[144:147], v[38:41]
	v_mfma_f32_16x16x32_bf16 v[30:33], v[106:109], v[144:147], v[30:33]
	s_add_u32 s20, s20, 0x80
	s_addc_u32 s21, s21, 0
	s_add_i32 s8, s8, 2
	s_cmpk_gt_u32 s17, 0x55
	v_mfma_f32_16x16x32_bf16 v[94:97], v[118:121], v[122:125], v[94:97]
	v_mfma_f32_16x16x32_bf16 v[82:85], v[114:117], v[122:125], v[82:85]
	v_mfma_f32_16x16x32_bf16 v[66:69], v[110:113], v[122:125], v[66:69]
	v_mfma_f32_16x16x32_bf16 v[34:37], v[106:109], v[122:125], v[34:37]
	s_branch .LBB0_135

.Lgf_G4x_top:
	s_waitcnt vmcnt(4)
	s_waitcnt lgkmcnt(0)
	s_barrier
	v_mfma_f32_16x16x32_bf16 v[158:161], v[122:125], v[150:153], v[158:161]
	v_mfma_f32_16x16x32_bf16 v[94:97], v[126:129], v[150:153], v[94:97]
	s_add_i32 s28, s31, 0xfffe8000
	s_and_b32 s34, s28, 0x10000
	v_add_u32_e32 v170, s34, v230
	ds_read_b128 v[162:165], v170
	v_mfma_f32_16x16x32_bf16 v[62:65], v[130:133], v[150:153], v[62:65]
	ds_read_b128 v[166:169], v170 offset:1024
	v_mfma_f32_16x16x32_bf16 v[30:33], v[134:137], v[150:153], v[30:33]
	ds_read_b128 v[232:235], v170 offset:2048
	v_mfma_f32_16x16x32_bf16 v[118:121], v[122:125], v[146:149], v[118:121]
	ds_read_b128 v[236:239], v170 offset:3072
	s_and_b32 s89, s31, 0x18000
	s_add_i32 s89, s89, s88
	s_mov_b32 m0, s89
	v_mfma_f32_16x16x32_bf16 v[86:89], v[126:129], v[146:149], v[86:89]
	global_load_lds_dwordx4 v186, s[90:91]
	s_add_i32 m0, s89, 0x2000
	v_mfma_f32_16x16x32_bf16 v[54:57], v[130:133], v[146:149], v[54:57]
	v_mfma_f32_16x16x32_bf16 v[22:25], v[134:137], v[146:149], v[22:25]
	global_load_lds_dwordx4 v188, s[90:91]
	s_add_i32 m0, s89, 0x4000
	v_mfma_f32_16x16x32_bf16 v[110:113], v[122:125], v[142:145], v[110:113]
	v_mfma_f32_16x16x32_bf16 v[78:81], v[126:129], v[142:145], v[78:81]
	global_load_lds_dwordx4 v190, s[92:93]
	s_add_i32 m0, s89, 0x6000
	v_mfma_f32_16x16x32_bf16 v[46:49], v[130:133], v[142:145], v[46:49]
	v_mfma_f32_16x16x32_bf16 v[14:17], v[134:137], v[142:145], v[14:17]
	global_load_lds_dwordx4 v192, s[92:93]
	s_add_u32 s90, s90, 64
	s_addc_u32 s91, s91, 0
	s_add_u32 s92, s92, 64
	s_addc_u32 s93, s93, 0
	v_mfma_f32_16x16x32_bf16 v[102:105], v[122:125], v[138:141], v[102:105]
	v_mfma_f32_16x16x32_bf16 v[70:73], v[126:129], v[138:141], v[70:73]
	v_mfma_f32_16x16x32_bf16 v[38:41], v[130:133], v[138:141], v[38:41]
	v_mfma_f32_16x16x32_bf16 v[6:9], v[134:137], v[138:141], v[6:9]
	s_waitcnt lgkmcnt(0)
	v_mfma_f32_16x16x32_bf16 v[154:157], v[122:125], v[162:165], v[154:157]
	s_add_i32 s28, s31, 0xffff0000
	s_and_b32 s35, s28, 0x18000
	v_add_u32_e32 v187, s35, v200
	v_add_u32_e32 v226, s35, v201
	ds_read_b128 v[150:153], v226
	v_mfma_f32_16x16x32_bf16 v[90:93], v[126:129], v[162:165], v[90:93]
	ds_read_b128 v[146:149], v226 offset:1024
	v_mfma_f32_16x16x32_bf16 v[58:61], v[130:133], v[162:165], v[58:61]
	ds_read_b128 v[142:145], v226 offset:2048
	v_mfma_f32_16x16x32_bf16 v[26:29], v[134:137], v[162:165], v[26:29]
	ds_read_b128 v[138:141], v226 offset:3072
	v_mfma_f32_16x16x32_bf16 v[114:117], v[122:125], v[166:169], v[114:117]
	ds_read_b128 v[174:177], v187
	v_mfma_f32_16x16x32_bf16 v[82:85], v[126:129], v[166:169], v[82:85]
	ds_read_b128 v[170:173], v187 offset:1024
	v_mfma_f32_16x16x32_bf16 v[50:53], v[130:133], v[166:169], v[50:53]
	ds_read_b128 v[162:165], v187 offset:3072
	v_mfma_f32_16x16x32_bf16 v[18:21], v[134:137], v[166:169], v[18:21]
	ds_read_b128 v[166:169], v187 offset:2048
	v_mfma_f32_16x16x32_bf16 v[106:109], v[122:125], v[232:235], v[106:109]
	v_mfma_f32_16x16x32_bf16 v[74:77], v[126:129], v[232:235], v[74:77]
	v_mfma_f32_16x16x32_bf16 v[42:45], v[130:133], v[232:235], v[42:45]
	v_mfma_f32_16x16x32_bf16 v[10:13], v[134:137], v[232:235], v[10:13]
	v_mfma_f32_16x16x32_bf16 v[98:101], v[122:125], v[236:239], v[98:101]
	v_mfma_f32_16x16x32_bf16 v[66:69], v[126:129], v[236:239], v[66:69]
	v_mfma_f32_16x16x32_bf16 v[34:37], v[130:133], v[236:239], v[34:37]
	v_mfma_f32_16x16x32_bf16 v[2:5], v[134:137], v[236:239], v[2:5]
	s_waitcnt vmcnt(4)
	s_waitcnt lgkmcnt(0)
	s_barrier
	v_mfma_f32_16x16x32_bf16 v[158:161], v[174:177], v[150:153], v[158:161]
	v_mfma_f32_16x16x32_bf16 v[94:97], v[170:173], v[150:153], v[94:97]
	v_add_u32_e32 v226, s35, v230
	ds_read_b128 v[232:235], v226
	v_mfma_f32_16x16x32_bf16 v[62:65], v[166:169], v[150:153], v[62:65]
	ds_read_b128 v[236:239], v226 offset:1024
	v_mfma_f32_16x16x32_bf16 v[30:33], v[162:165], v[150:153], v[30:33]
	ds_read_b128 v[182:185], v226 offset:2048
	v_mfma_f32_16x16x32_bf16 v[118:121], v[174:177], v[146:149], v[118:121]
	ds_read_b128 v[178:181], v226 offset:3072
	s_add_i32 s89, s34, s88
	s_mov_b32 m0, s89
	v_mfma_f32_16x16x32_bf16 v[86:89], v[170:173], v[146:149], v[86:89]
	global_load_lds_dwordx4 v186, s[90:91]
	s_add_i32 m0, s89, 0x2000
	v_mfma_f32_16x16x32_bf16 v[54:57], v[166:169], v[146:149], v[54:57]
	v_mfma_f32_16x16x32_bf16 v[22:25], v[162:165], v[146:149], v[22:25]
	global_load_lds_dwordx4 v188, s[90:91]
	s_add_i32 m0, s89, 0x4000
	v_mfma_f32_16x16x32_bf16 v[110:113], v[174:177], v[142:145], v[110:113]
	v_mfma_f32_16x16x32_bf16 v[78:81], v[170:173], v[142:145], v[78:81]
	global_load_lds_dwordx4 v190, s[92:93]
	s_add_i32 m0, s89, 0x6000
	v_mfma_f32_16x16x32_bf16 v[46:49], v[166:169], v[142:145], v[46:49]
	v_mfma_f32_16x16x32_bf16 v[14:17], v[162:165], v[142:145], v[14:17]
	global_load_lds_dwordx4 v192, s[92:93]
	s_add_u32 s90, s90, 64
	s_addc_u32 s91, s91, 0
	s_add_u32 s92, s92, 64
	s_addc_u32 s93, s93, 0
	v_mfma_f32_16x16x32_bf16 v[102:105], v[174:177], v[138:141], v[102:105]
	v_mfma_f32_16x16x32_bf16 v[70:73], v[170:173], v[138:141], v[70:73]
	v_mfma_f32_16x16x32_bf16 v[38:41], v[166:169], v[138:141], v[38:41]
	v_mfma_f32_16x16x32_bf16 v[6:9], v[162:165], v[138:141], v[6:9]
	s_waitcnt lgkmcnt(0)
	v_mfma_f32_16x16x32_bf16 v[154:157], v[174:177], v[232:235], v[154:157]
	s_add_i32 s24, s31, 0xffff8000
	s_and_b32 s24, s24, 0x10000
	v_add_u32_e32 v187, s24, v200
	v_add_u32_e32 v226, s24, v201
	ds_read_b128 v[150:153], v226
	v_mfma_f32_16x16x32_bf16 v[90:93], v[170:173], v[232:235], v[90:93]
	ds_read_b128 v[146:149], v226 offset:1024
	v_mfma_f32_16x16x32_bf16 v[58:61], v[166:169], v[232:235], v[58:61]
	ds_read_b128 v[142:145], v226 offset:2048
	v_mfma_f32_16x16x32_bf16 v[26:29], v[162:165], v[232:235], v[26:29]
	ds_read_b128 v[138:141], v226 offset:3072
	v_mfma_f32_16x16x32_bf16 v[114:117], v[174:177], v[236:239], v[114:117]
	ds_read_b128 v[122:125], v187
	v_mfma_f32_16x16x32_bf16 v[82:85], v[170:173], v[236:239], v[82:85]
	ds_read_b128 v[126:129], v187 offset:1024
	v_mfma_f32_16x16x32_bf16 v[50:53], v[166:169], v[236:239], v[50:53]
	ds_read_b128 v[130:133], v187 offset:2048
	v_mfma_f32_16x16x32_bf16 v[18:21], v[162:165], v[236:239], v[18:21]
	ds_read_b128 v[134:137], v187 offset:3072
	s_add_i32 s19, s19, 2
	s_add_u32 s20, s20, 0x80
	s_addc_u32 s21, s21, 0
	s_add_i32 s31, s31, 0x10000
	v_mfma_f32_16x16x32_bf16 v[106:109], v[174:177], v[182:185], v[106:109]
	v_mfma_f32_16x16x32_bf16 v[74:77], v[170:173], v[182:185], v[74:77]
	v_mfma_f32_16x16x32_bf16 v[42:45], v[166:169], v[182:185], v[42:45]
	v_mfma_f32_16x16x32_bf16 v[10:13], v[162:165], v[182:185], v[10:13]
	v_mfma_f32_16x16x32_bf16 v[98:101], v[174:177], v[178:181], v[98:101]
	v_mfma_f32_16x16x32_bf16 v[66:69], v[170:173], v[178:181], v[66:69]
	v_mfma_f32_16x16x32_bf16 v[34:37], v[166:169], v[178:181], v[34:37]
	v_mfma_f32_16x16x32_bf16 v[2:5], v[162:165], v[178:181], v[2:5]
	s_cmp_lt_u32 s19, 28
	s_cbranch_scc1 .Lgf_G4x_top
	s_waitcnt vmcnt(4)
	s_waitcnt lgkmcnt(0)
	s_barrier
	v_mfma_f32_16x16x32_bf16 v[158:161], v[122:125], v[150:153], v[158:161]
	v_mfma_f32_16x16x32_bf16 v[94:97], v[126:129], v[150:153], v[94:97]
	s_add_i32 s28, s31, 0xfffe8000
	s_and_b32 s34, s28, 0x10000
	v_add_u32_e32 v170, s34, v230
	ds_read_b128 v[162:165], v170
	v_mfma_f32_16x16x32_bf16 v[62:65], v[130:133], v[150:153], v[62:65]
	ds_read_b128 v[166:169], v170 offset:1024
	v_mfma_f32_16x16x32_bf16 v[30:33], v[134:137], v[150:153], v[30:33]
	ds_read_b128 v[232:235], v170 offset:2048
	v_mfma_f32_16x16x32_bf16 v[118:121], v[122:125], v[146:149], v[118:121]
	ds_read_b128 v[236:239], v170 offset:3072
	s_and_b32 s89, s31, 0x18000
	s_add_i32 s89, s89, s88
	s_mov_b32 m0, s89
	v_mfma_f32_16x16x32_bf16 v[86:89], v[126:129], v[146:149], v[86:89]
	global_load_lds_dwordx4 v186, s[90:91]
	s_add_i32 m0, s89, 0x2000
	v_mfma_f32_16x16x32_bf16 v[54:57], v[130:133], v[146:149], v[54:57]
	v_mfma_f32_16x16x32_bf16 v[22:25], v[134:137], v[146:149], v[22:25]
	global_load_lds_dwordx4 v188, s[90:91]
	s_add_i32 m0, s89, 0x4000
	v_mfma_f32_16x16x32_bf16 v[110:113], v[122:125], v[142:145], v[110:113]
	v_mfma_f32_16x16x32_bf16 v[78:81], v[126:129], v[142:145], v[78:81]
	global_load_lds_dwordx4 v190, s[92:93]
	s_add_i32 m0, s89, 0x6000
	v_mfma_f32_16x16x32_bf16 v[46:49], v[130:133], v[142:145], v[46:49]
	v_mfma_f32_16x16x32_bf16 v[14:17], v[134:137], v[142:145], v[14:17]
	global_load_lds_dwordx4 v192, s[92:93]
	s_add_u32 s90, s90, 64
	s_addc_u32 s91, s91, 0
	s_add_u32 s92, s92, 64
	s_addc_u32 s93, s93, 0
	v_mfma_f32_16x16x32_bf16 v[102:105], v[122:125], v[138:141], v[102:105]
	v_mfma_f32_16x16x32_bf16 v[70:73], v[126:129], v[138:141], v[70:73]
	v_mfma_f32_16x16x32_bf16 v[38:41], v[130:133], v[138:141], v[38:41]
	v_mfma_f32_16x16x32_bf16 v[6:9], v[134:137], v[138:141], v[6:9]
	s_waitcnt lgkmcnt(0)
	v_mfma_f32_16x16x32_bf16 v[154:157], v[122:125], v[162:165], v[154:157]
	s_add_i32 s28, s31, 0xffff0000
	s_and_b32 s35, s28, 0x18000
	v_add_u32_e32 v187, s35, v200
	v_add_u32_e32 v226, s35, v201
	ds_read_b128 v[150:153], v226
	v_mfma_f32_16x16x32_bf16 v[90:93], v[126:129], v[162:165], v[90:93]
	ds_read_b128 v[146:149], v226 offset:1024
	v_mfma_f32_16x16x32_bf16 v[58:61], v[130:133], v[162:165], v[58:61]
	ds_read_b128 v[142:145], v226 offset:2048
	v_mfma_f32_16x16x32_bf16 v[26:29], v[134:137], v[162:165], v[26:29]
	ds_read_b128 v[138:141], v226 offset:3072
	v_mfma_f32_16x16x32_bf16 v[114:117], v[122:125], v[166:169], v[114:117]
	ds_read_b128 v[174:177], v187
	v_mfma_f32_16x16x32_bf16 v[82:85], v[126:129], v[166:169], v[82:85]
	ds_read_b128 v[170:173], v187 offset:1024
	v_mfma_f32_16x16x32_bf16 v[50:53], v[130:133], v[166:169], v[50:53]
	ds_read_b128 v[162:165], v187 offset:3072
	v_mfma_f32_16x16x32_bf16 v[18:21], v[134:137], v[166:169], v[18:21]
	ds_read_b128 v[166:169], v187 offset:2048
	v_mfma_f32_16x16x32_bf16 v[106:109], v[122:125], v[232:235], v[106:109]
	v_mfma_f32_16x16x32_bf16 v[74:77], v[126:129], v[232:235], v[74:77]
	v_mfma_f32_16x16x32_bf16 v[42:45], v[130:133], v[232:235], v[42:45]
	v_mfma_f32_16x16x32_bf16 v[10:13], v[134:137], v[232:235], v[10:13]
	v_mfma_f32_16x16x32_bf16 v[98:101], v[122:125], v[236:239], v[98:101]
	v_mfma_f32_16x16x32_bf16 v[66:69], v[126:129], v[236:239], v[66:69]
	v_mfma_f32_16x16x32_bf16 v[34:37], v[130:133], v[236:239], v[34:37]
	v_mfma_f32_16x16x32_bf16 v[2:5], v[134:137], v[236:239], v[2:5]
	s_waitcnt vmcnt(4)
	s_waitcnt lgkmcnt(0)
	s_barrier
	v_mfma_f32_16x16x32_bf16 v[158:161], v[174:177], v[150:153], v[158:161]
	v_mfma_f32_16x16x32_bf16 v[94:97], v[170:173], v[150:153], v[94:97]
	v_add_u32_e32 v226, s35, v230
	ds_read_b128 v[232:235], v226
	v_mfma_f32_16x16x32_bf16 v[62:65], v[166:169], v[150:153], v[62:65]
	ds_read_b128 v[236:239], v226 offset:1024
	v_mfma_f32_16x16x32_bf16 v[30:33], v[162:165], v[150:153], v[30:33]
	ds_read_b128 v[182:185], v226 offset:2048
	v_mfma_f32_16x16x32_bf16 v[118:121], v[174:177], v[146:149], v[118:121]
	ds_read_b128 v[178:181], v226 offset:3072
	v_mfma_f32_16x16x32_bf16 v[86:89], v[170:173], v[146:149], v[86:89]
	v_mfma_f32_16x16x32_bf16 v[54:57], v[166:169], v[146:149], v[54:57]
	v_mfma_f32_16x16x32_bf16 v[22:25], v[162:165], v[146:149], v[22:25]
	v_mfma_f32_16x16x32_bf16 v[110:113], v[174:177], v[142:145], v[110:113]
	v_mfma_f32_16x16x32_bf16 v[78:81], v[170:173], v[142:145], v[78:81]
	v_mfma_f32_16x16x32_bf16 v[46:49], v[166:169], v[142:145], v[46:49]
	v_mfma_f32_16x16x32_bf16 v[14:17], v[162:165], v[142:145], v[14:17]
	v_mfma_f32_16x16x32_bf16 v[102:105], v[174:177], v[138:141], v[102:105]
	v_mfma_f32_16x16x32_bf16 v[70:73], v[170:173], v[138:141], v[70:73]
	v_mfma_f32_16x16x32_bf16 v[38:41], v[166:169], v[138:141], v[38:41]
	v_mfma_f32_16x16x32_bf16 v[6:9], v[162:165], v[138:141], v[6:9]
	s_waitcnt lgkmcnt(0)
	v_mfma_f32_16x16x32_bf16 v[154:157], v[174:177], v[232:235], v[154:157]
	s_add_i32 s24, s31, 0xffff8000
	s_and_b32 s24, s24, 0x10000
	v_add_u32_e32 v187, s24, v200
	v_add_u32_e32 v226, s24, v201
	ds_read_b128 v[150:153], v226
	v_mfma_f32_16x16x32_bf16 v[90:93], v[170:173], v[232:235], v[90:93]
	ds_read_b128 v[146:149], v226 offset:1024
	v_mfma_f32_16x16x32_bf16 v[58:61], v[166:169], v[232:235], v[58:61]
	ds_read_b128 v[142:145], v226 offset:2048
	v_mfma_f32_16x16x32_bf16 v[26:29], v[162:165], v[232:235], v[26:29]
	ds_read_b128 v[138:141], v226 offset:3072
	v_mfma_f32_16x16x32_bf16 v[114:117], v[174:177], v[236:239], v[114:117]
	ds_read_b128 v[122:125], v187
	v_mfma_f32_16x16x32_bf16 v[82:85], v[170:173], v[236:239], v[82:85]
	ds_read_b128 v[126:129], v187 offset:1024
	v_mfma_f32_16x16x32_bf16 v[50:53], v[166:169], v[236:239], v[50:53]
	ds_read_b128 v[130:133], v187 offset:2048
	v_mfma_f32_16x16x32_bf16 v[18:21], v[162:165], v[236:239], v[18:21]
	ds_read_b128 v[134:137], v187 offset:3072
	s_add_i32 s19, s19, 2
	s_add_u32 s20, s20, 0x80
	s_addc_u32 s21, s21, 0
	s_add_i32 s31, s31, 0x10000
	v_mfma_f32_16x16x32_bf16 v[106:109], v[174:177], v[182:185], v[106:109]
	v_mfma_f32_16x16x32_bf16 v[74:77], v[170:173], v[182:185], v[74:77]
	v_mfma_f32_16x16x32_bf16 v[42:45], v[166:169], v[182:185], v[42:45]
	v_mfma_f32_16x16x32_bf16 v[10:13], v[162:165], v[182:185], v[10:13]
	v_mfma_f32_16x16x32_bf16 v[98:101], v[174:177], v[178:181], v[98:101]
	v_mfma_f32_16x16x32_bf16 v[66:69], v[170:173], v[178:181], v[66:69]
	v_mfma_f32_16x16x32_bf16 v[34:37], v[166:169], v[178:181], v[34:37]
	v_mfma_f32_16x16x32_bf16 v[2:5], v[162:165], v[178:181], v[2:5]
	s_waitcnt vmcnt(0)
	s_waitcnt lgkmcnt(0)
	s_barrier
	v_mfma_f32_16x16x32_bf16 v[158:161], v[122:125], v[150:153], v[158:161]
	v_mfma_f32_16x16x32_bf16 v[94:97], v[126:129], v[150:153], v[94:97]
	s_add_i32 s28, s31, 0xfffe8000
	s_and_b32 s34, s28, 0x10000
	v_add_u32_e32 v170, s34, v230
	ds_read_b128 v[162:165], v170
	v_mfma_f32_16x16x32_bf16 v[62:65], v[130:133], v[150:153], v[62:65]
	ds_read_b128 v[166:169], v170 offset:1024
	v_mfma_f32_16x16x32_bf16 v[30:33], v[134:137], v[150:153], v[30:33]
	ds_read_b128 v[232:235], v170 offset:2048
	v_mfma_f32_16x16x32_bf16 v[118:121], v[122:125], v[146:149], v[118:121]
	ds_read_b128 v[236:239], v170 offset:3072
	v_mfma_f32_16x16x32_bf16 v[86:89], v[126:129], v[146:149], v[86:89]
	v_mfma_f32_16x16x32_bf16 v[54:57], v[130:133], v[146:149], v[54:57]
	v_mfma_f32_16x16x32_bf16 v[22:25], v[134:137], v[146:149], v[22:25]
	v_mfma_f32_16x16x32_bf16 v[110:113], v[122:125], v[142:145], v[110:113]
	v_mfma_f32_16x16x32_bf16 v[78:81], v[126:129], v[142:145], v[78:81]
	v_mfma_f32_16x16x32_bf16 v[46:49], v[130:133], v[142:145], v[46:49]
	v_mfma_f32_16x16x32_bf16 v[14:17], v[134:137], v[142:145], v[14:17]
	v_mfma_f32_16x16x32_bf16 v[102:105], v[122:125], v[138:141], v[102:105]
	v_mfma_f32_16x16x32_bf16 v[70:73], v[126:129], v[138:141], v[70:73]
	v_mfma_f32_16x16x32_bf16 v[38:41], v[130:133], v[138:141], v[38:41]
	v_mfma_f32_16x16x32_bf16 v[6:9], v[134:137], v[138:141], v[6:9]
	s_waitcnt lgkmcnt(0)
	v_mfma_f32_16x16x32_bf16 v[154:157], v[122:125], v[162:165], v[154:157]
	s_add_i32 s28, s31, 0xffff0000
	s_and_b32 s35, s28, 0x18000
	v_add_u32_e32 v187, s35, v200
	v_add_u32_e32 v226, s35, v201
	ds_read_b128 v[150:153], v226
	v_mfma_f32_16x16x32_bf16 v[90:93], v[126:129], v[162:165], v[90:93]
	ds_read_b128 v[146:149], v226 offset:1024
	v_mfma_f32_16x16x32_bf16 v[58:61], v[130:133], v[162:165], v[58:61]
	ds_read_b128 v[142:145], v226 offset:2048
	v_mfma_f32_16x16x32_bf16 v[26:29], v[134:137], v[162:165], v[26:29]
	ds_read_b128 v[138:141], v226 offset:3072
	v_mfma_f32_16x16x32_bf16 v[114:117], v[122:125], v[166:169], v[114:117]
	ds_read_b128 v[174:177], v187
	v_mfma_f32_16x16x32_bf16 v[82:85], v[126:129], v[166:169], v[82:85]
	ds_read_b128 v[170:173], v187 offset:1024
	v_mfma_f32_16x16x32_bf16 v[50:53], v[130:133], v[166:169], v[50:53]
	ds_read_b128 v[162:165], v187 offset:3072
	v_mfma_f32_16x16x32_bf16 v[18:21], v[134:137], v[166:169], v[18:21]
	ds_read_b128 v[166:169], v187 offset:2048
	v_mfma_f32_16x16x32_bf16 v[106:109], v[122:125], v[232:235], v[106:109]
	v_mfma_f32_16x16x32_bf16 v[74:77], v[126:129], v[232:235], v[74:77]
	v_mfma_f32_16x16x32_bf16 v[42:45], v[130:133], v[232:235], v[42:45]
	v_mfma_f32_16x16x32_bf16 v[10:13], v[134:137], v[232:235], v[10:13]
	v_mfma_f32_16x16x32_bf16 v[98:101], v[122:125], v[236:239], v[98:101]
	v_mfma_f32_16x16x32_bf16 v[66:69], v[126:129], v[236:239], v[66:69]
	v_mfma_f32_16x16x32_bf16 v[34:37], v[130:133], v[236:239], v[34:37]
	v_mfma_f32_16x16x32_bf16 v[2:5], v[134:137], v[236:239], v[2:5]
	s_waitcnt vmcnt(0)
	s_waitcnt lgkmcnt(0)
	s_barrier
	v_mfma_f32_16x16x32_bf16 v[158:161], v[174:177], v[150:153], v[158:161]
	v_mfma_f32_16x16x32_bf16 v[94:97], v[170:173], v[150:153], v[94:97]
	v_add_u32_e32 v226, s35, v230
	ds_read_b128 v[232:235], v226
	v_mfma_f32_16x16x32_bf16 v[62:65], v[166:169], v[150:153], v[62:65]
	ds_read_b128 v[236:239], v226 offset:1024
	v_mfma_f32_16x16x32_bf16 v[30:33], v[162:165], v[150:153], v[30:33]
	ds_read_b128 v[182:185], v226 offset:2048
	v_mfma_f32_16x16x32_bf16 v[118:121], v[174:177], v[146:149], v[118:121]
	ds_read_b128 v[178:181], v226 offset:3072
	v_mfma_f32_16x16x32_bf16 v[86:89], v[170:173], v[146:149], v[86:89]
	v_mfma_f32_16x16x32_bf16 v[54:57], v[166:169], v[146:149], v[54:57]
	v_mfma_f32_16x16x32_bf16 v[22:25], v[162:165], v[146:149], v[22:25]
	v_mfma_f32_16x16x32_bf16 v[110:113], v[174:177], v[142:145], v[110:113]
	v_mfma_f32_16x16x32_bf16 v[78:81], v[170:173], v[142:145], v[78:81]
	v_mfma_f32_16x16x32_bf16 v[46:49], v[166:169], v[142:145], v[46:49]
	v_mfma_f32_16x16x32_bf16 v[14:17], v[162:165], v[142:145], v[14:17]
	v_mfma_f32_16x16x32_bf16 v[102:105], v[174:177], v[138:141], v[102:105]
	v_mfma_f32_16x16x32_bf16 v[70:73], v[170:173], v[138:141], v[70:73]
	v_mfma_f32_16x16x32_bf16 v[38:41], v[166:169], v[138:141], v[38:41]
	v_mfma_f32_16x16x32_bf16 v[6:9], v[162:165], v[138:141], v[6:9]
	s_waitcnt lgkmcnt(0)
	v_mfma_f32_16x16x32_bf16 v[154:157], v[174:177], v[232:235], v[154:157]
	v_mfma_f32_16x16x32_bf16 v[90:93], v[170:173], v[232:235], v[90:93]
	v_mfma_f32_16x16x32_bf16 v[58:61], v[166:169], v[232:235], v[58:61]
	v_mfma_f32_16x16x32_bf16 v[26:29], v[162:165], v[232:235], v[26:29]
	v_mfma_f32_16x16x32_bf16 v[114:117], v[174:177], v[236:239], v[114:117]
	v_mfma_f32_16x16x32_bf16 v[82:85], v[170:173], v[236:239], v[82:85]
	v_mfma_f32_16x16x32_bf16 v[50:53], v[166:169], v[236:239], v[50:53]
	v_mfma_f32_16x16x32_bf16 v[18:21], v[162:165], v[236:239], v[18:21]
	s_add_i32 s19, s19, 2
	s_add_u32 s20, s20, 0x80
	s_addc_u32 s21, s21, 0
	s_add_i32 s31, s31, 0x10000
	v_mfma_f32_16x16x32_bf16 v[106:109], v[174:177], v[182:185], v[106:109]
	v_mfma_f32_16x16x32_bf16 v[74:77], v[170:173], v[182:185], v[74:77]
	v_mfma_f32_16x16x32_bf16 v[42:45], v[166:169], v[182:185], v[42:45]
	v_mfma_f32_16x16x32_bf16 v[10:13], v[162:165], v[182:185], v[10:13]
	v_mfma_f32_16x16x32_bf16 v[98:101], v[174:177], v[178:181], v[98:101]
	v_mfma_f32_16x16x32_bf16 v[66:69], v[170:173], v[178:181], v[66:69]
	v_mfma_f32_16x16x32_bf16 v[34:37], v[166:169], v[178:181], v[34:37]
	v_mfma_f32_16x16x32_bf16 v[2:5], v[162:165], v[178:181], v[2:5]
	s_branch .LBB0_197
.Lgr_G4x_entry:
	s_waitcnt vmcnt(4)
	s_waitcnt lgkmcnt(0)
	s_barrier
	v_mfma_f32_16x16x32_bf16 v[158:161], v[122:125], v[150:153], v[158:161]
	v_mfma_f32_16x16x32_bf16 v[94:97], v[126:129], v[150:153], v[94:97]
	s_add_i32 s28, s31, 0xfffe8000
	s_and_b32 s34, s28, 0x10000
	v_add_u32_e32 v170, s34, v230
	ds_read_b128 v[162:165], v170
	v_mfma_f32_16x16x32_bf16 v[62:65], v[130:133], v[150:153], v[62:65]
	ds_read_b128 v[166:169], v170 offset:1024
	v_mfma_f32_16x16x32_bf16 v[30:33], v[134:137], v[150:153], v[30:33]
	ds_read_b128 v[232:235], v170 offset:2048
	v_mfma_f32_16x16x32_bf16 v[118:121], v[122:125], v[146:149], v[118:121]
	ds_read_b128 v[236:239], v170 offset:3072
	s_and_b32 s89, s31, 0x18000
	s_add_i32 s89, s89, s88
	s_mov_b32 m0, s89
	v_mfma_f32_16x16x32_bf16 v[86:89], v[126:129], v[146:149], v[86:89]
	global_load_lds_dwordx4 v186, s[90:91]
	s_add_i32 m0, s89, 0x2000
	v_mfma_f32_16x16x32_bf16 v[54:57], v[130:133], v[146:149], v[54:57]
	v_mfma_f32_16x16x32_bf16 v[22:25], v[134:137], v[146:149], v[22:25]
	global_load_lds_dwordx4 v188, s[90:91]
	s_add_i32 m0, s89, 0x4000
	v_mfma_f32_16x16x32_bf16 v[110:113], v[122:125], v[142:145], v[110:113]
	v_mfma_f32_16x16x32_bf16 v[78:81], v[126:129], v[142:145], v[78:81]
	global_load_lds_dwordx4 v190, s[92:93]
	s_add_i32 m0, s89, 0x6000
	v_mfma_f32_16x16x32_bf16 v[46:49], v[130:133], v[142:145], v[46:49]
	v_mfma_f32_16x16x32_bf16 v[14:17], v[134:137], v[142:145], v[14:17]
	global_load_lds_dwordx4 v192, s[92:93]
	s_add_u32 s90, s90, 64
	s_addc_u32 s91, s91, 0
	s_add_u32 s92, s92, 64
	s_addc_u32 s93, s93, 0
	v_mfma_f32_16x16x32_bf16 v[102:105], v[122:125], v[138:141], v[102:105]
	v_mfma_f32_16x16x32_bf16 v[70:73], v[126:129], v[138:141], v[70:73]
	v_mfma_f32_16x16x32_bf16 v[38:41], v[130:133], v[138:141], v[38:41]
	v_mfma_f32_16x16x32_bf16 v[6:9], v[134:137], v[138:141], v[6:9]
	s_waitcnt vmcnt(4)
	s_waitcnt lgkmcnt(0)
	s_barrier
	v_mfma_f32_16x16x32_bf16 v[154:157], v[122:125], v[162:165], v[154:157]
	s_add_i32 s28, s31, 0xffff0000
	s_and_b32 s35, s28, 0x18000
	v_add_u32_e32 v187, s35, v200
	v_add_u32_e32 v226, s35, v201
	ds_read_b128 v[150:153], v226
	v_mfma_f32_16x16x32_bf16 v[90:93], v[126:129], v[162:165], v[90:93]
	ds_read_b128 v[146:149], v226 offset:1024
	v_mfma_f32_16x16x32_bf16 v[58:61], v[130:133], v[162:165], v[58:61]
	ds_read_b128 v[142:145], v226 offset:2048
	v_mfma_f32_16x16x32_bf16 v[26:29], v[134:137], v[162:165], v[26:29]
	ds_read_b128 v[138:141], v226 offset:3072
	v_mfma_f32_16x16x32_bf16 v[114:117], v[122:125], v[166:169], v[114:117]
	ds_read_b128 v[174:177], v187
	v_mfma_f32_16x16x32_bf16 v[82:85], v[126:129], v[166:169], v[82:85]
	ds_read_b128 v[170:173], v187 offset:1024
	v_mfma_f32_16x16x32_bf16 v[50:53], v[130:133], v[166:169], v[50:53]
	ds_read_b128 v[162:165], v187 offset:3072
	v_mfma_f32_16x16x32_bf16 v[18:21], v[134:137], v[166:169], v[18:21]
	ds_read_b128 v[166:169], v187 offset:2048
	v_mfma_f32_16x16x32_bf16 v[106:109], v[122:125], v[232:235], v[106:109]
	v_mfma_f32_16x16x32_bf16 v[74:77], v[126:129], v[232:235], v[74:77]
	v_mfma_f32_16x16x32_bf16 v[42:45], v[130:133], v[232:235], v[42:45]
	v_mfma_f32_16x16x32_bf16 v[10:13], v[134:137], v[232:235], v[10:13]
	v_mfma_f32_16x16x32_bf16 v[98:101], v[122:125], v[236:239], v[98:101]
	v_mfma_f32_16x16x32_bf16 v[66:69], v[126:129], v[236:239], v[66:69]
	v_mfma_f32_16x16x32_bf16 v[34:37], v[130:133], v[236:239], v[34:37]
	v_mfma_f32_16x16x32_bf16 v[2:5], v[134:137], v[236:239], v[2:5]
	s_waitcnt lgkmcnt(0)
	v_mfma_f32_16x16x32_bf16 v[158:161], v[174:177], v[150:153], v[158:161]
	v_mfma_f32_16x16x32_bf16 v[94:97], v[170:173], v[150:153], v[94:97]
	v_add_u32_e32 v226, s35, v230
	ds_read_b128 v[232:235], v226
	v_mfma_f32_16x16x32_bf16 v[62:65], v[166:169], v[150:153], v[62:65]
	ds_read_b128 v[236:239], v226 offset:1024
	v_mfma_f32_16x16x32_bf16 v[30:33], v[162:165], v[150:153], v[30:33]
	ds_read_b128 v[182:185], v226 offset:2048
	v_mfma_f32_16x16x32_bf16 v[118:121], v[174:177], v[146:149], v[118:121]
	ds_read_b128 v[178:181], v226 offset:3072
	s_add_i32 s89, s34, s88
	s_mov_b32 m0, s89
	v_mfma_f32_16x16x32_bf16 v[86:89], v[170:173], v[146:149], v[86:89]
	global_load_lds_dwordx4 v186, s[90:91]
	s_add_i32 m0, s89, 0x2000
	v_mfma_f32_16x16x32_bf16 v[54:57], v[166:169], v[146:149], v[54:57]
	v_mfma_f32_16x16x32_bf16 v[22:25], v[162:165], v[146:149], v[22:25]
	global_load_lds_dwordx4 v188, s[90:91]
	s_add_i32 m0, s89, 0x4000
	v_mfma_f32_16x16x32_bf16 v[110:113], v[174:177], v[142:145], v[110:113]
	v_mfma_f32_16x16x32_bf16 v[78:81], v[170:173], v[142:145], v[78:81]
	global_load_lds_dwordx4 v190, s[92:93]
	s_add_i32 m0, s89, 0x6000
	v_mfma_f32_16x16x32_bf16 v[46:49], v[166:169], v[142:145], v[46:49]
	v_mfma_f32_16x16x32_bf16 v[14:17], v[162:165], v[142:145], v[14:17]
	global_load_lds_dwordx4 v192, s[92:93]
	s_add_u32 s90, s90, 64
	s_addc_u32 s91, s91, 0
	s_add_u32 s92, s92, 64
	s_addc_u32 s93, s93, 0
	v_mfma_f32_16x16x32_bf16 v[102:105], v[174:177], v[138:141], v[102:105]
	v_mfma_f32_16x16x32_bf16 v[70:73], v[170:173], v[138:141], v[70:73]
	v_mfma_f32_16x16x32_bf16 v[38:41], v[166:169], v[138:141], v[38:41]
	v_mfma_f32_16x16x32_bf16 v[6:9], v[162:165], v[138:141], v[6:9]
.Lgr_G4x_top:
	s_waitcnt vmcnt(4)
	s_waitcnt lgkmcnt(0)
	s_barrier
	v_mfma_f32_16x16x32_bf16 v[154:157], v[174:177], v[232:235], v[154:157]
	s_add_i32 s24, s31, 0xffff8000
	s_and_b32 s24, s24, 0x10000
	v_add_u32_e32 v187, s24, v200
	v_add_u32_e32 v226, s24, v201
	ds_read_b128 v[150:153], v226
	v_mfma_f32_16x16x32_bf16 v[90:93], v[170:173], v[232:235], v[90:93]
	ds_read_b128 v[146:149], v226 offset:1024
	v_mfma_f32_16x16x32_bf16 v[58:61], v[166:169], v[232:235], v[58:61]
	ds_read_b128 v[142:145], v226 offset:2048
	v_mfma_f32_16x16x32_bf16 v[26:29], v[162:165], v[232:235], v[26:29]
	ds_read_b128 v[138:141], v226 offset:3072
	v_mfma_f32_16x16x32_bf16 v[114:117], v[174:177], v[236:239], v[114:117]
	ds_read_b128 v[122:125], v187
	v_mfma_f32_16x16x32_bf16 v[82:85], v[170:173], v[236:239], v[82:85]
	ds_read_b128 v[126:129], v187 offset:1024
	v_mfma_f32_16x16x32_bf16 v[50:53], v[166:169], v[236:239], v[50:53]
	ds_read_b128 v[130:133], v187 offset:2048
	v_mfma_f32_16x16x32_bf16 v[18:21], v[162:165], v[236:239], v[18:21]
	ds_read_b128 v[134:137], v187 offset:3072
	s_add_i32 s19, s19, 2
	s_add_u32 s20, s20, 0x80
	s_addc_u32 s21, s21, 0
	s_add_i32 s31, s31, 0x10000
	v_mfma_f32_16x16x32_bf16 v[106:109], v[174:177], v[182:185], v[106:109]
	v_mfma_f32_16x16x32_bf16 v[74:77], v[170:173], v[182:185], v[74:77]
	v_mfma_f32_16x16x32_bf16 v[42:45], v[166:169], v[182:185], v[42:45]
	v_mfma_f32_16x16x32_bf16 v[10:13], v[162:165], v[182:185], v[10:13]
	v_mfma_f32_16x16x32_bf16 v[98:101], v[174:177], v[178:181], v[98:101]
	v_mfma_f32_16x16x32_bf16 v[66:69], v[170:173], v[178:181], v[66:69]
	v_mfma_f32_16x16x32_bf16 v[34:37], v[166:169], v[178:181], v[34:37]
	v_mfma_f32_16x16x32_bf16 v[2:5], v[162:165], v[178:181], v[2:5]
	s_cmp_lt_u32 s19, 28
	s_cbranch_scc0 .Lgr_G4x_tail
	s_waitcnt lgkmcnt(0)
	v_mfma_f32_16x16x32_bf16 v[158:161], v[122:125], v[150:153], v[158:161]
	v_mfma_f32_16x16x32_bf16 v[94:97], v[126:129], v[150:153], v[94:97]
	s_add_i32 s28, s31, 0xfffe8000
	s_and_b32 s34, s28, 0x10000
	v_add_u32_e32 v170, s34, v230
	ds_read_b128 v[162:165], v170
	v_mfma_f32_16x16x32_bf16 v[62:65], v[130:133], v[150:153], v[62:65]
	ds_read_b128 v[166:169], v170 offset:1024
	v_mfma_f32_16x16x32_bf16 v[30:33], v[134:137], v[150:153], v[30:33]
	ds_read_b128 v[232:235], v170 offset:2048
	v_mfma_f32_16x16x32_bf16 v[118:121], v[122:125], v[146:149], v[118:121]
	ds_read_b128 v[236:239], v170 offset:3072
	s_and_b32 s89, s31, 0x18000
	s_add_i32 s89, s89, s88
	s_mov_b32 m0, s89
	v_mfma_f32_16x16x32_bf16 v[86:89], v[126:129], v[146:149], v[86:89]
	global_load_lds_dwordx4 v186, s[90:91]
	s_add_i32 m0, s89, 0x2000
	v_mfma_f32_16x16x32_bf16 v[54:57], v[130:133], v[146:149], v[54:57]
	v_mfma_f32_16x16x32_bf16 v[22:25], v[134:137], v[146:149], v[22:25]
	global_load_lds_dwordx4 v188, s[90:91]
	s_add_i32 m0, s89, 0x4000
	v_mfma_f32_16x16x32_bf16 v[110:113], v[122:125], v[142:145], v[110:113]
	v_mfma_f32_16x16x32_bf16 v[78:81], v[126:129], v[142:145], v[78:81]
	global_load_lds_dwordx4 v190, s[92:93]
	s_add_i32 m0, s89, 0x6000
	v_mfma_f32_16x16x32_bf16 v[46:49], v[130:133], v[142:145], v[46:49]
	v_mfma_f32_16x16x32_bf16 v[14:17], v[134:137], v[142:145], v[14:17]
	global_load_lds_dwordx4 v192, s[92:93]
	s_add_u32 s90, s90, 64
	s_addc_u32 s91, s91, 0
	s_add_u32 s92, s92, 64
	s_addc_u32 s93, s93, 0
	v_mfma_f32_16x16x32_bf16 v[102:105], v[122:125], v[138:141], v[102:105]
	v_mfma_f32_16x16x32_bf16 v[70:73], v[126:129], v[138:141], v[70:73]
	v_mfma_f32_16x16x32_bf16 v[38:41], v[130:133], v[138:141], v[38:41]
	v_mfma_f32_16x16x32_bf16 v[6:9], v[134:137], v[138:141], v[6:9]
	s_waitcnt vmcnt(4)
	s_waitcnt lgkmcnt(0)
	s_barrier
	v_mfma_f32_16x16x32_bf16 v[154:157], v[122:125], v[162:165], v[154:157]
	s_add_i32 s28, s31, 0xffff0000
	s_and_b32 s35, s28, 0x18000
	v_add_u32_e32 v187, s35, v200
	v_add_u32_e32 v226, s35, v201
	ds_read_b128 v[150:153], v226
	v_mfma_f32_16x16x32_bf16 v[90:93], v[126:129], v[162:165], v[90:93]
	ds_read_b128 v[146:149], v226 offset:1024
	v_mfma_f32_16x16x32_bf16 v[58:61], v[130:133], v[162:165], v[58:61]
	ds_read_b128 v[142:145], v226 offset:2048
	v_mfma_f32_16x16x32_bf16 v[26:29], v[134:137], v[162:165], v[26:29]
	ds_read_b128 v[138:141], v226 offset:3072
	v_mfma_f32_16x16x32_bf16 v[114:117], v[122:125], v[166:169], v[114:117]
	ds_read_b128 v[174:177], v187
	v_mfma_f32_16x16x32_bf16 v[82:85], v[126:129], v[166:169], v[82:85]
	ds_read_b128 v[170:173], v187 offset:1024
	v_mfma_f32_16x16x32_bf16 v[50:53], v[130:133], v[166:169], v[50:53]
	ds_read_b128 v[162:165], v187 offset:3072
	v_mfma_f32_16x16x32_bf16 v[18:21], v[134:137], v[166:169], v[18:21]
	ds_read_b128 v[166:169], v187 offset:2048
	v_mfma_f32_16x16x32_bf16 v[106:109], v[122:125], v[232:235], v[106:109]
	v_mfma_f32_16x16x32_bf16 v[74:77], v[126:129], v[232:235], v[74:77]
	v_mfma_f32_16x16x32_bf16 v[42:45], v[130:133], v[232:235], v[42:45]
	v_mfma_f32_16x16x32_bf16 v[10:13], v[134:137], v[232:235], v[10:13]
	v_mfma_f32_16x16x32_bf16 v[98:101], v[122:125], v[236:239], v[98:101]
	v_mfma_f32_16x16x32_bf16 v[66:69], v[126:129], v[236:239], v[66:69]
	v_mfma_f32_16x16x32_bf16 v[34:37], v[130:133], v[236:239], v[34:37]
	v_mfma_f32_16x16x32_bf16 v[2:5], v[134:137], v[236:239], v[2:5]
	s_waitcnt lgkmcnt(0)
	v_mfma_f32_16x16x32_bf16 v[158:161], v[174:177], v[150:153], v[158:161]
	v_mfma_f32_16x16x32_bf16 v[94:97], v[170:173], v[150:153], v[94:97]
	v_add_u32_e32 v226, s35, v230
	ds_read_b128 v[232:235], v226
	v_mfma_f32_16x16x32_bf16 v[62:65], v[166:169], v[150:153], v[62:65]
	ds_read_b128 v[236:239], v226 offset:1024
	v_mfma_f32_16x16x32_bf16 v[30:33], v[162:165], v[150:153], v[30:33]
	ds_read_b128 v[182:185], v226 offset:2048
	v_mfma_f32_16x16x32_bf16 v[118:121], v[174:177], v[146:149], v[118:121]
	ds_read_b128 v[178:181], v226 offset:3072
	s_add_i32 s89, s34, s88
	s_mov_b32 m0, s89
	v_mfma_f32_16x16x32_bf16 v[86:89], v[170:173], v[146:149], v[86:89]
	global_load_lds_dwordx4 v186, s[90:91]
	s_add_i32 m0, s89, 0x2000
	v_mfma_f32_16x16x32_bf16 v[54:57], v[166:169], v[146:149], v[54:57]
	v_mfma_f32_16x16x32_bf16 v[22:25], v[162:165], v[146:149], v[22:25]
	global_load_lds_dwordx4 v188, s[90:91]
	s_add_i32 m0, s89, 0x4000
	v_mfma_f32_16x16x32_bf16 v[110:113], v[174:177], v[142:145], v[110:113]
	v_mfma_f32_16x16x32_bf16 v[78:81], v[170:173], v[142:145], v[78:81]
	global_load_lds_dwordx4 v190, s[92:93]
	s_add_i32 m0, s89, 0x6000
	v_mfma_f32_16x16x32_bf16 v[46:49], v[166:169], v[142:145], v[46:49]
	v_mfma_f32_16x16x32_bf16 v[14:17], v[162:165], v[142:145], v[14:17]
	global_load_lds_dwordx4 v192, s[92:93]
	s_add_u32 s90, s90, 64
	s_addc_u32 s91, s91, 0
	s_add_u32 s92, s92, 64
	s_addc_u32 s93, s93, 0
	v_mfma_f32_16x16x32_bf16 v[102:105], v[174:177], v[138:141], v[102:105]
	v_mfma_f32_16x16x32_bf16 v[70:73], v[170:173], v[138:141], v[70:73]
	v_mfma_f32_16x16x32_bf16 v[38:41], v[166:169], v[138:141], v[38:41]
	v_mfma_f32_16x16x32_bf16 v[6:9], v[162:165], v[138:141], v[6:9]
	s_branch .Lgr_G4x_top
.Lgr_G4x_tail:
	s_waitcnt lgkmcnt(0)
	v_mfma_f32_16x16x32_bf16 v[158:161], v[122:125], v[150:153], v[158:161]
	v_mfma_f32_16x16x32_bf16 v[94:97], v[126:129], v[150:153], v[94:97]
	s_add_i32 s28, s31, 0xfffe8000
	s_and_b32 s34, s28, 0x10000
	v_add_u32_e32 v170, s34, v230
	ds_read_b128 v[162:165], v170
	v_mfma_f32_16x16x32_bf16 v[62:65], v[130:133], v[150:153], v[62:65]
	ds_read_b128 v[166:169], v170 offset:1024
	v_mfma_f32_16x16x32_bf16 v[30:33], v[134:137], v[150:153], v[30:33]
	ds_read_b128 v[232:235], v170 offset:2048
	v_mfma_f32_16x16x32_bf16 v[118:121], v[122:125], v[146:149], v[118:121]
	ds_read_b128 v[236:239], v170 offset:3072
	s_and_b32 s89, s31, 0x18000
	s_add_i32 s89, s89, s88
	s_mov_b32 m0, s89
	v_mfma_f32_16x16x32_bf16 v[86:89], v[126:129], v[146:149], v[86:89]
	global_load_lds_dwordx4 v186, s[90:91]
	s_add_i32 m0, s89, 0x2000
	v_mfma_f32_16x16x32_bf16 v[54:57], v[130:133], v[146:149], v[54:57]
	v_mfma_f32_16x16x32_bf16 v[22:25], v[134:137], v[146:149], v[22:25]
	global_load_lds_dwordx4 v188, s[90:91]
	s_add_i32 m0, s89, 0x4000
	v_mfma_f32_16x16x32_bf16 v[110:113], v[122:125], v[142:145], v[110:113]
	v_mfma_f32_16x16x32_bf16 v[78:81], v[126:129], v[142:145], v[78:81]
	global_load_lds_dwordx4 v190, s[92:93]
	s_add_i32 m0, s89, 0x6000
	v_mfma_f32_16x16x32_bf16 v[46:49], v[130:133], v[142:145], v[46:49]
	v_mfma_f32_16x16x32_bf16 v[14:17], v[134:137], v[142:145], v[14:17]
	global_load_lds_dwordx4 v192, s[92:93]
	s_add_u32 s90, s90, 64
	s_addc_u32 s91, s91, 0
	s_add_u32 s92, s92, 64
	s_addc_u32 s93, s93, 0
	v_mfma_f32_16x16x32_bf16 v[102:105], v[122:125], v[138:141], v[102:105]
	v_mfma_f32_16x16x32_bf16 v[70:73], v[126:129], v[138:141], v[70:73]
	v_mfma_f32_16x16x32_bf16 v[38:41], v[130:133], v[138:141], v[38:41]
	v_mfma_f32_16x16x32_bf16 v[6:9], v[134:137], v[138:141], v[6:9]
	s_waitcnt vmcnt(4)
	s_waitcnt lgkmcnt(0)
	s_barrier
	v_mfma_f32_16x16x32_bf16 v[154:157], v[122:125], v[162:165], v[154:157]
	s_add_i32 s28, s31, 0xffff0000
	s_and_b32 s35, s28, 0x18000
	v_add_u32_e32 v187, s35, v200
	v_add_u32_e32 v226, s35, v201
	ds_read_b128 v[150:153], v226
	v_mfma_f32_16x16x32_bf16 v[90:93], v[126:129], v[162:165], v[90:93]
	ds_read_b128 v[146:149], v226 offset:1024
	v_mfma_f32_16x16x32_bf16 v[58:61], v[130:133], v[162:165], v[58:61]
	ds_read_b128 v[142:145], v226 offset:2048
	v_mfma_f32_16x16x32_bf16 v[26:29], v[134:137], v[162:165], v[26:29]
	ds_read_b128 v[138:141], v226 offset:3072
	v_mfma_f32_16x16x32_bf16 v[114:117], v[122:125], v[166:169], v[114:117]
	ds_read_b128 v[174:177], v187
	v_mfma_f32_16x16x32_bf16 v[82:85], v[126:129], v[166:169], v[82:85]
	ds_read_b128 v[170:173], v187 offset:1024
	v_mfma_f32_16x16x32_bf16 v[50:53], v[130:133], v[166:169], v[50:53]
	ds_read_b128 v[162:165], v187 offset:3072
	v_mfma_f32_16x16x32_bf16 v[18:21], v[134:137], v[166:169], v[18:21]
	ds_read_b128 v[166:169], v187 offset:2048
	v_mfma_f32_16x16x32_bf16 v[106:109], v[122:125], v[232:235], v[106:109]
	v_mfma_f32_16x16x32_bf16 v[74:77], v[126:129], v[232:235], v[74:77]
	v_mfma_f32_16x16x32_bf16 v[42:45], v[130:133], v[232:235], v[42:45]
	v_mfma_f32_16x16x32_bf16 v[10:13], v[134:137], v[232:235], v[10:13]
	v_mfma_f32_16x16x32_bf16 v[98:101], v[122:125], v[236:239], v[98:101]
	v_mfma_f32_16x16x32_bf16 v[66:69], v[126:129], v[236:239], v[66:69]
	v_mfma_f32_16x16x32_bf16 v[34:37], v[130:133], v[236:239], v[34:37]
	v_mfma_f32_16x16x32_bf16 v[2:5], v[134:137], v[236:239], v[2:5]
	s_waitcnt lgkmcnt(0)
	v_mfma_f32_16x16x32_bf16 v[158:161], v[174:177], v[150:153], v[158:161]
	v_mfma_f32_16x16x32_bf16 v[94:97], v[170:173], v[150:153], v[94:97]
	v_add_u32_e32 v226, s35, v230
	ds_read_b128 v[232:235], v226
	v_mfma_f32_16x16x32_bf16 v[62:65], v[166:169], v[150:153], v[62:65]
	ds_read_b128 v[236:239], v226 offset:1024
	v_mfma_f32_16x16x32_bf16 v[30:33], v[162:165], v[150:153], v[30:33]
	ds_read_b128 v[182:185], v226 offset:2048
	v_mfma_f32_16x16x32_bf16 v[118:121], v[174:177], v[146:149], v[118:121]
	ds_read_b128 v[178:181], v226 offset:3072
	v_mfma_f32_16x16x32_bf16 v[86:89], v[170:173], v[146:149], v[86:89]
	v_mfma_f32_16x16x32_bf16 v[54:57], v[166:169], v[146:149], v[54:57]
	v_mfma_f32_16x16x32_bf16 v[22:25], v[162:165], v[146:149], v[22:25]
	v_mfma_f32_16x16x32_bf16 v[110:113], v[174:177], v[142:145], v[110:113]
	v_mfma_f32_16x16x32_bf16 v[78:81], v[170:173], v[142:145], v[78:81]
	v_mfma_f32_16x16x32_bf16 v[46:49], v[166:169], v[142:145], v[46:49]
	v_mfma_f32_16x16x32_bf16 v[14:17], v[162:165], v[142:145], v[14:17]
	v_mfma_f32_16x16x32_bf16 v[102:105], v[174:177], v[138:141], v[102:105]
	v_mfma_f32_16x16x32_bf16 v[70:73], v[170:173], v[138:141], v[70:73]
	v_mfma_f32_16x16x32_bf16 v[38:41], v[166:169], v[138:141], v[38:41]
	v_mfma_f32_16x16x32_bf16 v[6:9], v[162:165], v[138:141], v[6:9]
	s_waitcnt vmcnt(0)
	s_waitcnt lgkmcnt(0)
	s_barrier
	v_mfma_f32_16x16x32_bf16 v[154:157], v[174:177], v[232:235], v[154:157]
	s_add_i32 s24, s31, 0xffff8000
	s_and_b32 s24, s24, 0x10000
	v_add_u32_e32 v187, s24, v200
	v_add_u32_e32 v226, s24, v201
	ds_read_b128 v[150:153], v226
	v_mfma_f32_16x16x32_bf16 v[90:93], v[170:173], v[232:235], v[90:93]
	ds_read_b128 v[146:149], v226 offset:1024
	v_mfma_f32_16x16x32_bf16 v[58:61], v[166:169], v[232:235], v[58:61]
	ds_read_b128 v[142:145], v226 offset:2048
	v_mfma_f32_16x16x32_bf16 v[26:29], v[162:165], v[232:235], v[26:29]
	ds_read_b128 v[138:141], v226 offset:3072
	v_mfma_f32_16x16x32_bf16 v[114:117], v[174:177], v[236:239], v[114:117]
	ds_read_b128 v[122:125], v187
	v_mfma_f32_16x16x32_bf16 v[82:85], v[170:173], v[236:239], v[82:85]
	ds_read_b128 v[126:129], v187 offset:1024
	v_mfma_f32_16x16x32_bf16 v[50:53], v[166:169], v[236:239], v[50:53]
	ds_read_b128 v[130:133], v187 offset:2048
	v_mfma_f32_16x16x32_bf16 v[18:21], v[162:165], v[236:239], v[18:21]
	ds_read_b128 v[134:137], v187 offset:3072
	s_add_i32 s19, s19, 2
	s_add_u32 s20, s20, 0x80
	s_addc_u32 s21, s21, 0
	s_add_i32 s31, s31, 0x10000
	v_mfma_f32_16x16x32_bf16 v[106:109], v[174:177], v[182:185], v[106:109]
	v_mfma_f32_16x16x32_bf16 v[74:77], v[170:173], v[182:185], v[74:77]
	v_mfma_f32_16x16x32_bf16 v[42:45], v[166:169], v[182:185], v[42:45]
	v_mfma_f32_16x16x32_bf16 v[10:13], v[162:165], v[182:185], v[10:13]
	v_mfma_f32_16x16x32_bf16 v[98:101], v[174:177], v[178:181], v[98:101]
	v_mfma_f32_16x16x32_bf16 v[66:69], v[170:173], v[178:181], v[66:69]
	v_mfma_f32_16x16x32_bf16 v[34:37], v[166:169], v[178:181], v[34:37]
	v_mfma_f32_16x16x32_bf16 v[2:5], v[162:165], v[178:181], v[2:5]
	s_waitcnt lgkmcnt(0)
	v_mfma_f32_16x16x32_bf16 v[158:161], v[122:125], v[150:153], v[158:161]
	v_mfma_f32_16x16x32_bf16 v[94:97], v[126:129], v[150:153], v[94:97]
	s_add_i32 s28, s31, 0xfffe8000
	s_and_b32 s34, s28, 0x10000
	v_add_u32_e32 v170, s34, v230
	ds_read_b128 v[162:165], v170
	v_mfma_f32_16x16x32_bf16 v[62:65], v[130:133], v[150:153], v[62:65]
	ds_read_b128 v[166:169], v170 offset:1024
	v_mfma_f32_16x16x32_bf16 v[30:33], v[134:137], v[150:153], v[30:33]
	ds_read_b128 v[232:235], v170 offset:2048
	v_mfma_f32_16x16x32_bf16 v[118:121], v[122:125], v[146:149], v[118:121]
	ds_read_b128 v[236:239], v170 offset:3072
	v_mfma_f32_16x16x32_bf16 v[86:89], v[126:129], v[146:149], v[86:89]
	v_mfma_f32_16x16x32_bf16 v[54:57], v[130:133], v[146:149], v[54:57]
	v_mfma_f32_16x16x32_bf16 v[22:25], v[134:137], v[146:149], v[22:25]
	v_mfma_f32_16x16x32_bf16 v[110:113], v[122:125], v[142:145], v[110:113]
	v_mfma_f32_16x16x32_bf16 v[78:81], v[126:129], v[142:145], v[78:81]
	v_mfma_f32_16x16x32_bf16 v[46:49], v[130:133], v[142:145], v[46:49]
	v_mfma_f32_16x16x32_bf16 v[14:17], v[134:137], v[142:145], v[14:17]
	v_mfma_f32_16x16x32_bf16 v[102:105], v[122:125], v[138:141], v[102:105]
	v_mfma_f32_16x16x32_bf16 v[70:73], v[126:129], v[138:141], v[70:73]
	v_mfma_f32_16x16x32_bf16 v[38:41], v[130:133], v[138:141], v[38:41]
	v_mfma_f32_16x16x32_bf16 v[6:9], v[134:137], v[138:141], v[6:9]
	s_waitcnt vmcnt(0)
	s_waitcnt lgkmcnt(0)
	s_barrier
	v_mfma_f32_16x16x32_bf16 v[154:157], v[122:125], v[162:165], v[154:157]
	s_add_i32 s28, s31, 0xffff0000
	s_and_b32 s35, s28, 0x18000
	v_add_u32_e32 v187, s35, v200
	v_add_u32_e32 v226, s35, v201
	ds_read_b128 v[150:153], v226
	v_mfma_f32_16x16x32_bf16 v[90:93], v[126:129], v[162:165], v[90:93]
	ds_read_b128 v[146:149], v226 offset:1024
	v_mfma_f32_16x16x32_bf16 v[58:61], v[130:133], v[162:165], v[58:61]
	ds_read_b128 v[142:145], v226 offset:2048
	v_mfma_f32_16x16x32_bf16 v[26:29], v[134:137], v[162:165], v[26:29]
	ds_read_b128 v[138:141], v226 offset:3072
	v_mfma_f32_16x16x32_bf16 v[114:117], v[122:125], v[166:169], v[114:117]
	ds_read_b128 v[174:177], v187
	v_mfma_f32_16x16x32_bf16 v[82:85], v[126:129], v[166:169], v[82:85]
	ds_read_b128 v[170:173], v187 offset:1024
	v_mfma_f32_16x16x32_bf16 v[50:53], v[130:133], v[166:169], v[50:53]
	ds_read_b128 v[162:165], v187 offset:3072
	v_mfma_f32_16x16x32_bf16 v[18:21], v[134:137], v[166:169], v[18:21]
	ds_read_b128 v[166:169], v187 offset:2048
	v_mfma_f32_16x16x32_bf16 v[106:109], v[122:125], v[232:235], v[106:109]
	v_mfma_f32_16x16x32_bf16 v[74:77], v[126:129], v[232:235], v[74:77]
	v_mfma_f32_16x16x32_bf16 v[42:45], v[130:133], v[232:235], v[42:45]
	v_mfma_f32_16x16x32_bf16 v[10:13], v[134:137], v[232:235], v[10:13]
	v_mfma_f32_16x16x32_bf16 v[98:101], v[122:125], v[236:239], v[98:101]
	v_mfma_f32_16x16x32_bf16 v[66:69], v[126:129], v[236:239], v[66:69]
	v_mfma_f32_16x16x32_bf16 v[34:37], v[130:133], v[236:239], v[34:37]
	v_mfma_f32_16x16x32_bf16 v[2:5], v[134:137], v[236:239], v[2:5]
	s_waitcnt lgkmcnt(0)
	v_mfma_f32_16x16x32_bf16 v[158:161], v[174:177], v[150:153], v[158:161]
	v_mfma_f32_16x16x32_bf16 v[94:97], v[170:173], v[150:153], v[94:97]
	v_add_u32_e32 v226, s35, v230
	ds_read_b128 v[232:235], v226
	v_mfma_f32_16x16x32_bf16 v[62:65], v[166:169], v[150:153], v[62:65]
	ds_read_b128 v[236:239], v226 offset:1024
	v_mfma_f32_16x16x32_bf16 v[30:33], v[162:165], v[150:153], v[30:33]
	ds_read_b128 v[182:185], v226 offset:2048
	v_mfma_f32_16x16x32_bf16 v[118:121], v[174:177], v[146:149], v[118:121]
	ds_read_b128 v[178:181], v226 offset:3072
	v_mfma_f32_16x16x32_bf16 v[86:89], v[170:173], v[146:149], v[86:89]
	v_mfma_f32_16x16x32_bf16 v[54:57], v[166:169], v[146:149], v[54:57]
	v_mfma_f32_16x16x32_bf16 v[22:25], v[162:165], v[146:149], v[22:25]
	v_mfma_f32_16x16x32_bf16 v[110:113], v[174:177], v[142:145], v[110:113]
	v_mfma_f32_16x16x32_bf16 v[78:81], v[170:173], v[142:145], v[78:81]
	v_mfma_f32_16x16x32_bf16 v[46:49], v[166:169], v[142:145], v[46:49]
	v_mfma_f32_16x16x32_bf16 v[14:17], v[162:165], v[142:145], v[14:17]
	v_mfma_f32_16x16x32_bf16 v[102:105], v[174:177], v[138:141], v[102:105]
	v_mfma_f32_16x16x32_bf16 v[70:73], v[170:173], v[138:141], v[70:73]
	v_mfma_f32_16x16x32_bf16 v[38:41], v[166:169], v[138:141], v[38:41]
	v_mfma_f32_16x16x32_bf16 v[6:9], v[162:165], v[138:141], v[6:9]
	s_waitcnt vmcnt(0)
	s_waitcnt lgkmcnt(0)
	s_barrier
	v_mfma_f32_16x16x32_bf16 v[154:157], v[174:177], v[232:235], v[154:157]
	v_mfma_f32_16x16x32_bf16 v[90:93], v[170:173], v[232:235], v[90:93]
	v_mfma_f32_16x16x32_bf16 v[58:61], v[166:169], v[232:235], v[58:61]
	v_mfma_f32_16x16x32_bf16 v[26:29], v[162:165], v[232:235], v[26:29]
	v_mfma_f32_16x16x32_bf16 v[114:117], v[174:177], v[236:239], v[114:117]
	v_mfma_f32_16x16x32_bf16 v[82:85], v[170:173], v[236:239], v[82:85]
	v_mfma_f32_16x16x32_bf16 v[50:53], v[166:169], v[236:239], v[50:53]
	v_mfma_f32_16x16x32_bf16 v[18:21], v[162:165], v[236:239], v[18:21]
	s_add_i32 s19, s19, 2
	s_add_u32 s20, s20, 0x80
	s_addc_u32 s21, s21, 0
	s_add_i32 s31, s31, 0x10000
	v_mfma_f32_16x16x32_bf16 v[106:109], v[174:177], v[182:185], v[106:109]
	v_mfma_f32_16x16x32_bf16 v[74:77], v[170:173], v[182:185], v[74:77]
	v_mfma_f32_16x16x32_bf16 v[42:45], v[166:169], v[182:185], v[42:45]
	v_mfma_f32_16x16x32_bf16 v[10:13], v[162:165], v[182:185], v[10:13]
	v_mfma_f32_16x16x32_bf16 v[98:101], v[174:177], v[178:181], v[98:101]
	v_mfma_f32_16x16x32_bf16 v[66:69], v[170:173], v[178:181], v[66:69]
	v_mfma_f32_16x16x32_bf16 v[34:37], v[166:169], v[178:181], v[34:37]
	v_mfma_f32_16x16x32_bf16 v[2:5], v[162:165], v[178:181], v[2:5]
	s_branch .LBB0_197

.Lgf_G3x_top:
	s_waitcnt vmcnt(3)
	s_waitcnt lgkmcnt(0)
	s_barrier
	v_mfma_f32_16x16x32_bf16 v[102:105], v[2:5], v[26:29], v[102:105]
	v_mfma_f32_16x16x32_bf16 v[98:101], v[6:9], v[26:29], v[98:101]
	s_add_i32 s17, s8, -3
	s_and_b32 s19, s17, 2
	s_mulk_i32 s19, 0x6000
	v_add_u32_e32 v110, s19, v142
	ds_read_b128 v[106:109], v110
	v_mfma_f32_16x16x32_bf16 v[86:89], v[10:13], v[26:29], v[86:89]
	ds_read_b128 v[144:147], v110 offset:1024
	s_and_b32 s69, s8, 3
	s_mulk_i32 s69, 0x6000
	s_add_i32 s69, s69, s29
	s_mov_b32 m0, s69
	v_mfma_f32_16x16x32_bf16 v[70:73], v[14:17], v[26:29], v[70:73]
	global_load_lds_dwordx4 v126, s[44:45]
	s_add_i32 m0, s69, 0x2000
	v_mfma_f32_16x16x32_bf16 v[90:93], v[2:5], v[22:25], v[90:93]
	global_load_lds_dwordx4 v128, s[44:45]
	s_add_i32 m0, s69, 0x4000
	v_mfma_f32_16x16x32_bf16 v[78:81], v[6:9], v[22:25], v[78:81]
	global_load_lds_dwordx4 v130, s[30:31]
	s_add_u32 s44, s44, 64
	s_addc_u32 s45, s45, 0
	s_add_u32 s30, s30, 64
	s_addc_u32 s31, s31, 0
	v_mfma_f32_16x16x32_bf16 v[62:65], v[10:13], v[22:25], v[62:65]
	v_mfma_f32_16x16x32_bf16 v[46:49], v[14:17], v[22:25], v[46:49]
	s_waitcnt lgkmcnt(0)
	v_mfma_f32_16x16x32_bf16 v[74:77], v[2:5], v[106:109], v[74:77]
	s_add_i32 s26, s8, -2
	s_and_b32 s28, s26, 3
	s_mulk_i32 s28, 0x6000
	v_add_u32_e32 v127, s28, v140
	v_add_u32_e32 v143, s28, v141
	ds_read_b128 v[26:29], v143
	v_mfma_f32_16x16x32_bf16 v[58:61], v[6:9], v[106:109], v[58:61]
	ds_read_b128 v[22:25], v143 offset:1024
	v_mfma_f32_16x16x32_bf16 v[38:41], v[10:13], v[106:109], v[38:41]
	ds_read_b128 v[118:121], v127
	v_mfma_f32_16x16x32_bf16 v[30:33], v[14:17], v[106:109], v[30:33]
	ds_read_b128 v[114:117], v127 offset:1024
	ds_read_b128 v[110:113], v127 offset:2048
	ds_read_b128 v[106:109], v127 offset:3072
	v_mfma_f32_16x16x32_bf16 v[94:97], v[2:5], v[144:147], v[94:97]
	v_mfma_f32_16x16x32_bf16 v[82:85], v[6:9], v[144:147], v[82:85]
	v_mfma_f32_16x16x32_bf16 v[66:69], v[10:13], v[144:147], v[66:69]
	v_mfma_f32_16x16x32_bf16 v[34:37], v[14:17], v[144:147], v[34:37]
	s_waitcnt vmcnt(3)
	s_waitcnt lgkmcnt(0)
	s_barrier
	v_mfma_f32_16x16x32_bf16 v[102:105], v[118:121], v[26:29], v[102:105]
	v_mfma_f32_16x16x32_bf16 v[98:101], v[114:117], v[26:29], v[98:101]
	v_add_u32_e32 v132, s28, v142
	ds_read_b128 v[144:147], v132
	v_mfma_f32_16x16x32_bf16 v[86:89], v[110:113], v[26:29], v[86:89]
	ds_read_b128 v[122:125], v132 offset:1024
	s_add_i32 s69, s19, s29
	s_mov_b32 m0, s69
	v_mfma_f32_16x16x32_bf16 v[70:73], v[106:109], v[26:29], v[70:73]
	global_load_lds_dwordx4 v126, s[44:45]
	s_add_i32 m0, s69, 0x2000
	v_mfma_f32_16x16x32_bf16 v[90:93], v[118:121], v[22:25], v[90:93]
	global_load_lds_dwordx4 v128, s[44:45]
	s_add_i32 m0, s69, 0x4000
	v_mfma_f32_16x16x32_bf16 v[78:81], v[114:117], v[22:25], v[78:81]
	global_load_lds_dwordx4 v130, s[30:31]
	s_add_u32 s44, s44, 64
	s_addc_u32 s45, s45, 0
	s_add_u32 s30, s30, 64
	s_addc_u32 s31, s31, 0
	v_mfma_f32_16x16x32_bf16 v[62:65], v[110:113], v[22:25], v[62:65]
	v_mfma_f32_16x16x32_bf16 v[46:49], v[106:109], v[22:25], v[46:49]
	s_waitcnt lgkmcnt(0)
	v_mfma_f32_16x16x32_bf16 v[74:77], v[118:121], v[144:147], v[74:77]
	s_add_i32 s19, s8, -1
	s_and_b32 s19, s19, 2
	s_mulk_i32 s19, 0x6000
	v_add_u32_e32 v127, s19, v140
	v_add_u32_e32 v132, s19, v141
	ds_read_b128 v[26:29], v132
	v_mfma_f32_16x16x32_bf16 v[58:61], v[114:117], v[144:147], v[58:61]
	ds_read_b128 v[22:25], v132 offset:1024
	v_mfma_f32_16x16x32_bf16 v[38:41], v[110:113], v[144:147], v[38:41]
	ds_read_b128 v[2:5], v127
	v_mfma_f32_16x16x32_bf16 v[30:33], v[106:109], v[144:147], v[30:33]
	ds_read_b128 v[6:9], v127 offset:1024
	ds_read_b128 v[10:13], v127 offset:2048
	ds_read_b128 v[14:17], v127 offset:3072
	s_add_u32 s20, s20, 0x80
	s_addc_u32 s21, s21, 0
	s_add_i32 s8, s8, 2
	s_cmp_gt_u32 s17, 29
	v_mfma_f32_16x16x32_bf16 v[94:97], v[118:121], v[122:125], v[94:97]
	v_mfma_f32_16x16x32_bf16 v[82:85], v[114:117], v[122:125], v[82:85]
	v_mfma_f32_16x16x32_bf16 v[66:69], v[110:113], v[122:125], v[66:69]
	v_mfma_f32_16x16x32_bf16 v[34:37], v[106:109], v[122:125], v[34:37]
	s_cmp_lt_u32 s8, 30
	s_cbranch_scc1 .Lgf_G3x_top
	s_waitcnt vmcnt(3)
	s_waitcnt lgkmcnt(0)
	s_barrier
	v_mfma_f32_16x16x32_bf16 v[102:105], v[2:5], v[26:29], v[102:105]
	v_mfma_f32_16x16x32_bf16 v[98:101], v[6:9], v[26:29], v[98:101]
	s_add_i32 s17, s8, -3
	s_and_b32 s19, s17, 2
	s_mulk_i32 s19, 0x6000
	v_add_u32_e32 v110, s19, v142
	ds_read_b128 v[106:109], v110
	v_mfma_f32_16x16x32_bf16 v[86:89], v[10:13], v[26:29], v[86:89]
	ds_read_b128 v[144:147], v110 offset:1024
	s_and_b32 s69, s8, 3
	s_mulk_i32 s69, 0x6000
	s_add_i32 s69, s69, s29
	s_mov_b32 m0, s69
	v_mfma_f32_16x16x32_bf16 v[70:73], v[14:17], v[26:29], v[70:73]
	global_load_lds_dwordx4 v126, s[44:45]
	s_add_i32 m0, s69, 0x2000
	v_mfma_f32_16x16x32_bf16 v[90:93], v[2:5], v[22:25], v[90:93]
	global_load_lds_dwordx4 v128, s[44:45]
	s_add_i32 m0, s69, 0x4000
	v_mfma_f32_16x16x32_bf16 v[78:81], v[6:9], v[22:25], v[78:81]
	global_load_lds_dwordx4 v130, s[30:31]
	s_add_u32 s44, s44, 64
	s_addc_u32 s45, s45, 0
	s_add_u32 s30, s30, 64
	s_addc_u32 s31, s31, 0
	v_mfma_f32_16x16x32_bf16 v[62:65], v[10:13], v[22:25], v[62:65]
	v_mfma_f32_16x16x32_bf16 v[46:49], v[14:17], v[22:25], v[46:49]
	s_waitcnt lgkmcnt(0)
	v_mfma_f32_16x16x32_bf16 v[74:77], v[2:5], v[106:109], v[74:77]
	s_add_i32 s26, s8, -2
	s_and_b32 s28, s26, 3
	s_mulk_i32 s28, 0x6000
	v_add_u32_e32 v127, s28, v140
	v_add_u32_e32 v143, s28, v141
	ds_read_b128 v[26:29], v143
	v_mfma_f32_16x16x32_bf16 v[58:61], v[6:9], v[106:109], v[58:61]
	ds_read_b128 v[22:25], v143 offset:1024
	v_mfma_f32_16x16x32_bf16 v[38:41], v[10:13], v[106:109], v[38:41]
	ds_read_b128 v[118:121], v127
	v_mfma_f32_16x16x32_bf16 v[30:33], v[14:17], v[106:109], v[30:33]
	ds_read_b128 v[114:117], v127 offset:1024
	ds_read_b128 v[110:113], v127 offset:2048
	ds_read_b128 v[106:109], v127 offset:3072
	v_mfma_f32_16x16x32_bf16 v[94:97], v[2:5], v[144:147], v[94:97]
	v_mfma_f32_16x16x32_bf16 v[82:85], v[6:9], v[144:147], v[82:85]
	v_mfma_f32_16x16x32_bf16 v[66:69], v[10:13], v[144:147], v[66:69]
	v_mfma_f32_16x16x32_bf16 v[34:37], v[14:17], v[144:147], v[34:37]
	s_waitcnt vmcnt(3)
	s_waitcnt lgkmcnt(0)
	s_barrier
	v_mfma_f32_16x16x32_bf16 v[102:105], v[118:121], v[26:29], v[102:105]
	v_mfma_f32_16x16x32_bf16 v[98:101], v[114:117], v[26:29], v[98:101]
	v_add_u32_e32 v132, s28, v142
	ds_read_b128 v[144:147], v132
	v_mfma_f32_16x16x32_bf16 v[86:89], v[110:113], v[26:29], v[86:89]
	ds_read_b128 v[122:125], v132 offset:1024
	v_mfma_f32_16x16x32_bf16 v[70:73], v[106:109], v[26:29], v[70:73]
	v_mfma_f32_16x16x32_bf16 v[90:93], v[118:121], v[22:25], v[90:93]
	v_mfma_f32_16x16x32_bf16 v[78:81], v[114:117], v[22:25], v[78:81]
	v_mfma_f32_16x16x32_bf16 v[62:65], v[110:113], v[22:25], v[62:65]
	v_mfma_f32_16x16x32_bf16 v[46:49], v[106:109], v[22:25], v[46:49]
	s_waitcnt lgkmcnt(0)
	v_mfma_f32_16x16x32_bf16 v[74:77], v[118:121], v[144:147], v[74:77]
	s_add_i32 s19, s8, -1
	s_and_b32 s19, s19, 2
	s_mulk_i32 s19, 0x6000
	v_add_u32_e32 v127, s19, v140
	v_add_u32_e32 v132, s19, v141
	ds_read_b128 v[26:29], v132
	v_mfma_f32_16x16x32_bf16 v[58:61], v[114:117], v[144:147], v[58:61]
	ds_read_b128 v[22:25], v132 offset:1024
	v_mfma_f32_16x16x32_bf16 v[38:41], v[110:113], v[144:147], v[38:41]
	ds_read_b128 v[2:5], v127
	v_mfma_f32_16x16x32_bf16 v[30:33], v[106:109], v[144:147], v[30:33]
	ds_read_b128 v[6:9], v127 offset:1024
	ds_read_b128 v[10:13], v127 offset:2048
	ds_read_b128 v[14:17], v127 offset:3072
	s_add_u32 s20, s20, 0x80
	s_addc_u32 s21, s21, 0
	s_add_i32 s8, s8, 2
	s_cmp_gt_u32 s17, 29
	v_mfma_f32_16x16x32_bf16 v[94:97], v[118:121], v[122:125], v[94:97]
	v_mfma_f32_16x16x32_bf16 v[82:85], v[114:117], v[122:125], v[82:85]
	v_mfma_f32_16x16x32_bf16 v[66:69], v[110:113], v[122:125], v[66:69]
	v_mfma_f32_16x16x32_bf16 v[34:37], v[106:109], v[122:125], v[34:37]
	s_waitcnt vmcnt(0)
	s_waitcnt lgkmcnt(0)
	s_barrier
	v_mfma_f32_16x16x32_bf16 v[102:105], v[2:5], v[26:29], v[102:105]
	v_mfma_f32_16x16x32_bf16 v[98:101], v[6:9], v[26:29], v[98:101]
	s_add_i32 s17, s8, -3
	s_and_b32 s19, s17, 2
	s_mulk_i32 s19, 0x6000
	v_add_u32_e32 v110, s19, v142
	ds_read_b128 v[106:109], v110
	v_mfma_f32_16x16x32_bf16 v[86:89], v[10:13], v[26:29], v[86:89]
	ds_read_b128 v[144:147], v110 offset:1024
	v_mfma_f32_16x16x32_bf16 v[70:73], v[14:17], v[26:29], v[70:73]
	v_mfma_f32_16x16x32_bf16 v[90:93], v[2:5], v[22:25], v[90:93]
	v_mfma_f32_16x16x32_bf16 v[78:81], v[6:9], v[22:25], v[78:81]
	v_mfma_f32_16x16x32_bf16 v[62:65], v[10:13], v[22:25], v[62:65]
	v_mfma_f32_16x16x32_bf16 v[46:49], v[14:17], v[22:25], v[46:49]
	s_waitcnt lgkmcnt(0)
	v_mfma_f32_16x16x32_bf16 v[74:77], v[2:5], v[106:109], v[74:77]
	s_add_i32 s26, s8, -2
	s_and_b32 s28, s26, 3
	s_mulk_i32 s28, 0x6000
	v_add_u32_e32 v127, s28, v140
	v_add_u32_e32 v143, s28, v141
	ds_read_b128 v[26:29], v143
	v_mfma_f32_16x16x32_bf16 v[58:61], v[6:9], v[106:109], v[58:61]
	ds_read_b128 v[22:25], v143 offset:1024
	v_mfma_f32_16x16x32_bf16 v[38:41], v[10:13], v[106:109], v[38:41]
	ds_read_b128 v[118:121], v127
	v_mfma_f32_16x16x32_bf16 v[30:33], v[14:17], v[106:109], v[30:33]
	ds_read_b128 v[114:117], v127 offset:1024
	ds_read_b128 v[110:113], v127 offset:2048
	ds_read_b128 v[106:109], v127 offset:3072
	v_mfma_f32_16x16x32_bf16 v[94:97], v[2:5], v[144:147], v[94:97]
	v_mfma_f32_16x16x32_bf16 v[82:85], v[6:9], v[144:147], v[82:85]
	v_mfma_f32_16x16x32_bf16 v[66:69], v[10:13], v[144:147], v[66:69]
	v_mfma_f32_16x16x32_bf16 v[34:37], v[14:17], v[144:147], v[34:37]
	s_waitcnt vmcnt(0)
	s_waitcnt lgkmcnt(0)
	s_barrier
	v_mfma_f32_16x16x32_bf16 v[102:105], v[118:121], v[26:29], v[102:105]
	v_mfma_f32_16x16x32_bf16 v[98:101], v[114:117], v[26:29], v[98:101]
	v_add_u32_e32 v132, s28, v142
	ds_read_b128 v[144:147], v132
	v_mfma_f32_16x16x32_bf16 v[86:89], v[110:113], v[26:29], v[86:89]
	ds_read_b128 v[122:125], v132 offset:1024
	v_mfma_f32_16x16x32_bf16 v[70:73], v[106:109], v[26:29], v[70:73]
	v_mfma_f32_16x16x32_bf16 v[90:93], v[118:121], v[22:25], v[90:93]
	v_mfma_f32_16x16x32_bf16 v[78:81], v[114:117], v[22:25], v[78:81]
	v_mfma_f32_16x16x32_bf16 v[62:65], v[110:113], v[22:25], v[62:65]
	v_mfma_f32_16x16x32_bf16 v[46:49], v[106:109], v[22:25], v[46:49]
	s_waitcnt lgkmcnt(0)
	v_mfma_f32_16x16x32_bf16 v[74:77], v[118:121], v[144:147], v[74:77]
	v_mfma_f32_16x16x32_bf16 v[58:61], v[114:117], v[144:147], v[58:61]
	v_mfma_f32_16x16x32_bf16 v[38:41], v[110:113], v[144:147], v[38:41]
	v_mfma_f32_16x16x32_bf16 v[30:33], v[106:109], v[144:147], v[30:33]
	s_add_u32 s20, s20, 0x80
	s_addc_u32 s21, s21, 0
	s_add_i32 s8, s8, 2
	s_cmp_gt_u32 s17, 29
	v_mfma_f32_16x16x32_bf16 v[94:97], v[118:121], v[122:125], v[94:97]
	v_mfma_f32_16x16x32_bf16 v[82:85], v[114:117], v[122:125], v[82:85]
	v_mfma_f32_16x16x32_bf16 v[66:69], v[110:113], v[122:125], v[66:69]
	v_mfma_f32_16x16x32_bf16 v[34:37], v[106:109], v[122:125], v[34:37]
	s_branch .LBB0_305
.Lgr_G3x_entry:
	s_waitcnt vmcnt(3)
	s_waitcnt lgkmcnt(0)
	s_barrier
	v_mfma_f32_16x16x32_bf16 v[102:105], v[2:5], v[26:29], v[102:105]
	v_mfma_f32_16x16x32_bf16 v[98:101], v[6:9], v[26:29], v[98:101]
	s_add_i32 s17, s8, -3
	s_and_b32 s19, s17, 2
	s_mulk_i32 s19, 0x6000
	v_add_u32_e32 v110, s19, v142
	ds_read_b128 v[106:109], v110
	v_mfma_f32_16x16x32_bf16 v[86:89], v[10:13], v[26:29], v[86:89]
	ds_read_b128 v[144:147], v110 offset:1024
	s_and_b32 s69, s8, 3
	s_mulk_i32 s69, 0x6000
	s_add_i32 s69, s69, s29
	s_mov_b32 m0, s69
	v_mfma_f32_16x16x32_bf16 v[70:73], v[14:17], v[26:29], v[70:73]
	global_load_lds_dwordx4 v126, s[44:45]
	s_add_i32 m0, s69, 0x2000
	v_mfma_f32_16x16x32_bf16 v[90:93], v[2:5], v[22:25], v[90:93]
	global_load_lds_dwordx4 v128, s[44:45]
	s_add_i32 m0, s69, 0x4000
	v_mfma_f32_16x16x32_bf16 v[78:81], v[6:9], v[22:25], v[78:81]
	global_load_lds_dwordx4 v130, s[30:31]
	s_add_u32 s44, s44, 64
	s_addc_u32 s45, s45, 0
	s_add_u32 s30, s30, 64
	s_addc_u32 s31, s31, 0
	v_mfma_f32_16x16x32_bf16 v[62:65], v[10:13], v[22:25], v[62:65]
	v_mfma_f32_16x16x32_bf16 v[46:49], v[14:17], v[22:25], v[46:49]
	s_waitcnt vmcnt(3)
	s_waitcnt lgkmcnt(0)
	s_barrier
	v_mfma_f32_16x16x32_bf16 v[74:77], v[2:5], v[106:109], v[74:77]
	s_add_i32 s26, s8, -2
	s_and_b32 s28, s26, 3
	s_mulk_i32 s28, 0x6000
	v_add_u32_e32 v127, s28, v140
	v_add_u32_e32 v143, s28, v141
	ds_read_b128 v[26:29], v143
	v_mfma_f32_16x16x32_bf16 v[58:61], v[6:9], v[106:109], v[58:61]
	ds_read_b128 v[22:25], v143 offset:1024
	v_mfma_f32_16x16x32_bf16 v[38:41], v[10:13], v[106:109], v[38:41]
	ds_read_b128 v[118:121], v127
	v_mfma_f32_16x16x32_bf16 v[30:33], v[14:17], v[106:109], v[30:33]
	ds_read_b128 v[114:117], v127 offset:1024
	ds_read_b128 v[110:113], v127 offset:2048
	ds_read_b128 v[106:109], v127 offset:3072
	v_mfma_f32_16x16x32_bf16 v[94:97], v[2:5], v[144:147], v[94:97]
	v_mfma_f32_16x16x32_bf16 v[82:85], v[6:9], v[144:147], v[82:85]
	v_mfma_f32_16x16x32_bf16 v[66:69], v[10:13], v[144:147], v[66:69]
	v_mfma_f32_16x16x32_bf16 v[34:37], v[14:17], v[144:147], v[34:37]
	s_waitcnt lgkmcnt(0)
	v_mfma_f32_16x16x32_bf16 v[102:105], v[118:121], v[26:29], v[102:105]
	v_mfma_f32_16x16x32_bf16 v[98:101], v[114:117], v[26:29], v[98:101]
	v_add_u32_e32 v132, s28, v142
	ds_read_b128 v[144:147], v132
	v_mfma_f32_16x16x32_bf16 v[86:89], v[110:113], v[26:29], v[86:89]
	ds_read_b128 v[122:125], v132 offset:1024
	s_add_i32 s69, s19, s29
	s_mov_b32 m0, s69
	v_mfma_f32_16x16x32_bf16 v[70:73], v[106:109], v[26:29], v[70:73]
	global_load_lds_dwordx4 v126, s[44:45]
	s_add_i32 m0, s69, 0x2000
	v_mfma_f32_16x16x32_bf16 v[90:93], v[118:121], v[22:25], v[90:93]
	global_load_lds_dwordx4 v128, s[44:45]
	s_add_i32 m0, s69, 0x4000
	v_mfma_f32_16x16x32_bf16 v[78:81], v[114:117], v[22:25], v[78:81]
	global_load_lds_dwordx4 v130, s[30:31]
	s_add_u32 s44, s44, 64
	s_addc_u32 s45, s45, 0
	s_add_u32 s30, s30, 64
	s_addc_u32 s31, s31, 0
	v_mfma_f32_16x16x32_bf16 v[62:65], v[110:113], v[22:25], v[62:65]
	v_mfma_f32_16x16x32_bf16 v[46:49], v[106:109], v[22:25], v[46:49]
.Lgr_G3x_top:
	s_waitcnt vmcnt(3)
	s_waitcnt lgkmcnt(0)
	s_barrier
	v_mfma_f32_16x16x32_bf16 v[74:77], v[118:121], v[144:147], v[74:77]
	s_add_i32 s19, s8, -1
	s_and_b32 s19, s19, 2
	s_mulk_i32 s19, 0x6000
	v_add_u32_e32 v127, s19, v140
	v_add_u32_e32 v132, s19, v141
	ds_read_b128 v[26:29], v132
	v_mfma_f32_16x16x32_bf16 v[58:61], v[114:117], v[144:147], v[58:61]
	ds_read_b128 v[22:25], v132 offset:1024
	v_mfma_f32_16x16x32_bf16 v[38:41], v[110:113], v[144:147], v[38:41]
	ds_read_b128 v[2:5], v127
	v_mfma_f32_16x16x32_bf16 v[30:33], v[106:109], v[144:147], v[30:33]
	ds_read_b128 v[6:9], v127 offset:1024
	ds_read_b128 v[10:13], v127 offset:2048
	ds_read_b128 v[14:17], v127 offset:3072
	s_add_u32 s20, s20, 0x80
	s_addc_u32 s21, s21, 0
	s_add_i32 s8, s8, 2
	s_cmp_gt_u32 s17, 29
	v_mfma_f32_16x16x32_bf16 v[94:97], v[118:121], v[122:125], v[94:97]
	v_mfma_f32_16x16x32_bf16 v[82:85], v[114:117], v[122:125], v[82:85]
	v_mfma_f32_16x16x32_bf16 v[66:69], v[110:113], v[122:125], v[66:69]
	v_mfma_f32_16x16x32_bf16 v[34:37], v[106:109], v[122:125], v[34:37]
	s_cmp_lt_u32 s8, 30
	s_cbranch_scc0 .Lgr_G3x_tail
	s_waitcnt lgkmcnt(0)
	v_mfma_f32_16x16x32_bf16 v[102:105], v[2:5], v[26:29], v[102:105]
	v_mfma_f32_16x16x32_bf16 v[98:101], v[6:9], v[26:29], v[98:101]
	s_add_i32 s17, s8, -3
	s_and_b32 s19, s17, 2
	s_mulk_i32 s19, 0x6000
	v_add_u32_e32 v110, s19, v142
	ds_read_b128 v[106:109], v110
	v_mfma_f32_16x16x32_bf16 v[86:89], v[10:13], v[26:29], v[86:89]
	ds_read_b128 v[144:147], v110 offset:1024
	s_and_b32 s69, s8, 3
	s_mulk_i32 s69, 0x6000
	s_add_i32 s69, s69, s29
	s_mov_b32 m0, s69
	v_mfma_f32_16x16x32_bf16 v[70:73], v[14:17], v[26:29], v[70:73]
	global_load_lds_dwordx4 v126, s[44:45]
	s_add_i32 m0, s69, 0x2000
	v_mfma_f32_16x16x32_bf16 v[90:93], v[2:5], v[22:25], v[90:93]
	global_load_lds_dwordx4 v128, s[44:45]
	s_add_i32 m0, s69, 0x4000
	v_mfma_f32_16x16x32_bf16 v[78:81], v[6:9], v[22:25], v[78:81]
	global_load_lds_dwordx4 v130, s[30:31]
	s_add_u32 s44, s44, 64
	s_addc_u32 s45, s45, 0
	s_add_u32 s30, s30, 64
	s_addc_u32 s31, s31, 0
	v_mfma_f32_16x16x32_bf16 v[62:65], v[10:13], v[22:25], v[62:65]
	v_mfma_f32_16x16x32_bf16 v[46:49], v[14:17], v[22:25], v[46:49]
	s_waitcnt vmcnt(3)
	s_waitcnt lgkmcnt(0)
	s_barrier
	v_mfma_f32_16x16x32_bf16 v[74:77], v[2:5], v[106:109], v[74:77]
	s_add_i32 s26, s8, -2
	s_and_b32 s28, s26, 3
	s_mulk_i32 s28, 0x6000
	v_add_u32_e32 v127, s28, v140
	v_add_u32_e32 v143, s28, v141
	ds_read_b128 v[26:29], v143
	v_mfma_f32_16x16x32_bf16 v[58:61], v[6:9], v[106:109], v[58:61]
	ds_read_b128 v[22:25], v143 offset:1024
	v_mfma_f32_16x16x32_bf16 v[38:41], v[10:13], v[106:109], v[38:41]
	ds_read_b128 v[118:121], v127
	v_mfma_f32_16x16x32_bf16 v[30:33], v[14:17], v[106:109], v[30:33]
	ds_read_b128 v[114:117], v127 offset:1024
	ds_read_b128 v[110:113], v127 offset:2048
	ds_read_b128 v[106:109], v127 offset:3072
	v_mfma_f32_16x16x32_bf16 v[94:97], v[2:5], v[144:147], v[94:97]
	v_mfma_f32_16x16x32_bf16 v[82:85], v[6:9], v[144:147], v[82:85]
	v_mfma_f32_16x16x32_bf16 v[66:69], v[10:13], v[144:147], v[66:69]
	v_mfma_f32_16x16x32_bf16 v[34:37], v[14:17], v[144:147], v[34:37]
	s_waitcnt lgkmcnt(0)
	v_mfma_f32_16x16x32_bf16 v[102:105], v[118:121], v[26:29], v[102:105]
	v_mfma_f32_16x16x32_bf16 v[98:101], v[114:117], v[26:29], v[98:101]
	v_add_u32_e32 v132, s28, v142
	ds_read_b128 v[144:147], v132
	v_mfma_f32_16x16x32_bf16 v[86:89], v[110:113], v[26:29], v[86:89]
	ds_read_b128 v[122:125], v132 offset:1024
	s_add_i32 s69, s19, s29
	s_mov_b32 m0, s69
	v_mfma_f32_16x16x32_bf16 v[70:73], v[106:109], v[26:29], v[70:73]
	global_load_lds_dwordx4 v126, s[44:45]
	s_add_i32 m0, s69, 0x2000
	v_mfma_f32_16x16x32_bf16 v[90:93], v[118:121], v[22:25], v[90:93]
	global_load_lds_dwordx4 v128, s[44:45]
	s_add_i32 m0, s69, 0x4000
	v_mfma_f32_16x16x32_bf16 v[78:81], v[114:117], v[22:25], v[78:81]
	global_load_lds_dwordx4 v130, s[30:31]
	s_add_u32 s44, s44, 64
	s_addc_u32 s45, s45, 0
	s_add_u32 s30, s30, 64
	s_addc_u32 s31, s31, 0
	v_mfma_f32_16x16x32_bf16 v[62:65], v[110:113], v[22:25], v[62:65]
	v_mfma_f32_16x16x32_bf16 v[46:49], v[106:109], v[22:25], v[46:49]
	s_branch .Lgr_G3x_top
.Lgr_G3x_tail:
	s_waitcnt lgkmcnt(0)
	v_mfma_f32_16x16x32_bf16 v[102:105], v[2:5], v[26:29], v[102:105]
	v_mfma_f32_16x16x32_bf16 v[98:101], v[6:9], v[26:29], v[98:101]
	s_add_i32 s17, s8, -3
	s_and_b32 s19, s17, 2
	s_mulk_i32 s19, 0x6000
	v_add_u32_e32 v110, s19, v142
	ds_read_b128 v[106:109], v110
	v_mfma_f32_16x16x32_bf16 v[86:89], v[10:13], v[26:29], v[86:89]
	ds_read_b128 v[144:147], v110 offset:1024
	s_and_b32 s69, s8, 3
	s_mulk_i32 s69, 0x6000
	s_add_i32 s69, s69, s29
	s_mov_b32 m0, s69
	v_mfma_f32_16x16x32_bf16 v[70:73], v[14:17], v[26:29], v[70:73]
	global_load_lds_dwordx4 v126, s[44:45]
	s_add_i32 m0, s69, 0x2000
	v_mfma_f32_16x16x32_bf16 v[90:93], v[2:5], v[22:25], v[90:93]
	global_load_lds_dwordx4 v128, s[44:45]
	s_add_i32 m0, s69, 0x4000
	v_mfma_f32_16x16x32_bf16 v[78:81], v[6:9], v[22:25], v[78:81]
	global_load_lds_dwordx4 v130, s[30:31]
	s_add_u32 s44, s44, 64
	s_addc_u32 s45, s45, 0
	s_add_u32 s30, s30, 64
	s_addc_u32 s31, s31, 0
	v_mfma_f32_16x16x32_bf16 v[62:65], v[10:13], v[22:25], v[62:65]
	v_mfma_f32_16x16x32_bf16 v[46:49], v[14:17], v[22:25], v[46:49]
	s_waitcnt vmcnt(3)
	s_waitcnt lgkmcnt(0)
	s_barrier
	v_mfma_f32_16x16x32_bf16 v[74:77], v[2:5], v[106:109], v[74:77]
	s_add_i32 s26, s8, -2
	s_and_b32 s28, s26, 3
	s_mulk_i32 s28, 0x6000
	v_add_u32_e32 v127, s28, v140
	v_add_u32_e32 v143, s28, v141
	ds_read_b128 v[26:29], v143
	v_mfma_f32_16x16x32_bf16 v[58:61], v[6:9], v[106:109], v[58:61]
	ds_read_b128 v[22:25], v143 offset:1024
	v_mfma_f32_16x16x32_bf16 v[38:41], v[10:13], v[106:109], v[38:41]
	ds_read_b128 v[118:121], v127
	v_mfma_f32_16x16x32_bf16 v[30:33], v[14:17], v[106:109], v[30:33]
	ds_read_b128 v[114:117], v127 offset:1024
	ds_read_b128 v[110:113], v127 offset:2048
	ds_read_b128 v[106:109], v127 offset:3072
	v_mfma_f32_16x16x32_bf16 v[94:97], v[2:5], v[144:147], v[94:97]
	v_mfma_f32_16x16x32_bf16 v[82:85], v[6:9], v[144:147], v[82:85]
	v_mfma_f32_16x16x32_bf16 v[66:69], v[10:13], v[144:147], v[66:69]
	v_mfma_f32_16x16x32_bf16 v[34:37], v[14:17], v[144:147], v[34:37]
	s_waitcnt lgkmcnt(0)
	v_mfma_f32_16x16x32_bf16 v[102:105], v[118:121], v[26:29], v[102:105]
	v_mfma_f32_16x16x32_bf16 v[98:101], v[114:117], v[26:29], v[98:101]
	v_add_u32_e32 v132, s28, v142
	ds_read_b128 v[144:147], v132
	v_mfma_f32_16x16x32_bf16 v[86:89], v[110:113], v[26:29], v[86:89]
	ds_read_b128 v[122:125], v132 offset:1024
	v_mfma_f32_16x16x32_bf16 v[70:73], v[106:109], v[26:29], v[70:73]
	v_mfma_f32_16x16x32_bf16 v[90:93], v[118:121], v[22:25], v[90:93]
	v_mfma_f32_16x16x32_bf16 v[78:81], v[114:117], v[22:25], v[78:81]
	v_mfma_f32_16x16x32_bf16 v[62:65], v[110:113], v[22:25], v[62:65]
	v_mfma_f32_16x16x32_bf16 v[46:49], v[106:109], v[22:25], v[46:49]
	s_waitcnt vmcnt(0)
	s_waitcnt lgkmcnt(0)
	s_barrier
	v_mfma_f32_16x16x32_bf16 v[74:77], v[118:121], v[144:147], v[74:77]
	s_add_i32 s19, s8, -1
	s_and_b32 s19, s19, 2
	s_mulk_i32 s19, 0x6000
	v_add_u32_e32 v127, s19, v140
	v_add_u32_e32 v132, s19, v141
	ds_read_b128 v[26:29], v132
	v_mfma_f32_16x16x32_bf16 v[58:61], v[114:117], v[144:147], v[58:61]
	ds_read_b128 v[22:25], v132 offset:1024
	v_mfma_f32_16x16x32_bf16 v[38:41], v[110:113], v[144:147], v[38:41]
	ds_read_b128 v[2:5], v127
	v_mfma_f32_16x16x32_bf16 v[30:33], v[106:109], v[144:147], v[30:33]
	ds_read_b128 v[6:9], v127 offset:1024
	ds_read_b128 v[10:13], v127 offset:2048
	ds_read_b128 v[14:17], v127 offset:3072
	s_add_u32 s20, s20, 0x80
	s_addc_u32 s21, s21, 0
	s_add_i32 s8, s8, 2
	s_cmp_gt_u32 s17, 29
	v_mfma_f32_16x16x32_bf16 v[94:97], v[118:121], v[122:125], v[94:97]
	v_mfma_f32_16x16x32_bf16 v[82:85], v[114:117], v[122:125], v[82:85]
	v_mfma_f32_16x16x32_bf16 v[66:69], v[110:113], v[122:125], v[66:69]
	v_mfma_f32_16x16x32_bf16 v[34:37], v[106:109], v[122:125], v[34:37]
	s_waitcnt lgkmcnt(0)
	v_mfma_f32_16x16x32_bf16 v[102:105], v[2:5], v[26:29], v[102:105]
	v_mfma_f32_16x16x32_bf16 v[98:101], v[6:9], v[26:29], v[98:101]
	s_add_i32 s17, s8, -3
	s_and_b32 s19, s17, 2
	s_mulk_i32 s19, 0x6000
	v_add_u32_e32 v110, s19, v142
	ds_read_b128 v[106:109], v110
	v_mfma_f32_16x16x32_bf16 v[86:89], v[10:13], v[26:29], v[86:89]
	ds_read_b128 v[144:147], v110 offset:1024
	v_mfma_f32_16x16x32_bf16 v[70:73], v[14:17], v[26:29], v[70:73]
	v_mfma_f32_16x16x32_bf16 v[90:93], v[2:5], v[22:25], v[90:93]
	v_mfma_f32_16x16x32_bf16 v[78:81], v[6:9], v[22:25], v[78:81]
	v_mfma_f32_16x16x32_bf16 v[62:65], v[10:13], v[22:25], v[62:65]
	v_mfma_f32_16x16x32_bf16 v[46:49], v[14:17], v[22:25], v[46:49]
	s_waitcnt vmcnt(0)
	s_waitcnt lgkmcnt(0)
	s_barrier
	v_mfma_f32_16x16x32_bf16 v[74:77], v[2:5], v[106:109], v[74:77]
	s_add_i32 s26, s8, -2
	s_and_b32 s28, s26, 3
	s_mulk_i32 s28, 0x6000
	v_add_u32_e32 v127, s28, v140
	v_add_u32_e32 v143, s28, v141
	ds_read_b128 v[26:29], v143
	v_mfma_f32_16x16x32_bf16 v[58:61], v[6:9], v[106:109], v[58:61]
	ds_read_b128 v[22:25], v143 offset:1024
	v_mfma_f32_16x16x32_bf16 v[38:41], v[10:13], v[106:109], v[38:41]
	ds_read_b128 v[118:121], v127
	v_mfma_f32_16x16x32_bf16 v[30:33], v[14:17], v[106:109], v[30:33]
	ds_read_b128 v[114:117], v127 offset:1024
	ds_read_b128 v[110:113], v127 offset:2048
	ds_read_b128 v[106:109], v127 offset:3072
	v_mfma_f32_16x16x32_bf16 v[94:97], v[2:5], v[144:147], v[94:97]
	v_mfma_f32_16x16x32_bf16 v[82:85], v[6:9], v[144:147], v[82:85]
	v_mfma_f32_16x16x32_bf16 v[66:69], v[10:13], v[144:147], v[66:69]
	v_mfma_f32_16x16x32_bf16 v[34:37], v[14:17], v[144:147], v[34:37]
	s_waitcnt lgkmcnt(0)
	v_mfma_f32_16x16x32_bf16 v[102:105], v[118:121], v[26:29], v[102:105]
	v_mfma_f32_16x16x32_bf16 v[98:101], v[114:117], v[26:29], v[98:101]
	v_add_u32_e32 v132, s28, v142
	ds_read_b128 v[144:147], v132
	v_mfma_f32_16x16x32_bf16 v[86:89], v[110:113], v[26:29], v[86:89]
	ds_read_b128 v[122:125], v132 offset:1024
	v_mfma_f32_16x16x32_bf16 v[70:73], v[106:109], v[26:29], v[70:73]
	v_mfma_f32_16x16x32_bf16 v[90:93], v[118:121], v[22:25], v[90:93]
	v_mfma_f32_16x16x32_bf16 v[78:81], v[114:117], v[22:25], v[78:81]
	v_mfma_f32_16x16x32_bf16 v[62:65], v[110:113], v[22:25], v[62:65]
	v_mfma_f32_16x16x32_bf16 v[46:49], v[106:109], v[22:25], v[46:49]
	s_waitcnt vmcnt(0)
	s_waitcnt lgkmcnt(0)
	s_barrier
	v_mfma_f32_16x16x32_bf16 v[74:77], v[118:121], v[144:147], v[74:77]
	v_mfma_f32_16x16x32_bf16 v[58:61], v[114:117], v[144:147], v[58:61]
	v_mfma_f32_16x16x32_bf16 v[38:41], v[110:113], v[144:147], v[38:41]
	v_mfma_f32_16x16x32_bf16 v[30:33], v[106:109], v[144:147], v[30:33]
	s_add_u32 s20, s20, 0x80
	s_addc_u32 s21, s21, 0
	s_add_i32 s8, s8, 2
	s_cmp_gt_u32 s17, 29
	v_mfma_f32_16x16x32_bf16 v[94:97], v[118:121], v[122:125], v[94:97]
	v_mfma_f32_16x16x32_bf16 v[82:85], v[114:117], v[122:125], v[82:85]
	v_mfma_f32_16x16x32_bf16 v[66:69], v[110:113], v[122:125], v[66:69]
	v_mfma_f32_16x16x32_bf16 v[34:37], v[106:109], v[122:125], v[34:37]
	s_branch .LBB0_305

.Lgf_G1x_top:
	s_waitcnt vmcnt(4)
	s_waitcnt lgkmcnt(0)
	s_barrier
	v_mfma_f32_16x16x32_bf16 v[126:129], v[130:133], v[158:161], v[126:129]
	v_mfma_f32_16x16x32_bf16 v[98:101], v[134:137], v[158:161], v[98:101]
	s_add_i32 s28, s31, 0xfffe8000
	s_and_b32 s34, s28, 0x10000
	v_add_u32_e32 v170, s34, v233
	ds_read_b128 v[162:165], v170
	v_mfma_f32_16x16x32_bf16 v[66:69], v[138:141], v[158:161], v[66:69]
	ds_read_b128 v[166:169], v170 offset:1024
	v_mfma_f32_16x16x32_bf16 v[34:37], v[142:145], v[158:161], v[34:37]
	ds_read_b128 v[234:237], v170 offset:2048
	v_mfma_f32_16x16x32_bf16 v[122:125], v[130:133], v[154:157], v[122:125]
	ds_read_b128 v[238:241], v170 offset:3072
	s_and_b32 s40, s31, 0x18000
	s_add_i32 s40, s40, s69
	s_mov_b32 m0, s40
	v_mfma_f32_16x16x32_bf16 v[90:93], v[134:137], v[154:157], v[90:93]
	global_load_lds_dwordx4 v188, s[94:95]
	s_add_i32 m0, s40, 0x2000
	v_mfma_f32_16x16x32_bf16 v[58:61], v[138:141], v[154:157], v[58:61]
	v_mfma_f32_16x16x32_bf16 v[26:29], v[142:145], v[154:157], v[26:29]
	global_load_lds_dwordx4 v190, s[94:95]
	s_add_i32 m0, s40, 0x4000
	v_mfma_f32_16x16x32_bf16 v[118:121], v[130:133], v[150:153], v[118:121]
	v_mfma_f32_16x16x32_bf16 v[86:89], v[134:137], v[150:153], v[86:89]
	global_load_lds_dwordx4 v192, s[42:43]
	s_add_i32 m0, s40, 0x6000
	v_mfma_f32_16x16x32_bf16 v[54:57], v[138:141], v[150:153], v[54:57]
	v_mfma_f32_16x16x32_bf16 v[22:25], v[142:145], v[150:153], v[22:25]
	global_load_lds_dwordx4 v194, s[42:43]
	s_add_u32 s94, s94, 64
	s_addc_u32 s95, s95, 0
	s_add_u32 s42, s42, 64
	s_addc_u32 s43, s43, 0
	v_mfma_f32_16x16x32_bf16 v[114:117], v[130:133], v[146:149], v[114:117]
	v_mfma_f32_16x16x32_bf16 v[82:85], v[134:137], v[146:149], v[82:85]
	v_mfma_f32_16x16x32_bf16 v[50:53], v[138:141], v[146:149], v[50:53]
	v_mfma_f32_16x16x32_bf16 v[18:21], v[142:145], v[146:149], v[18:21]
	s_waitcnt lgkmcnt(0)
	v_mfma_f32_16x16x32_bf16 v[110:113], v[130:133], v[162:165], v[110:113]
	s_add_i32 s28, s31, 0xffff0000
	s_and_b32 s35, s28, 0x18000
	v_add_u32_e32 v189, s35, v231
	v_add_u32_e32 v226, s35, v232
	ds_read_b128 v[158:161], v226
	v_mfma_f32_16x16x32_bf16 v[78:81], v[134:137], v[162:165], v[78:81]
	ds_read_b128 v[154:157], v226 offset:1024
	v_mfma_f32_16x16x32_bf16 v[46:49], v[138:141], v[162:165], v[46:49]
	ds_read_b128 v[150:153], v226 offset:2048
	v_mfma_f32_16x16x32_bf16 v[14:17], v[142:145], v[162:165], v[14:17]
	ds_read_b128 v[146:149], v226 offset:3072
	v_mfma_f32_16x16x32_bf16 v[106:109], v[130:133], v[166:169], v[106:109]
	ds_read_b128 v[174:177], v189
	v_mfma_f32_16x16x32_bf16 v[74:77], v[134:137], v[166:169], v[74:77]
	ds_read_b128 v[170:173], v189 offset:1024
	v_mfma_f32_16x16x32_bf16 v[42:45], v[138:141], v[166:169], v[42:45]
	ds_read_b128 v[162:165], v189 offset:3072
	v_mfma_f32_16x16x32_bf16 v[10:13], v[142:145], v[166:169], v[10:13]
	ds_read_b128 v[166:169], v189 offset:2048
	v_mfma_f32_16x16x32_bf16 v[102:105], v[130:133], v[234:237], v[102:105]
	v_mfma_f32_16x16x32_bf16 v[70:73], v[134:137], v[234:237], v[70:73]
	v_mfma_f32_16x16x32_bf16 v[38:41], v[138:141], v[234:237], v[38:41]
	v_mfma_f32_16x16x32_bf16 v[6:9], v[142:145], v[234:237], v[6:9]
	v_mfma_f32_16x16x32_bf16 v[94:97], v[130:133], v[238:241], v[94:97]
	v_mfma_f32_16x16x32_bf16 v[62:65], v[134:137], v[238:241], v[62:65]
	v_mfma_f32_16x16x32_bf16 v[30:33], v[138:141], v[238:241], v[30:33]
	v_mfma_f32_16x16x32_bf16 v[2:5], v[142:145], v[238:241], v[2:5]
	s_waitcnt vmcnt(4)
	s_waitcnt lgkmcnt(0)
	s_barrier
	v_mfma_f32_16x16x32_bf16 v[126:129], v[174:177], v[158:161], v[126:129]
	v_mfma_f32_16x16x32_bf16 v[98:101], v[170:173], v[158:161], v[98:101]
	v_add_u32_e32 v226, s35, v233
	ds_read_b128 v[234:237], v226
	v_mfma_f32_16x16x32_bf16 v[66:69], v[166:169], v[158:161], v[66:69]
	ds_read_b128 v[238:241], v226 offset:1024
	v_mfma_f32_16x16x32_bf16 v[34:37], v[162:165], v[158:161], v[34:37]
	ds_read_b128 v[182:185], v226 offset:2048
	v_mfma_f32_16x16x32_bf16 v[122:125], v[174:177], v[154:157], v[122:125]
	ds_read_b128 v[178:181], v226 offset:3072
	s_add_i32 s40, s34, s69
	s_mov_b32 m0, s40
	v_mfma_f32_16x16x32_bf16 v[90:93], v[170:173], v[154:157], v[90:93]
	global_load_lds_dwordx4 v188, s[94:95]
	s_add_i32 m0, s40, 0x2000
	v_mfma_f32_16x16x32_bf16 v[58:61], v[166:169], v[154:157], v[58:61]
	v_mfma_f32_16x16x32_bf16 v[26:29], v[162:165], v[154:157], v[26:29]
	global_load_lds_dwordx4 v190, s[94:95]
	s_add_i32 m0, s40, 0x4000
	v_mfma_f32_16x16x32_bf16 v[118:121], v[174:177], v[150:153], v[118:121]
	v_mfma_f32_16x16x32_bf16 v[86:89], v[170:173], v[150:153], v[86:89]
	global_load_lds_dwordx4 v192, s[42:43]
	s_add_i32 m0, s40, 0x6000
	v_mfma_f32_16x16x32_bf16 v[54:57], v[166:169], v[150:153], v[54:57]
	v_mfma_f32_16x16x32_bf16 v[22:25], v[162:165], v[150:153], v[22:25]
	global_load_lds_dwordx4 v194, s[42:43]
	s_add_u32 s94, s94, 64
	s_addc_u32 s95, s95, 0
	s_add_u32 s42, s42, 64
	s_addc_u32 s43, s43, 0
	v_mfma_f32_16x16x32_bf16 v[114:117], v[174:177], v[146:149], v[114:117]
	v_mfma_f32_16x16x32_bf16 v[82:85], v[170:173], v[146:149], v[82:85]
	v_mfma_f32_16x16x32_bf16 v[50:53], v[166:169], v[146:149], v[50:53]
	v_mfma_f32_16x16x32_bf16 v[18:21], v[162:165], v[146:149], v[18:21]
	s_waitcnt lgkmcnt(0)
	v_mfma_f32_16x16x32_bf16 v[110:113], v[174:177], v[234:237], v[110:113]
	s_add_i32 s24, s31, 0xffff8000
	s_and_b32 s24, s24, 0x10000
	v_add_u32_e32 v189, s24, v231
	v_add_u32_e32 v226, s24, v232
	ds_read_b128 v[158:161], v226
	v_mfma_f32_16x16x32_bf16 v[78:81], v[170:173], v[234:237], v[78:81]
	ds_read_b128 v[154:157], v226 offset:1024
	v_mfma_f32_16x16x32_bf16 v[46:49], v[166:169], v[234:237], v[46:49]
	ds_read_b128 v[150:153], v226 offset:2048
	v_mfma_f32_16x16x32_bf16 v[14:17], v[162:165], v[234:237], v[14:17]
	ds_read_b128 v[146:149], v226 offset:3072
	v_mfma_f32_16x16x32_bf16 v[106:109], v[174:177], v[238:241], v[106:109]
	ds_read_b128 v[130:133], v189
	v_mfma_f32_16x16x32_bf16 v[74:77], v[170:173], v[238:241], v[74:77]
	ds_read_b128 v[134:137], v189 offset:1024
	v_mfma_f32_16x16x32_bf16 v[42:45], v[166:169], v[238:241], v[42:45]
	ds_read_b128 v[138:141], v189 offset:2048
	v_mfma_f32_16x16x32_bf16 v[10:13], v[162:165], v[238:241], v[10:13]
	ds_read_b128 v[142:145], v189 offset:3072
	s_add_i32 s30, s30, 2
	s_add_u32 s20, s20, 0x80
	s_addc_u32 s21, s21, 0
	s_add_i32 s31, s31, 0x10000
	v_mfma_f32_16x16x32_bf16 v[102:105], v[174:177], v[182:185], v[102:105]
	v_mfma_f32_16x16x32_bf16 v[70:73], v[170:173], v[182:185], v[70:73]
	v_mfma_f32_16x16x32_bf16 v[38:41], v[166:169], v[182:185], v[38:41]
	v_mfma_f32_16x16x32_bf16 v[6:9], v[162:165], v[182:185], v[6:9]
	v_mfma_f32_16x16x32_bf16 v[94:97], v[174:177], v[178:181], v[94:97]
	v_mfma_f32_16x16x32_bf16 v[62:65], v[170:173], v[178:181], v[62:65]
	v_mfma_f32_16x16x32_bf16 v[30:33], v[166:169], v[178:181], v[30:33]
	v_mfma_f32_16x16x32_bf16 v[2:5], v[162:165], v[178:181], v[2:5]
	s_cmp_lt_u32 s30, 28
	s_cbranch_scc1 .Lgf_G1x_top
	s_waitcnt vmcnt(4)
	s_waitcnt lgkmcnt(0)
	s_barrier
	v_mfma_f32_16x16x32_bf16 v[126:129], v[130:133], v[158:161], v[126:129]
	v_mfma_f32_16x16x32_bf16 v[98:101], v[134:137], v[158:161], v[98:101]
	s_add_i32 s28, s31, 0xfffe8000
	s_and_b32 s34, s28, 0x10000
	v_add_u32_e32 v170, s34, v233
	ds_read_b128 v[162:165], v170
	v_mfma_f32_16x16x32_bf16 v[66:69], v[138:141], v[158:161], v[66:69]
	ds_read_b128 v[166:169], v170 offset:1024
	v_mfma_f32_16x16x32_bf16 v[34:37], v[142:145], v[158:161], v[34:37]
	ds_read_b128 v[234:237], v170 offset:2048
	v_mfma_f32_16x16x32_bf16 v[122:125], v[130:133], v[154:157], v[122:125]
	ds_read_b128 v[238:241], v170 offset:3072
	s_and_b32 s40, s31, 0x18000
	s_add_i32 s40, s40, s69
	s_mov_b32 m0, s40
	v_mfma_f32_16x16x32_bf16 v[90:93], v[134:137], v[154:157], v[90:93]
	global_load_lds_dwordx4 v188, s[94:95]
	s_add_i32 m0, s40, 0x2000
	v_mfma_f32_16x16x32_bf16 v[58:61], v[138:141], v[154:157], v[58:61]
	v_mfma_f32_16x16x32_bf16 v[26:29], v[142:145], v[154:157], v[26:29]
	global_load_lds_dwordx4 v190, s[94:95]
	s_add_i32 m0, s40, 0x4000
	v_mfma_f32_16x16x32_bf16 v[118:121], v[130:133], v[150:153], v[118:121]
	v_mfma_f32_16x16x32_bf16 v[86:89], v[134:137], v[150:153], v[86:89]
	global_load_lds_dwordx4 v192, s[42:43]
	s_add_i32 m0, s40, 0x6000
	v_mfma_f32_16x16x32_bf16 v[54:57], v[138:141], v[150:153], v[54:57]
	v_mfma_f32_16x16x32_bf16 v[22:25], v[142:145], v[150:153], v[22:25]
	global_load_lds_dwordx4 v194, s[42:43]
	s_add_u32 s94, s94, 64
	s_addc_u32 s95, s95, 0
	s_add_u32 s42, s42, 64
	s_addc_u32 s43, s43, 0
	v_mfma_f32_16x16x32_bf16 v[114:117], v[130:133], v[146:149], v[114:117]
	v_mfma_f32_16x16x32_bf16 v[82:85], v[134:137], v[146:149], v[82:85]
	v_mfma_f32_16x16x32_bf16 v[50:53], v[138:141], v[146:149], v[50:53]
	v_mfma_f32_16x16x32_bf16 v[18:21], v[142:145], v[146:149], v[18:21]
	s_waitcnt lgkmcnt(0)
	v_mfma_f32_16x16x32_bf16 v[110:113], v[130:133], v[162:165], v[110:113]
	s_add_i32 s28, s31, 0xffff0000
	s_and_b32 s35, s28, 0x18000
	v_add_u32_e32 v189, s35, v231
	v_add_u32_e32 v226, s35, v232
	ds_read_b128 v[158:161], v226
	v_mfma_f32_16x16x32_bf16 v[78:81], v[134:137], v[162:165], v[78:81]
	ds_read_b128 v[154:157], v226 offset:1024
	v_mfma_f32_16x16x32_bf16 v[46:49], v[138:141], v[162:165], v[46:49]
	ds_read_b128 v[150:153], v226 offset:2048
	v_mfma_f32_16x16x32_bf16 v[14:17], v[142:145], v[162:165], v[14:17]
	ds_read_b128 v[146:149], v226 offset:3072
	v_mfma_f32_16x16x32_bf16 v[106:109], v[130:133], v[166:169], v[106:109]
	ds_read_b128 v[174:177], v189
	v_mfma_f32_16x16x32_bf16 v[74:77], v[134:137], v[166:169], v[74:77]
	ds_read_b128 v[170:173], v189 offset:1024
	v_mfma_f32_16x16x32_bf16 v[42:45], v[138:141], v[166:169], v[42:45]
	ds_read_b128 v[162:165], v189 offset:3072
	v_mfma_f32_16x16x32_bf16 v[10:13], v[142:145], v[166:169], v[10:13]
	ds_read_b128 v[166:169], v189 offset:2048
	v_mfma_f32_16x16x32_bf16 v[102:105], v[130:133], v[234:237], v[102:105]
	v_mfma_f32_16x16x32_bf16 v[70:73], v[134:137], v[234:237], v[70:73]
	v_mfma_f32_16x16x32_bf16 v[38:41], v[138:141], v[234:237], v[38:41]
	v_mfma_f32_16x16x32_bf16 v[6:9], v[142:145], v[234:237], v[6:9]
	v_mfma_f32_16x16x32_bf16 v[94:97], v[130:133], v[238:241], v[94:97]
	v_mfma_f32_16x16x32_bf16 v[62:65], v[134:137], v[238:241], v[62:65]
	v_mfma_f32_16x16x32_bf16 v[30:33], v[138:141], v[238:241], v[30:33]
	v_mfma_f32_16x16x32_bf16 v[2:5], v[142:145], v[238:241], v[2:5]
	s_waitcnt vmcnt(4)
	s_waitcnt lgkmcnt(0)
	s_barrier
	v_mfma_f32_16x16x32_bf16 v[126:129], v[174:177], v[158:161], v[126:129]
	v_mfma_f32_16x16x32_bf16 v[98:101], v[170:173], v[158:161], v[98:101]
	v_add_u32_e32 v226, s35, v233
	ds_read_b128 v[234:237], v226
	v_mfma_f32_16x16x32_bf16 v[66:69], v[166:169], v[158:161], v[66:69]
	ds_read_b128 v[238:241], v226 offset:1024
	v_mfma_f32_16x16x32_bf16 v[34:37], v[162:165], v[158:161], v[34:37]
	ds_read_b128 v[182:185], v226 offset:2048
	v_mfma_f32_16x16x32_bf16 v[122:125], v[174:177], v[154:157], v[122:125]
	ds_read_b128 v[178:181], v226 offset:3072
	v_mfma_f32_16x16x32_bf16 v[90:93], v[170:173], v[154:157], v[90:93]
	v_mfma_f32_16x16x32_bf16 v[58:61], v[166:169], v[154:157], v[58:61]
	v_mfma_f32_16x16x32_bf16 v[26:29], v[162:165], v[154:157], v[26:29]
	v_mfma_f32_16x16x32_bf16 v[118:121], v[174:177], v[150:153], v[118:121]
	v_mfma_f32_16x16x32_bf16 v[86:89], v[170:173], v[150:153], v[86:89]
	v_mfma_f32_16x16x32_bf16 v[54:57], v[166:169], v[150:153], v[54:57]
	v_mfma_f32_16x16x32_bf16 v[22:25], v[162:165], v[150:153], v[22:25]
	v_mfma_f32_16x16x32_bf16 v[114:117], v[174:177], v[146:149], v[114:117]
	v_mfma_f32_16x16x32_bf16 v[82:85], v[170:173], v[146:149], v[82:85]
	v_mfma_f32_16x16x32_bf16 v[50:53], v[166:169], v[146:149], v[50:53]
	v_mfma_f32_16x16x32_bf16 v[18:21], v[162:165], v[146:149], v[18:21]
	s_waitcnt lgkmcnt(0)
	v_mfma_f32_16x16x32_bf16 v[110:113], v[174:177], v[234:237], v[110:113]
	s_add_i32 s24, s31, 0xffff8000
	s_and_b32 s24, s24, 0x10000
	v_add_u32_e32 v189, s24, v231
	v_add_u32_e32 v226, s24, v232
	ds_read_b128 v[158:161], v226
	v_mfma_f32_16x16x32_bf16 v[78:81], v[170:173], v[234:237], v[78:81]
	ds_read_b128 v[154:157], v226 offset:1024
	v_mfma_f32_16x16x32_bf16 v[46:49], v[166:169], v[234:237], v[46:49]
	ds_read_b128 v[150:153], v226 offset:2048
	v_mfma_f32_16x16x32_bf16 v[14:17], v[162:165], v[234:237], v[14:17]
	ds_read_b128 v[146:149], v226 offset:3072
	v_mfma_f32_16x16x32_bf16 v[106:109], v[174:177], v[238:241], v[106:109]
	ds_read_b128 v[130:133], v189
	v_mfma_f32_16x16x32_bf16 v[74:77], v[170:173], v[238:241], v[74:77]
	ds_read_b128 v[134:137], v189 offset:1024
	v_mfma_f32_16x16x32_bf16 v[42:45], v[166:169], v[238:241], v[42:45]
	ds_read_b128 v[138:141], v189 offset:2048
	v_mfma_f32_16x16x32_bf16 v[10:13], v[162:165], v[238:241], v[10:13]
	ds_read_b128 v[142:145], v189 offset:3072
	s_add_i32 s30, s30, 2
	s_add_u32 s20, s20, 0x80
	s_addc_u32 s21, s21, 0
	s_add_i32 s31, s31, 0x10000
	v_mfma_f32_16x16x32_bf16 v[102:105], v[174:177], v[182:185], v[102:105]
	v_mfma_f32_16x16x32_bf16 v[70:73], v[170:173], v[182:185], v[70:73]
	v_mfma_f32_16x16x32_bf16 v[38:41], v[166:169], v[182:185], v[38:41]
	v_mfma_f32_16x16x32_bf16 v[6:9], v[162:165], v[182:185], v[6:9]
	v_mfma_f32_16x16x32_bf16 v[94:97], v[174:177], v[178:181], v[94:97]
	v_mfma_f32_16x16x32_bf16 v[62:65], v[170:173], v[178:181], v[62:65]
	v_mfma_f32_16x16x32_bf16 v[30:33], v[166:169], v[178:181], v[30:33]
	v_mfma_f32_16x16x32_bf16 v[2:5], v[162:165], v[178:181], v[2:5]
	s_waitcnt vmcnt(0)
	s_waitcnt lgkmcnt(0)
	s_barrier
	v_mfma_f32_16x16x32_bf16 v[126:129], v[130:133], v[158:161], v[126:129]
	v_mfma_f32_16x16x32_bf16 v[98:101], v[134:137], v[158:161], v[98:101]
	s_add_i32 s28, s31, 0xfffe8000
	s_and_b32 s34, s28, 0x10000
	v_add_u32_e32 v170, s34, v233
	ds_read_b128 v[162:165], v170
	v_mfma_f32_16x16x32_bf16 v[66:69], v[138:141], v[158:161], v[66:69]
	ds_read_b128 v[166:169], v170 offset:1024
	v_mfma_f32_16x16x32_bf16 v[34:37], v[142:145], v[158:161], v[34:37]
	ds_read_b128 v[234:237], v170 offset:2048
	v_mfma_f32_16x16x32_bf16 v[122:125], v[130:133], v[154:157], v[122:125]
	ds_read_b128 v[238:241], v170 offset:3072
	v_mfma_f32_16x16x32_bf16 v[90:93], v[134:137], v[154:157], v[90:93]
	v_mfma_f32_16x16x32_bf16 v[58:61], v[138:141], v[154:157], v[58:61]
	v_mfma_f32_16x16x32_bf16 v[26:29], v[142:145], v[154:157], v[26:29]
	v_mfma_f32_16x16x32_bf16 v[118:121], v[130:133], v[150:153], v[118:121]
	v_mfma_f32_16x16x32_bf16 v[86:89], v[134:137], v[150:153], v[86:89]
	v_mfma_f32_16x16x32_bf16 v[54:57], v[138:141], v[150:153], v[54:57]
	v_mfma_f32_16x16x32_bf16 v[22:25], v[142:145], v[150:153], v[22:25]
	v_mfma_f32_16x16x32_bf16 v[114:117], v[130:133], v[146:149], v[114:117]
	v_mfma_f32_16x16x32_bf16 v[82:85], v[134:137], v[146:149], v[82:85]
	v_mfma_f32_16x16x32_bf16 v[50:53], v[138:141], v[146:149], v[50:53]
	v_mfma_f32_16x16x32_bf16 v[18:21], v[142:145], v[146:149], v[18:21]
	s_waitcnt lgkmcnt(0)
	v_mfma_f32_16x16x32_bf16 v[110:113], v[130:133], v[162:165], v[110:113]
	s_add_i32 s28, s31, 0xffff0000
	s_and_b32 s35, s28, 0x18000
	v_add_u32_e32 v189, s35, v231
	v_add_u32_e32 v226, s35, v232
	ds_read_b128 v[158:161], v226
	v_mfma_f32_16x16x32_bf16 v[78:81], v[134:137], v[162:165], v[78:81]
	ds_read_b128 v[154:157], v226 offset:1024
	v_mfma_f32_16x16x32_bf16 v[46:49], v[138:141], v[162:165], v[46:49]
	ds_read_b128 v[150:153], v226 offset:2048
	v_mfma_f32_16x16x32_bf16 v[14:17], v[142:145], v[162:165], v[14:17]
	ds_read_b128 v[146:149], v226 offset:3072
	v_mfma_f32_16x16x32_bf16 v[106:109], v[130:133], v[166:169], v[106:109]
	ds_read_b128 v[174:177], v189
	v_mfma_f32_16x16x32_bf16 v[74:77], v[134:137], v[166:169], v[74:77]
	ds_read_b128 v[170:173], v189 offset:1024
	v_mfma_f32_16x16x32_bf16 v[42:45], v[138:141], v[166:169], v[42:45]
	ds_read_b128 v[162:165], v189 offset:3072
	v_mfma_f32_16x16x32_bf16 v[10:13], v[142:145], v[166:169], v[10:13]
	ds_read_b128 v[166:169], v189 offset:2048
	v_mfma_f32_16x16x32_bf16 v[102:105], v[130:133], v[234:237], v[102:105]
	v_mfma_f32_16x16x32_bf16 v[70:73], v[134:137], v[234:237], v[70:73]
	v_mfma_f32_16x16x32_bf16 v[38:41], v[138:141], v[234:237], v[38:41]
	v_mfma_f32_16x16x32_bf16 v[6:9], v[142:145], v[234:237], v[6:9]
	v_mfma_f32_16x16x32_bf16 v[94:97], v[130:133], v[238:241], v[94:97]
	v_mfma_f32_16x16x32_bf16 v[62:65], v[134:137], v[238:241], v[62:65]
	v_mfma_f32_16x16x32_bf16 v[30:33], v[138:141], v[238:241], v[30:33]
	v_mfma_f32_16x16x32_bf16 v[2:5], v[142:145], v[238:241], v[2:5]
	s_waitcnt vmcnt(0)
	s_waitcnt lgkmcnt(0)
	s_barrier
	v_mfma_f32_16x16x32_bf16 v[126:129], v[174:177], v[158:161], v[126:129]
	v_mfma_f32_16x16x32_bf16 v[98:101], v[170:173], v[158:161], v[98:101]
	v_add_u32_e32 v226, s35, v233
	ds_read_b128 v[234:237], v226
	v_mfma_f32_16x16x32_bf16 v[66:69], v[166:169], v[158:161], v[66:69]
	ds_read_b128 v[238:241], v226 offset:1024
	v_mfma_f32_16x16x32_bf16 v[34:37], v[162:165], v[158:161], v[34:37]
	ds_read_b128 v[182:185], v226 offset:2048
	v_mfma_f32_16x16x32_bf16 v[122:125], v[174:177], v[154:157], v[122:125]
	ds_read_b128 v[178:181], v226 offset:3072
	v_mfma_f32_16x16x32_bf16 v[90:93], v[170:173], v[154:157], v[90:93]
	v_mfma_f32_16x16x32_bf16 v[58:61], v[166:169], v[154:157], v[58:61]
	v_mfma_f32_16x16x32_bf16 v[26:29], v[162:165], v[154:157], v[26:29]
	v_mfma_f32_16x16x32_bf16 v[118:121], v[174:177], v[150:153], v[118:121]
	v_mfma_f32_16x16x32_bf16 v[86:89], v[170:173], v[150:153], v[86:89]
	v_mfma_f32_16x16x32_bf16 v[54:57], v[166:169], v[150:153], v[54:57]
	v_mfma_f32_16x16x32_bf16 v[22:25], v[162:165], v[150:153], v[22:25]
	v_mfma_f32_16x16x32_bf16 v[114:117], v[174:177], v[146:149], v[114:117]
	v_mfma_f32_16x16x32_bf16 v[82:85], v[170:173], v[146:149], v[82:85]
	v_mfma_f32_16x16x32_bf16 v[50:53], v[166:169], v[146:149], v[50:53]
	v_mfma_f32_16x16x32_bf16 v[18:21], v[162:165], v[146:149], v[18:21]
	s_waitcnt lgkmcnt(0)
	v_mfma_f32_16x16x32_bf16 v[110:113], v[174:177], v[234:237], v[110:113]
	v_mfma_f32_16x16x32_bf16 v[78:81], v[170:173], v[234:237], v[78:81]
	v_mfma_f32_16x16x32_bf16 v[46:49], v[166:169], v[234:237], v[46:49]
	v_mfma_f32_16x16x32_bf16 v[14:17], v[162:165], v[234:237], v[14:17]
	v_mfma_f32_16x16x32_bf16 v[106:109], v[174:177], v[238:241], v[106:109]
	v_mfma_f32_16x16x32_bf16 v[74:77], v[170:173], v[238:241], v[74:77]
	v_mfma_f32_16x16x32_bf16 v[42:45], v[166:169], v[238:241], v[42:45]
	v_mfma_f32_16x16x32_bf16 v[10:13], v[162:165], v[238:241], v[10:13]
	s_add_i32 s30, s30, 2
	s_add_u32 s20, s20, 0x80
	s_addc_u32 s21, s21, 0
	s_add_i32 s31, s31, 0x10000
	v_mfma_f32_16x16x32_bf16 v[102:105], v[174:177], v[182:185], v[102:105]
	v_mfma_f32_16x16x32_bf16 v[70:73], v[170:173], v[182:185], v[70:73]
	v_mfma_f32_16x16x32_bf16 v[38:41], v[166:169], v[182:185], v[38:41]
	v_mfma_f32_16x16x32_bf16 v[6:9], v[162:165], v[182:185], v[6:9]
	v_mfma_f32_16x16x32_bf16 v[94:97], v[174:177], v[178:181], v[94:97]
	v_mfma_f32_16x16x32_bf16 v[62:65], v[170:173], v[178:181], v[62:65]
	v_mfma_f32_16x16x32_bf16 v[30:33], v[166:169], v[178:181], v[30:33]
	v_mfma_f32_16x16x32_bf16 v[2:5], v[162:165], v[178:181], v[2:5]
	s_branch .LBB0_659
.Lgr_G1x_entry:
	s_waitcnt vmcnt(4)
	s_waitcnt lgkmcnt(0)
	s_barrier
	v_mfma_f32_16x16x32_bf16 v[126:129], v[130:133], v[158:161], v[126:129]
	v_mfma_f32_16x16x32_bf16 v[98:101], v[134:137], v[158:161], v[98:101]
	s_add_i32 s28, s31, 0xfffe8000
	s_and_b32 s34, s28, 0x10000
	v_add_u32_e32 v170, s34, v233
	ds_read_b128 v[162:165], v170
	v_mfma_f32_16x16x32_bf16 v[66:69], v[138:141], v[158:161], v[66:69]
	ds_read_b128 v[166:169], v170 offset:1024
	v_mfma_f32_16x16x32_bf16 v[34:37], v[142:145], v[158:161], v[34:37]
	ds_read_b128 v[234:237], v170 offset:2048
	v_mfma_f32_16x16x32_bf16 v[122:125], v[130:133], v[154:157], v[122:125]
	ds_read_b128 v[238:241], v170 offset:3072
	s_and_b32 s40, s31, 0x18000
	s_add_i32 s40, s40, s69
	s_mov_b32 m0, s40
	v_mfma_f32_16x16x32_bf16 v[90:93], v[134:137], v[154:157], v[90:93]
	global_load_lds_dwordx4 v188, s[94:95]
	s_add_i32 m0, s40, 0x2000
	v_mfma_f32_16x16x32_bf16 v[58:61], v[138:141], v[154:157], v[58:61]
	v_mfma_f32_16x16x32_bf16 v[26:29], v[142:145], v[154:157], v[26:29]
	global_load_lds_dwordx4 v190, s[94:95]
	s_add_i32 m0, s40, 0x4000
	v_mfma_f32_16x16x32_bf16 v[118:121], v[130:133], v[150:153], v[118:121]
	v_mfma_f32_16x16x32_bf16 v[86:89], v[134:137], v[150:153], v[86:89]
	global_load_lds_dwordx4 v192, s[42:43]
	s_add_i32 m0, s40, 0x6000
	v_mfma_f32_16x16x32_bf16 v[54:57], v[138:141], v[150:153], v[54:57]
	v_mfma_f32_16x16x32_bf16 v[22:25], v[142:145], v[150:153], v[22:25]
	global_load_lds_dwordx4 v194, s[42:43]
	s_add_u32 s94, s94, 64
	s_addc_u32 s95, s95, 0
	s_add_u32 s42, s42, 64
	s_addc_u32 s43, s43, 0
	v_mfma_f32_16x16x32_bf16 v[114:117], v[130:133], v[146:149], v[114:117]
	v_mfma_f32_16x16x32_bf16 v[82:85], v[134:137], v[146:149], v[82:85]
	v_mfma_f32_16x16x32_bf16 v[50:53], v[138:141], v[146:149], v[50:53]
	v_mfma_f32_16x16x32_bf16 v[18:21], v[142:145], v[146:149], v[18:21]
	s_waitcnt vmcnt(4)
	s_waitcnt lgkmcnt(0)
	s_barrier
	v_mfma_f32_16x16x32_bf16 v[110:113], v[130:133], v[162:165], v[110:113]
	s_add_i32 s28, s31, 0xffff0000
	s_and_b32 s35, s28, 0x18000
	v_add_u32_e32 v189, s35, v231
	v_add_u32_e32 v226, s35, v232
	ds_read_b128 v[158:161], v226
	v_mfma_f32_16x16x32_bf16 v[78:81], v[134:137], v[162:165], v[78:81]
	ds_read_b128 v[154:157], v226 offset:1024
	v_mfma_f32_16x16x32_bf16 v[46:49], v[138:141], v[162:165], v[46:49]
	ds_read_b128 v[150:153], v226 offset:2048
	v_mfma_f32_16x16x32_bf16 v[14:17], v[142:145], v[162:165], v[14:17]
	ds_read_b128 v[146:149], v226 offset:3072
	v_mfma_f32_16x16x32_bf16 v[106:109], v[130:133], v[166:169], v[106:109]
	ds_read_b128 v[174:177], v189
	v_mfma_f32_16x16x32_bf16 v[74:77], v[134:137], v[166:169], v[74:77]
	ds_read_b128 v[170:173], v189 offset:1024
	v_mfma_f32_16x16x32_bf16 v[42:45], v[138:141], v[166:169], v[42:45]
	ds_read_b128 v[162:165], v189 offset:3072
	v_mfma_f32_16x16x32_bf16 v[10:13], v[142:145], v[166:169], v[10:13]
	ds_read_b128 v[166:169], v189 offset:2048
	v_mfma_f32_16x16x32_bf16 v[102:105], v[130:133], v[234:237], v[102:105]
	v_mfma_f32_16x16x32_bf16 v[70:73], v[134:137], v[234:237], v[70:73]
	v_mfma_f32_16x16x32_bf16 v[38:41], v[138:141], v[234:237], v[38:41]
	v_mfma_f32_16x16x32_bf16 v[6:9], v[142:145], v[234:237], v[6:9]
	v_mfma_f32_16x16x32_bf16 v[94:97], v[130:133], v[238:241], v[94:97]
	v_mfma_f32_16x16x32_bf16 v[62:65], v[134:137], v[238:241], v[62:65]
	v_mfma_f32_16x16x32_bf16 v[30:33], v[138:141], v[238:241], v[30:33]
	v_mfma_f32_16x16x32_bf16 v[2:5], v[142:145], v[238:241], v[2:5]
	s_waitcnt lgkmcnt(0)
	v_mfma_f32_16x16x32_bf16 v[126:129], v[174:177], v[158:161], v[126:129]
	v_mfma_f32_16x16x32_bf16 v[98:101], v[170:173], v[158:161], v[98:101]
	v_add_u32_e32 v226, s35, v233
	ds_read_b128 v[234:237], v226
	v_mfma_f32_16x16x32_bf16 v[66:69], v[166:169], v[158:161], v[66:69]
	ds_read_b128 v[238:241], v226 offset:1024
	v_mfma_f32_16x16x32_bf16 v[34:37], v[162:165], v[158:161], v[34:37]
	ds_read_b128 v[182:185], v226 offset:2048
	v_mfma_f32_16x16x32_bf16 v[122:125], v[174:177], v[154:157], v[122:125]
	ds_read_b128 v[178:181], v226 offset:3072
	s_add_i32 s40, s34, s69
	s_mov_b32 m0, s40
	v_mfma_f32_16x16x32_bf16 v[90:93], v[170:173], v[154:157], v[90:93]
	global_load_lds_dwordx4 v188, s[94:95]
	s_add_i32 m0, s40, 0x2000
	v_mfma_f32_16x16x32_bf16 v[58:61], v[166:169], v[154:157], v[58:61]
	v_mfma_f32_16x16x32_bf16 v[26:29], v[162:165], v[154:157], v[26:29]
	global_load_lds_dwordx4 v190, s[94:95]
	s_add_i32 m0, s40, 0x4000
	v_mfma_f32_16x16x32_bf16 v[118:121], v[174:177], v[150:153], v[118:121]
	v_mfma_f32_16x16x32_bf16 v[86:89], v[170:173], v[150:153], v[86:89]
	global_load_lds_dwordx4 v192, s[42:43]
	s_add_i32 m0, s40, 0x6000
	v_mfma_f32_16x16x32_bf16 v[54:57], v[166:169], v[150:153], v[54:57]
	v_mfma_f32_16x16x32_bf16 v[22:25], v[162:165], v[150:153], v[22:25]
	global_load_lds_dwordx4 v194, s[42:43]
	s_add_u32 s94, s94, 64
	s_addc_u32 s95, s95, 0
	s_add_u32 s42, s42, 64
	s_addc_u32 s43, s43, 0
	v_mfma_f32_16x16x32_bf16 v[114:117], v[174:177], v[146:149], v[114:117]
	v_mfma_f32_16x16x32_bf16 v[82:85], v[170:173], v[146:149], v[82:85]
	v_mfma_f32_16x16x32_bf16 v[50:53], v[166:169], v[146:149], v[50:53]
	v_mfma_f32_16x16x32_bf16 v[18:21], v[162:165], v[146:149], v[18:21]
.Lgr_G1x_top:
	s_waitcnt vmcnt(4)
	s_waitcnt lgkmcnt(0)
	s_barrier
	v_mfma_f32_16x16x32_bf16 v[110:113], v[174:177], v[234:237], v[110:113]
	s_add_i32 s24, s31, 0xffff8000
	s_and_b32 s24, s24, 0x10000
	v_add_u32_e32 v189, s24, v231
	v_add_u32_e32 v226, s24, v232
	ds_read_b128 v[158:161], v226
	v_mfma_f32_16x16x32_bf16 v[78:81], v[170:173], v[234:237], v[78:81]
	ds_read_b128 v[154:157], v226 offset:1024
	v_mfma_f32_16x16x32_bf16 v[46:49], v[166:169], v[234:237], v[46:49]
	ds_read_b128 v[150:153], v226 offset:2048
	v_mfma_f32_16x16x32_bf16 v[14:17], v[162:165], v[234:237], v[14:17]
	ds_read_b128 v[146:149], v226 offset:3072
	v_mfma_f32_16x16x32_bf16 v[106:109], v[174:177], v[238:241], v[106:109]
	ds_read_b128 v[130:133], v189
	v_mfma_f32_16x16x32_bf16 v[74:77], v[170:173], v[238:241], v[74:77]
	ds_read_b128 v[134:137], v189 offset:1024
	v_mfma_f32_16x16x32_bf16 v[42:45], v[166:169], v[238:241], v[42:45]
	ds_read_b128 v[138:141], v189 offset:2048
	v_mfma_f32_16x16x32_bf16 v[10:13], v[162:165], v[238:241], v[10:13]
	ds_read_b128 v[142:145], v189 offset:3072
	s_add_i32 s30, s30, 2
	s_add_u32 s20, s20, 0x80
	s_addc_u32 s21, s21, 0
	s_add_i32 s31, s31, 0x10000
	v_mfma_f32_16x16x32_bf16 v[102:105], v[174:177], v[182:185], v[102:105]
	v_mfma_f32_16x16x32_bf16 v[70:73], v[170:173], v[182:185], v[70:73]
	v_mfma_f32_16x16x32_bf16 v[38:41], v[166:169], v[182:185], v[38:41]
	v_mfma_f32_16x16x32_bf16 v[6:9], v[162:165], v[182:185], v[6:9]
	v_mfma_f32_16x16x32_bf16 v[94:97], v[174:177], v[178:181], v[94:97]
	v_mfma_f32_16x16x32_bf16 v[62:65], v[170:173], v[178:181], v[62:65]
	v_mfma_f32_16x16x32_bf16 v[30:33], v[166:169], v[178:181], v[30:33]
	v_mfma_f32_16x16x32_bf16 v[2:5], v[162:165], v[178:181], v[2:5]
	s_cmp_lt_u32 s30, 28
	s_cbranch_scc0 .Lgr_G1x_tail
	s_waitcnt lgkmcnt(0)
	v_mfma_f32_16x16x32_bf16 v[126:129], v[130:133], v[158:161], v[126:129]
	v_mfma_f32_16x16x32_bf16 v[98:101], v[134:137], v[158:161], v[98:101]
	s_add_i32 s28, s31, 0xfffe8000
	s_and_b32 s34, s28, 0x10000
	v_add_u32_e32 v170, s34, v233
	ds_read_b128 v[162:165], v170
	v_mfma_f32_16x16x32_bf16 v[66:69], v[138:141], v[158:161], v[66:69]
	ds_read_b128 v[166:169], v170 offset:1024
	v_mfma_f32_16x16x32_bf16 v[34:37], v[142:145], v[158:161], v[34:37]
	ds_read_b128 v[234:237], v170 offset:2048
	v_mfma_f32_16x16x32_bf16 v[122:125], v[130:133], v[154:157], v[122:125]
	ds_read_b128 v[238:241], v170 offset:3072
	s_and_b32 s40, s31, 0x18000
	s_add_i32 s40, s40, s69
	s_mov_b32 m0, s40
	v_mfma_f32_16x16x32_bf16 v[90:93], v[134:137], v[154:157], v[90:93]
	global_load_lds_dwordx4 v188, s[94:95]
	s_add_i32 m0, s40, 0x2000
	v_mfma_f32_16x16x32_bf16 v[58:61], v[138:141], v[154:157], v[58:61]
	v_mfma_f32_16x16x32_bf16 v[26:29], v[142:145], v[154:157], v[26:29]
	global_load_lds_dwordx4 v190, s[94:95]
	s_add_i32 m0, s40, 0x4000
	v_mfma_f32_16x16x32_bf16 v[118:121], v[130:133], v[150:153], v[118:121]
	v_mfma_f32_16x16x32_bf16 v[86:89], v[134:137], v[150:153], v[86:89]
	global_load_lds_dwordx4 v192, s[42:43]
	s_add_i32 m0, s40, 0x6000
	v_mfma_f32_16x16x32_bf16 v[54:57], v[138:141], v[150:153], v[54:57]
	v_mfma_f32_16x16x32_bf16 v[22:25], v[142:145], v[150:153], v[22:25]
	global_load_lds_dwordx4 v194, s[42:43]
	s_add_u32 s94, s94, 64
	s_addc_u32 s95, s95, 0
	s_add_u32 s42, s42, 64
	s_addc_u32 s43, s43, 0
	v_mfma_f32_16x16x32_bf16 v[114:117], v[130:133], v[146:149], v[114:117]
	v_mfma_f32_16x16x32_bf16 v[82:85], v[134:137], v[146:149], v[82:85]
	v_mfma_f32_16x16x32_bf16 v[50:53], v[138:141], v[146:149], v[50:53]
	v_mfma_f32_16x16x32_bf16 v[18:21], v[142:145], v[146:149], v[18:21]
	s_waitcnt vmcnt(4)
	s_waitcnt lgkmcnt(0)
	s_barrier
	v_mfma_f32_16x16x32_bf16 v[110:113], v[130:133], v[162:165], v[110:113]
	s_add_i32 s28, s31, 0xffff0000
	s_and_b32 s35, s28, 0x18000
	v_add_u32_e32 v189, s35, v231
	v_add_u32_e32 v226, s35, v232
	ds_read_b128 v[158:161], v226
	v_mfma_f32_16x16x32_bf16 v[78:81], v[134:137], v[162:165], v[78:81]
	ds_read_b128 v[154:157], v226 offset:1024
	v_mfma_f32_16x16x32_bf16 v[46:49], v[138:141], v[162:165], v[46:49]
	ds_read_b128 v[150:153], v226 offset:2048
	v_mfma_f32_16x16x32_bf16 v[14:17], v[142:145], v[162:165], v[14:17]
	ds_read_b128 v[146:149], v226 offset:3072
	v_mfma_f32_16x16x32_bf16 v[106:109], v[130:133], v[166:169], v[106:109]
	ds_read_b128 v[174:177], v189
	v_mfma_f32_16x16x32_bf16 v[74:77], v[134:137], v[166:169], v[74:77]
	ds_read_b128 v[170:173], v189 offset:1024
	v_mfma_f32_16x16x32_bf16 v[42:45], v[138:141], v[166:169], v[42:45]
	ds_read_b128 v[162:165], v189 offset:3072
	v_mfma_f32_16x16x32_bf16 v[10:13], v[142:145], v[166:169], v[10:13]
	ds_read_b128 v[166:169], v189 offset:2048
	v_mfma_f32_16x16x32_bf16 v[102:105], v[130:133], v[234:237], v[102:105]
	v_mfma_f32_16x16x32_bf16 v[70:73], v[134:137], v[234:237], v[70:73]
	v_mfma_f32_16x16x32_bf16 v[38:41], v[138:141], v[234:237], v[38:41]
	v_mfma_f32_16x16x32_bf16 v[6:9], v[142:145], v[234:237], v[6:9]
	v_mfma_f32_16x16x32_bf16 v[94:97], v[130:133], v[238:241], v[94:97]
	v_mfma_f32_16x16x32_bf16 v[62:65], v[134:137], v[238:241], v[62:65]
	v_mfma_f32_16x16x32_bf16 v[30:33], v[138:141], v[238:241], v[30:33]
	v_mfma_f32_16x16x32_bf16 v[2:5], v[142:145], v[238:241], v[2:5]
	s_waitcnt lgkmcnt(0)
	v_mfma_f32_16x16x32_bf16 v[126:129], v[174:177], v[158:161], v[126:129]
	v_mfma_f32_16x16x32_bf16 v[98:101], v[170:173], v[158:161], v[98:101]
	v_add_u32_e32 v226, s35, v233
	ds_read_b128 v[234:237], v226
	v_mfma_f32_16x16x32_bf16 v[66:69], v[166:169], v[158:161], v[66:69]
	ds_read_b128 v[238:241], v226 offset:1024
	v_mfma_f32_16x16x32_bf16 v[34:37], v[162:165], v[158:161], v[34:37]
	ds_read_b128 v[182:185], v226 offset:2048
	v_mfma_f32_16x16x32_bf16 v[122:125], v[174:177], v[154:157], v[122:125]
	ds_read_b128 v[178:181], v226 offset:3072
	s_add_i32 s40, s34, s69
	s_mov_b32 m0, s40
	v_mfma_f32_16x16x32_bf16 v[90:93], v[170:173], v[154:157], v[90:93]
	global_load_lds_dwordx4 v188, s[94:95]
	s_add_i32 m0, s40, 0x2000
	v_mfma_f32_16x16x32_bf16 v[58:61], v[166:169], v[154:157], v[58:61]
	v_mfma_f32_16x16x32_bf16 v[26:29], v[162:165], v[154:157], v[26:29]
	global_load_lds_dwordx4 v190, s[94:95]
	s_add_i32 m0, s40, 0x4000
	v_mfma_f32_16x16x32_bf16 v[118:121], v[174:177], v[150:153], v[118:121]
	v_mfma_f32_16x16x32_bf16 v[86:89], v[170:173], v[150:153], v[86:89]
	global_load_lds_dwordx4 v192, s[42:43]
	s_add_i32 m0, s40, 0x6000
	v_mfma_f32_16x16x32_bf16 v[54:57], v[166:169], v[150:153], v[54:57]
	v_mfma_f32_16x16x32_bf16 v[22:25], v[162:165], v[150:153], v[22:25]
	global_load_lds_dwordx4 v194, s[42:43]
	s_add_u32 s94, s94, 64
	s_addc_u32 s95, s95, 0
	s_add_u32 s42, s42, 64
	s_addc_u32 s43, s43, 0
	v_mfma_f32_16x16x32_bf16 v[114:117], v[174:177], v[146:149], v[114:117]
	v_mfma_f32_16x16x32_bf16 v[82:85], v[170:173], v[146:149], v[82:85]
	v_mfma_f32_16x16x32_bf16 v[50:53], v[166:169], v[146:149], v[50:53]
	v_mfma_f32_16x16x32_bf16 v[18:21], v[162:165], v[146:149], v[18:21]
	s_branch .Lgr_G1x_top
.Lgr_G1x_tail:
	s_waitcnt lgkmcnt(0)
	v_mfma_f32_16x16x32_bf16 v[126:129], v[130:133], v[158:161], v[126:129]
	v_mfma_f32_16x16x32_bf16 v[98:101], v[134:137], v[158:161], v[98:101]
	s_add_i32 s28, s31, 0xfffe8000
	s_and_b32 s34, s28, 0x10000
	v_add_u32_e32 v170, s34, v233
	ds_read_b128 v[162:165], v170
	v_mfma_f32_16x16x32_bf16 v[66:69], v[138:141], v[158:161], v[66:69]
	ds_read_b128 v[166:169], v170 offset:1024
	v_mfma_f32_16x16x32_bf16 v[34:37], v[142:145], v[158:161], v[34:37]
	ds_read_b128 v[234:237], v170 offset:2048
	v_mfma_f32_16x16x32_bf16 v[122:125], v[130:133], v[154:157], v[122:125]
	ds_read_b128 v[238:241], v170 offset:3072
	s_and_b32 s40, s31, 0x18000
	s_add_i32 s40, s40, s69
	s_mov_b32 m0, s40
	v_mfma_f32_16x16x32_bf16 v[90:93], v[134:137], v[154:157], v[90:93]
	global_load_lds_dwordx4 v188, s[94:95]
	s_add_i32 m0, s40, 0x2000
	v_mfma_f32_16x16x32_bf16 v[58:61], v[138:141], v[154:157], v[58:61]
	v_mfma_f32_16x16x32_bf16 v[26:29], v[142:145], v[154:157], v[26:29]
	global_load_lds_dwordx4 v190, s[94:95]
	s_add_i32 m0, s40, 0x4000
	v_mfma_f32_16x16x32_bf16 v[118:121], v[130:133], v[150:153], v[118:121]
	v_mfma_f32_16x16x32_bf16 v[86:89], v[134:137], v[150:153], v[86:89]
	global_load_lds_dwordx4 v192, s[42:43]
	s_add_i32 m0, s40, 0x6000
	v_mfma_f32_16x16x32_bf16 v[54:57], v[138:141], v[150:153], v[54:57]
	v_mfma_f32_16x16x32_bf16 v[22:25], v[142:145], v[150:153], v[22:25]
	global_load_lds_dwordx4 v194, s[42:43]
	s_add_u32 s94, s94, 64
	s_addc_u32 s95, s95, 0
	s_add_u32 s42, s42, 64
	s_addc_u32 s43, s43, 0
	v_mfma_f32_16x16x32_bf16 v[114:117], v[130:133], v[146:149], v[114:117]
	v_mfma_f32_16x16x32_bf16 v[82:85], v[134:137], v[146:149], v[82:85]
	v_mfma_f32_16x16x32_bf16 v[50:53], v[138:141], v[146:149], v[50:53]
	v_mfma_f32_16x16x32_bf16 v[18:21], v[142:145], v[146:149], v[18:21]
	s_waitcnt vmcnt(4)
	s_waitcnt lgkmcnt(0)
	s_barrier
	v_mfma_f32_16x16x32_bf16 v[110:113], v[130:133], v[162:165], v[110:113]
	s_add_i32 s28, s31, 0xffff0000
	s_and_b32 s35, s28, 0x18000
	v_add_u32_e32 v189, s35, v231
	v_add_u32_e32 v226, s35, v232
	ds_read_b128 v[158:161], v226
	v_mfma_f32_16x16x32_bf16 v[78:81], v[134:137], v[162:165], v[78:81]
	ds_read_b128 v[154:157], v226 offset:1024
	v_mfma_f32_16x16x32_bf16 v[46:49], v[138:141], v[162:165], v[46:49]
	ds_read_b128 v[150:153], v226 offset:2048
	v_mfma_f32_16x16x32_bf16 v[14:17], v[142:145], v[162:165], v[14:17]
	ds_read_b128 v[146:149], v226 offset:3072
	v_mfma_f32_16x16x32_bf16 v[106:109], v[130:133], v[166:169], v[106:109]
	ds_read_b128 v[174:177], v189
	v_mfma_f32_16x16x32_bf16 v[74:77], v[134:137], v[166:169], v[74:77]
	ds_read_b128 v[170:173], v189 offset:1024
	v_mfma_f32_16x16x32_bf16 v[42:45], v[138:141], v[166:169], v[42:45]
	ds_read_b128 v[162:165], v189 offset:3072
	v_mfma_f32_16x16x32_bf16 v[10:13], v[142:145], v[166:169], v[10:13]
	ds_read_b128 v[166:169], v189 offset:2048
	v_mfma_f32_16x16x32_bf16 v[102:105], v[130:133], v[234:237], v[102:105]
	v_mfma_f32_16x16x32_bf16 v[70:73], v[134:137], v[234:237], v[70:73]
	v_mfma_f32_16x16x32_bf16 v[38:41], v[138:141], v[234:237], v[38:41]
	v_mfma_f32_16x16x32_bf16 v[6:9], v[142:145], v[234:237], v[6:9]
	v_mfma_f32_16x16x32_bf16 v[94:97], v[130:133], v[238:241], v[94:97]
	v_mfma_f32_16x16x32_bf16 v[62:65], v[134:137], v[238:241], v[62:65]
	v_mfma_f32_16x16x32_bf16 v[30:33], v[138:141], v[238:241], v[30:33]
	v_mfma_f32_16x16x32_bf16 v[2:5], v[142:145], v[238:241], v[2:5]
	s_waitcnt lgkmcnt(0)
	v_mfma_f32_16x16x32_bf16 v[126:129], v[174:177], v[158:161], v[126:129]
	v_mfma_f32_16x16x32_bf16 v[98:101], v[170:173], v[158:161], v[98:101]
	v_add_u32_e32 v226, s35, v233
	ds_read_b128 v[234:237], v226
	v_mfma_f32_16x16x32_bf16 v[66:69], v[166:169], v[158:161], v[66:69]
	ds_read_b128 v[238:241], v226 offset:1024
	v_mfma_f32_16x16x32_bf16 v[34:37], v[162:165], v[158:161], v[34:37]
	ds_read_b128 v[182:185], v226 offset:2048
	v_mfma_f32_16x16x32_bf16 v[122:125], v[174:177], v[154:157], v[122:125]
	ds_read_b128 v[178:181], v226 offset:3072
	v_mfma_f32_16x16x32_bf16 v[90:93], v[170:173], v[154:157], v[90:93]
	v_mfma_f32_16x16x32_bf16 v[58:61], v[166:169], v[154:157], v[58:61]
	v_mfma_f32_16x16x32_bf16 v[26:29], v[162:165], v[154:157], v[26:29]
	v_mfma_f32_16x16x32_bf16 v[118:121], v[174:177], v[150:153], v[118:121]
	v_mfma_f32_16x16x32_bf16 v[86:89], v[170:173], v[150:153], v[86:89]
	v_mfma_f32_16x16x32_bf16 v[54:57], v[166:169], v[150:153], v[54:57]
	v_mfma_f32_16x16x32_bf16 v[22:25], v[162:165], v[150:153], v[22:25]
	v_mfma_f32_16x16x32_bf16 v[114:117], v[174:177], v[146:149], v[114:117]
	v_mfma_f32_16x16x32_bf16 v[82:85], v[170:173], v[146:149], v[82:85]
	v_mfma_f32_16x16x32_bf16 v[50:53], v[166:169], v[146:149], v[50:53]
	v_mfma_f32_16x16x32_bf16 v[18:21], v[162:165], v[146:149], v[18:21]
	s_waitcnt vmcnt(0)
	s_waitcnt lgkmcnt(0)
	s_barrier
	v_mfma_f32_16x16x32_bf16 v[110:113], v[174:177], v[234:237], v[110:113]
	s_add_i32 s24, s31, 0xffff8000
	s_and_b32 s24, s24, 0x10000
	v_add_u32_e32 v189, s24, v231
	v_add_u32_e32 v226, s24, v232
	ds_read_b128 v[158:161], v226
	v_mfma_f32_16x16x32_bf16 v[78:81], v[170:173], v[234:237], v[78:81]
	ds_read_b128 v[154:157], v226 offset:1024
	v_mfma_f32_16x16x32_bf16 v[46:49], v[166:169], v[234:237], v[46:49]
	ds_read_b128 v[150:153], v226 offset:2048
	v_mfma_f32_16x16x32_bf16 v[14:17], v[162:165], v[234:237], v[14:17]
	ds_read_b128 v[146:149], v226 offset:3072
	v_mfma_f32_16x16x32_bf16 v[106:109], v[174:177], v[238:241], v[106:109]
	ds_read_b128 v[130:133], v189
	v_mfma_f32_16x16x32_bf16 v[74:77], v[170:173], v[238:241], v[74:77]
	ds_read_b128 v[134:137], v189 offset:1024
	v_mfma_f32_16x16x32_bf16 v[42:45], v[166:169], v[238:241], v[42:45]
	ds_read_b128 v[138:141], v189 offset:2048
	v_mfma_f32_16x16x32_bf16 v[10:13], v[162:165], v[238:241], v[10:13]
	ds_read_b128 v[142:145], v189 offset:3072
	s_add_i32 s30, s30, 2
	s_add_u32 s20, s20, 0x80
	s_addc_u32 s21, s21, 0
	s_add_i32 s31, s31, 0x10000
	v_mfma_f32_16x16x32_bf16 v[102:105], v[174:177], v[182:185], v[102:105]
	v_mfma_f32_16x16x32_bf16 v[70:73], v[170:173], v[182:185], v[70:73]
	v_mfma_f32_16x16x32_bf16 v[38:41], v[166:169], v[182:185], v[38:41]
	v_mfma_f32_16x16x32_bf16 v[6:9], v[162:165], v[182:185], v[6:9]
	v_mfma_f32_16x16x32_bf16 v[94:97], v[174:177], v[178:181], v[94:97]
	v_mfma_f32_16x16x32_bf16 v[62:65], v[170:173], v[178:181], v[62:65]
	v_mfma_f32_16x16x32_bf16 v[30:33], v[166:169], v[178:181], v[30:33]
	v_mfma_f32_16x16x32_bf16 v[2:5], v[162:165], v[178:181], v[2:5]
	s_waitcnt lgkmcnt(0)
	v_mfma_f32_16x16x32_bf16 v[126:129], v[130:133], v[158:161], v[126:129]
	v_mfma_f32_16x16x32_bf16 v[98:101], v[134:137], v[158:161], v[98:101]
	s_add_i32 s28, s31, 0xfffe8000
	s_and_b32 s34, s28, 0x10000
	v_add_u32_e32 v170, s34, v233
	ds_read_b128 v[162:165], v170
	v_mfma_f32_16x16x32_bf16 v[66:69], v[138:141], v[158:161], v[66:69]
	ds_read_b128 v[166:169], v170 offset:1024
	v_mfma_f32_16x16x32_bf16 v[34:37], v[142:145], v[158:161], v[34:37]
	ds_read_b128 v[234:237], v170 offset:2048
	v_mfma_f32_16x16x32_bf16 v[122:125], v[130:133], v[154:157], v[122:125]
	ds_read_b128 v[238:241], v170 offset:3072
	v_mfma_f32_16x16x32_bf16 v[90:93], v[134:137], v[154:157], v[90:93]
	v_mfma_f32_16x16x32_bf16 v[58:61], v[138:141], v[154:157], v[58:61]
	v_mfma_f32_16x16x32_bf16 v[26:29], v[142:145], v[154:157], v[26:29]
	v_mfma_f32_16x16x32_bf16 v[118:121], v[130:133], v[150:153], v[118:121]
	v_mfma_f32_16x16x32_bf16 v[86:89], v[134:137], v[150:153], v[86:89]
	v_mfma_f32_16x16x32_bf16 v[54:57], v[138:141], v[150:153], v[54:57]
	v_mfma_f32_16x16x32_bf16 v[22:25], v[142:145], v[150:153], v[22:25]
	v_mfma_f32_16x16x32_bf16 v[114:117], v[130:133], v[146:149], v[114:117]
	v_mfma_f32_16x16x32_bf16 v[82:85], v[134:137], v[146:149], v[82:85]
	v_mfma_f32_16x16x32_bf16 v[50:53], v[138:141], v[146:149], v[50:53]
	v_mfma_f32_16x16x32_bf16 v[18:21], v[142:145], v[146:149], v[18:21]
	s_waitcnt vmcnt(0)
	s_waitcnt lgkmcnt(0)
	s_barrier
	v_mfma_f32_16x16x32_bf16 v[110:113], v[130:133], v[162:165], v[110:113]
	s_add_i32 s28, s31, 0xffff0000
	s_and_b32 s35, s28, 0x18000
	v_add_u32_e32 v189, s35, v231
	v_add_u32_e32 v226, s35, v232
	ds_read_b128 v[158:161], v226
	v_mfma_f32_16x16x32_bf16 v[78:81], v[134:137], v[162:165], v[78:81]
	ds_read_b128 v[154:157], v226 offset:1024
	v_mfma_f32_16x16x32_bf16 v[46:49], v[138:141], v[162:165], v[46:49]
	ds_read_b128 v[150:153], v226 offset:2048
	v_mfma_f32_16x16x32_bf16 v[14:17], v[142:145], v[162:165], v[14:17]
	ds_read_b128 v[146:149], v226 offset:3072
	v_mfma_f32_16x16x32_bf16 v[106:109], v[130:133], v[166:169], v[106:109]
	ds_read_b128 v[174:177], v189
	v_mfma_f32_16x16x32_bf16 v[74:77], v[134:137], v[166:169], v[74:77]
	ds_read_b128 v[170:173], v189 offset:1024
	v_mfma_f32_16x16x32_bf16 v[42:45], v[138:141], v[166:169], v[42:45]
	ds_read_b128 v[162:165], v189 offset:3072
	v_mfma_f32_16x16x32_bf16 v[10:13], v[142:145], v[166:169], v[10:13]
	ds_read_b128 v[166:169], v189 offset:2048
	v_mfma_f32_16x16x32_bf16 v[102:105], v[130:133], v[234:237], v[102:105]
	v_mfma_f32_16x16x32_bf16 v[70:73], v[134:137], v[234:237], v[70:73]
	v_mfma_f32_16x16x32_bf16 v[38:41], v[138:141], v[234:237], v[38:41]
	v_mfma_f32_16x16x32_bf16 v[6:9], v[142:145], v[234:237], v[6:9]
	v_mfma_f32_16x16x32_bf16 v[94:97], v[130:133], v[238:241], v[94:97]
	v_mfma_f32_16x16x32_bf16 v[62:65], v[134:137], v[238:241], v[62:65]
	v_mfma_f32_16x16x32_bf16 v[30:33], v[138:141], v[238:241], v[30:33]
	v_mfma_f32_16x16x32_bf16 v[2:5], v[142:145], v[238:241], v[2:5]
	s_waitcnt lgkmcnt(0)
	v_mfma_f32_16x16x32_bf16 v[126:129], v[174:177], v[158:161], v[126:129]
	v_mfma_f32_16x16x32_bf16 v[98:101], v[170:173], v[158:161], v[98:101]
	v_add_u32_e32 v226, s35, v233
	ds_read_b128 v[234:237], v226
	v_mfma_f32_16x16x32_bf16 v[66:69], v[166:169], v[158:161], v[66:69]
	ds_read_b128 v[238:241], v226 offset:1024
	v_mfma_f32_16x16x32_bf16 v[34:37], v[162:165], v[158:161], v[34:37]
	ds_read_b128 v[182:185], v226 offset:2048
	v_mfma_f32_16x16x32_bf16 v[122:125], v[174:177], v[154:157], v[122:125]
	ds_read_b128 v[178:181], v226 offset:3072
	v_mfma_f32_16x16x32_bf16 v[90:93], v[170:173], v[154:157], v[90:93]
	v_mfma_f32_16x16x32_bf16 v[58:61], v[166:169], v[154:157], v[58:61]
	v_mfma_f32_16x16x32_bf16 v[26:29], v[162:165], v[154:157], v[26:29]
	v_mfma_f32_16x16x32_bf16 v[118:121], v[174:177], v[150:153], v[118:121]
	v_mfma_f32_16x16x32_bf16 v[86:89], v[170:173], v[150:153], v[86:89]
	v_mfma_f32_16x16x32_bf16 v[54:57], v[166:169], v[150:153], v[54:57]
	v_mfma_f32_16x16x32_bf16 v[22:25], v[162:165], v[150:153], v[22:25]
	v_mfma_f32_16x16x32_bf16 v[114:117], v[174:177], v[146:149], v[114:117]
	v_mfma_f32_16x16x32_bf16 v[82:85], v[170:173], v[146:149], v[82:85]
	v_mfma_f32_16x16x32_bf16 v[50:53], v[166:169], v[146:149], v[50:53]
	v_mfma_f32_16x16x32_bf16 v[18:21], v[162:165], v[146:149], v[18:21]
	s_waitcnt vmcnt(0)
	s_waitcnt lgkmcnt(0)
	s_barrier
	v_mfma_f32_16x16x32_bf16 v[110:113], v[174:177], v[234:237], v[110:113]
	v_mfma_f32_16x16x32_bf16 v[78:81], v[170:173], v[234:237], v[78:81]
	v_mfma_f32_16x16x32_bf16 v[46:49], v[166:169], v[234:237], v[46:49]
	v_mfma_f32_16x16x32_bf16 v[14:17], v[162:165], v[234:237], v[14:17]
	v_mfma_f32_16x16x32_bf16 v[106:109], v[174:177], v[238:241], v[106:109]
	v_mfma_f32_16x16x32_bf16 v[74:77], v[170:173], v[238:241], v[74:77]
	v_mfma_f32_16x16x32_bf16 v[42:45], v[166:169], v[238:241], v[42:45]
	v_mfma_f32_16x16x32_bf16 v[10:13], v[162:165], v[238:241], v[10:13]
	s_add_i32 s30, s30, 2
	s_add_u32 s20, s20, 0x80
	s_addc_u32 s21, s21, 0
	s_add_i32 s31, s31, 0x10000
	v_mfma_f32_16x16x32_bf16 v[102:105], v[174:177], v[182:185], v[102:105]
	v_mfma_f32_16x16x32_bf16 v[70:73], v[170:173], v[182:185], v[70:73]
	v_mfma_f32_16x16x32_bf16 v[38:41], v[166:169], v[182:185], v[38:41]
	v_mfma_f32_16x16x32_bf16 v[6:9], v[162:165], v[182:185], v[6:9]
	v_mfma_f32_16x16x32_bf16 v[94:97], v[174:177], v[178:181], v[94:97]
	v_mfma_f32_16x16x32_bf16 v[62:65], v[170:173], v[178:181], v[62:65]
	v_mfma_f32_16x16x32_bf16 v[30:33], v[166:169], v[178:181], v[30:33]
	v_mfma_f32_16x16x32_bf16 v[2:5], v[162:165], v[178:181], v[2:5]
	s_branch .LBB0_659
